# speedup vs baseline: 1.0120x; 1.0120x over previous
; #define STAGE_A(POFF, h, kt) STAGE_AX(POFF, h, kt, brow)
; #define STAGE_B(POFF, h, kt) STAGE_BX(POFF, h, kt, bcol)
; #define LDA(dst, b, h) _Pragma("unroll") for (int m = 0; m < 4; ++m) _Pragma("unroll") for (int k = 0; k < 2; ++k) \
;     dst[m][k] = *reinterpret_cast<const bf16x8*>((char*)SA(b, h) + lds_byte(wr * 64 + m * 16 + fr, k * 32 + fq * 8))
; #define LDB(dst, b, h) _Pragma("unroll") for (int n = 0; n < 2; ++n) _Pragma("unroll") for (int k = 0; k < 2; ++k) \
;     dst[n][k] = *reinterpret_cast<const bf16x8*>((char*)SB(b, h) + lds_byte(wc * 32 + n * 16 + fr, k * 32 + fq * 8))
; #define MMA(ai, bj, At_, Bt_) do { __builtin_amdgcn_s_setprio(1); \
;     _Pragma("unroll") for (int k = 0; k < 2; ++k) _Pragma("unroll") for (int m = 0; m < 4; ++m) _Pragma("unroll") for (int n = 0; n < 2; ++n) \
;       acc[ai][bj][m][n] = __builtin_amdgcn_mfma_f32_16x16x32_bf16(At_[m][k], Bt_[n][k], acc[ai][bj][m][n], 0, 0, 0); \
;     __builtin_amdgcn_s_setprio(0); } while (0)
; #define WAIT_V(n) asm volatile("s_waitcnt vmcnt(" #n ")" ::: "memory")
; #define BAR __builtin_amdgcn_s_barrier()
; #define SCHED __builtin_amdgcn_sched_barrier(0)
; template <int EPI, int N, int K>
; __device__ __forceinline__ void gemm_phase(const bf16_t* __restrict__ A, const bf16_t* __restrict__ Bt, const EpiArgs ea) {
;     ...
;       LDB(B0, 0, 0); SCHED; LDA(At, 0, 0); STAGE_A(SA_OFF(1, 1), 1, t + 1);
;       WAIT_L(8); BAR; WAIT_L(0); MMA(0, 0, At, B0); BAR; SCHED;
;       LDB(B1, 0, 1); STAGE_B(SB_OFF(0, 0), 0, t + 2);
;       BAR; WAIT_L(0); MMA(0, 1, At, B1); BAR;
;       LDA(At, 0, 1); STAGE_A(SA_OFF(0, 0), 0, t + 2);
;       BAR; WAIT_L(0); MMA(1, 0, At, B0); BAR; SCHED;
;       STAGE_B(SB_OFF(0, 1), 1, t + 2);
;       WAIT_V(6); BAR; MMA(1, 1, At, B1); BAR;
.LBB0_133:
	ds_read_b128 v[218:221], v146 offset:16384
	ds_read_b128 v[222:225], v146 offset:17408
	ds_read_b128 v[226:229], v147 offset:16384
	ds_read_b128 v[230:233], v147 offset:17408
	ds_read_b128 v[238:241], v148 offset:16384
	ds_read_b128 v[242:245], v148 offset:17408
	s_add_i32 s30, s27, s29
	s_or_b32 s31, s30, 0x80080
	s_mov_b32 m0, s24
	s_nop 0
	buffer_load_dwordx4 v131, s[48:51], s31 offen lds
	s_or_b32 s31, s30, 0xc0080
	s_mov_b32 m0, s25
	s_nop 0
	buffer_load_dwordx4 v131, s[48:51], s31 offen lds
	s_setprio 1
	s_barrier
	s_waitcnt lgkmcnt(6)
	v_mfma_f32_16x16x32_bf16 v[124:127], v[170:173], v[154:157], v[124:127]
	v_mfma_f32_16x16x32_bf16 v[120:123], v[170:173], v[162:165], v[120:123]
	v_mfma_f32_16x16x32_bf16 v[116:119], v[178:181], v[154:157], v[116:119]
	v_mfma_f32_16x16x32_bf16 v[112:115], v[178:181], v[162:165], v[112:115]
	v_mfma_f32_16x16x32_bf16 v[108:111], v[186:189], v[154:157], v[108:111]
	v_mfma_f32_16x16x32_bf16 v[104:107], v[186:189], v[162:165], v[104:107]
	v_mfma_f32_16x16x32_bf16 v[100:103], v[194:197], v[154:157], v[100:103]
	v_mfma_f32_16x16x32_bf16 v[96:99], v[194:197], v[162:165], v[96:99]
	v_mfma_f32_16x16x32_bf16 v[124:127], v[174:177], v[158:161], v[124:127]
	v_mfma_f32_16x16x32_bf16 v[120:123], v[174:177], v[166:169], v[120:123]
	v_mfma_f32_16x16x32_bf16 v[116:119], v[182:185], v[158:161], v[116:119]
	v_mfma_f32_16x16x32_bf16 v[112:115], v[182:185], v[166:169], v[112:115]
	v_mfma_f32_16x16x32_bf16 v[108:111], v[190:193], v[158:161], v[108:111]
	v_mfma_f32_16x16x32_bf16 v[104:107], v[190:193], v[166:169], v[104:107]
	v_mfma_f32_16x16x32_bf16 v[100:103], v[198:201], v[158:161], v[100:103]
	v_mfma_f32_16x16x32_bf16 v[96:99], v[198:201], v[166:169], v[96:99]
	s_barrier
	s_setprio 0
	ds_read_b128 v[202:205], v150
	ds_read_b128 v[206:209], v150 offset:1024
	ds_read_b128 v[210:213], v150 offset:2048
	ds_read_b128 v[214:217], v150 offset:3072
	ds_read_b128 v[246:249], v149 offset:16384
	ds_read_b128 v[250:253], v149 offset:17408
	s_add_i32 s31, s3, s29
	s_add_i32 s34, s31, 0x100
	s_mov_b32 m0, s11
	s_nop 0
	buffer_load_dwordx4 v134, s[72:75], s34 offen lds
	s_add_i32 s34, s31, 0x80100
	s_mov_b32 m0, s12
	s_nop 0
	buffer_load_dwordx4 v134, s[72:75], s34 offen lds
	s_waitcnt vmcnt(6)
	s_setprio 1
	s_barrier
	s_waitcnt lgkmcnt(2)
	v_mfma_f32_16x16x32_bf16 v[92:95], v[170:173], v[202:205], v[92:95]
	v_mfma_f32_16x16x32_bf16 v[88:91], v[170:173], v[210:213], v[88:91]
	v_mfma_f32_16x16x32_bf16 v[84:87], v[178:181], v[202:205], v[84:87]
	v_mfma_f32_16x16x32_bf16 v[80:83], v[178:181], v[210:213], v[80:83]
	v_mfma_f32_16x16x32_bf16 v[76:79], v[186:189], v[202:205], v[76:79]
	v_mfma_f32_16x16x32_bf16 v[72:75], v[186:189], v[210:213], v[72:75]
	v_mfma_f32_16x16x32_bf16 v[68:71], v[194:197], v[202:205], v[68:71]
	v_mfma_f32_16x16x32_bf16 v[64:67], v[194:197], v[210:213], v[64:67]
	v_mfma_f32_16x16x32_bf16 v[92:95], v[174:177], v[206:209], v[92:95]
	v_mfma_f32_16x16x32_bf16 v[88:91], v[174:177], v[214:217], v[88:91]
	v_mfma_f32_16x16x32_bf16 v[84:87], v[182:185], v[206:209], v[84:87]
	v_mfma_f32_16x16x32_bf16 v[80:83], v[182:185], v[214:217], v[80:83]
	v_mfma_f32_16x16x32_bf16 v[76:79], v[190:193], v[206:209], v[76:79]
	v_mfma_f32_16x16x32_bf16 v[72:75], v[190:193], v[214:217], v[72:75]
	v_mfma_f32_16x16x32_bf16 v[68:71], v[198:201], v[206:209], v[68:71]
	v_mfma_f32_16x16x32_bf16 v[64:67], v[198:201], v[214:217], v[64:67]
	s_barrier
	s_setprio 0
	ds_read_b128 v[170:173], v146 offset:32768
	ds_read_b128 v[174:177], v146 offset:33792
	ds_read_b128 v[178:181], v147 offset:32768
	ds_read_b128 v[182:185], v147 offset:33792
	ds_read_b128 v[186:189], v148 offset:32768
	ds_read_b128 v[190:193], v148 offset:33792
	s_add_i32 s34, s30, 0x100
	s_mov_b32 m0, s10
	s_nop 0
	buffer_load_dwordx4 v131, s[48:51], s34 offen lds
	s_add_i32 s35, s30, 0x40100
	s_mov_b32 m0, s13
	s_nop 0
	buffer_load_dwordx4 v131, s[48:51], s35 offen lds
	s_waitcnt vmcnt(10)
	s_setprio 1
	s_barrier
	s_waitcnt lgkmcnt(6)
	v_mfma_f32_16x16x32_bf16 v[60:63], v[218:221], v[154:157], v[60:63]
	v_mfma_f32_16x16x32_bf16 v[56:59], v[218:221], v[162:165], v[56:59]
	v_mfma_f32_16x16x32_bf16 v[52:55], v[226:229], v[154:157], v[52:55]
	v_mfma_f32_16x16x32_bf16 v[48:51], v[226:229], v[162:165], v[48:51]
	v_mfma_f32_16x16x32_bf16 v[44:47], v[238:241], v[154:157], v[44:47]
	v_mfma_f32_16x16x32_bf16 v[40:43], v[238:241], v[162:165], v[40:43]
	v_mfma_f32_16x16x32_bf16 v[36:39], v[246:249], v[154:157], v[36:39]
	v_mfma_f32_16x16x32_bf16 v[32:35], v[246:249], v[162:165], v[32:35]
	v_mfma_f32_16x16x32_bf16 v[60:63], v[222:225], v[158:161], v[60:63]
	v_mfma_f32_16x16x32_bf16 v[56:59], v[222:225], v[166:169], v[56:59]
	v_mfma_f32_16x16x32_bf16 v[52:55], v[230:233], v[158:161], v[52:55]
	v_mfma_f32_16x16x32_bf16 v[48:51], v[230:233], v[166:169], v[48:51]
	v_mfma_f32_16x16x32_bf16 v[44:47], v[242:245], v[158:161], v[44:47]
	v_mfma_f32_16x16x32_bf16 v[40:43], v[242:245], v[166:169], v[40:43]
	v_mfma_f32_16x16x32_bf16 v[36:39], v[250:253], v[158:161], v[36:39]
	v_mfma_f32_16x16x32_bf16 v[32:35], v[250:253], v[166:169], v[32:35]
	s_barrier
	s_setprio 0
	ds_read_b128 v[154:157], v151
	ds_read_b128 v[158:161], v151 offset:1024
	ds_read_b128 v[162:165], v151 offset:2048
	ds_read_b128 v[166:169], v151 offset:3072
	ds_read_b128 v[194:197], v149 offset:32768
	ds_read_b128 v[198:201], v149 offset:33792
	s_add_i32 s35, s31, 0x2100
	s_mov_b32 m0, s14
	s_nop 0
	buffer_load_dwordx4 v134, s[72:75], s35 offen lds
	s_add_i32 s35, s31, 0x82100
	s_mov_b32 m0, s15
	s_nop 0
	buffer_load_dwordx4 v134, s[72:75], s35 offen lds
	s_waitcnt vmcnt(6)
	s_setprio 1
	s_barrier
; #define STAGE_A(POFF, h, kt) STAGE_AX(POFF, h, kt, brow)
; #define STAGE_B(POFF, h, kt) STAGE_BX(POFF, h, kt, bcol)
; #define LDA(dst, b, h) _Pragma("unroll") for (int m = 0; m < 4; ++m) _Pragma("unroll") for (int k = 0; k < 2; ++k) \
;     dst[m][k] = *reinterpret_cast<const bf16x8*>((char*)SA(b, h) + lds_byte(wr * 64 + m * 16 + fr, k * 32 + fq * 8))
; #define LDB(dst, b, h) _Pragma("unroll") for (int n = 0; n < 2; ++n) _Pragma("unroll") for (int k = 0; k < 2; ++k) \
;     dst[n][k] = *reinterpret_cast<const bf16x8*>((char*)SB(b, h) + lds_byte(wc * 32 + n * 16 + fr, k * 32 + fq * 8))
; #define MMA(ai, bj, At_, Bt_) do { __builtin_amdgcn_s_setprio(1); \
;     _Pragma("unroll") for (int k = 0; k < 2; ++k) _Pragma("unroll") for (int m = 0; m < 4; ++m) _Pragma("unroll") for (int n = 0; n < 2; ++n) \
;       acc[ai][bj][m][n] = __builtin_amdgcn_mfma_f32_16x16x32_bf16(At_[m][k], Bt_[n][k], acc[ai][bj][m][n], 0, 0, 0); \
;     __builtin_amdgcn_s_setprio(0); } while (0)
; #define WAIT_V(n) asm volatile("s_waitcnt vmcnt(" #n ")" ::: "memory")
; #define BAR __builtin_amdgcn_s_barrier()
; #define SCHED __builtin_amdgcn_sched_barrier(0)
; template <int EPI, int N, int K>
; __device__ __forceinline__ void gemm_phase(const bf16_t* __restrict__ A, const bf16_t* __restrict__ Bt, const EpiArgs ea) {
;     ...
;       WAIT_V(6); BAR; MMA(1, 1, At, B1); BAR;
;       LDB(B0, 1, 0); SCHED; LDA(At, 1, 0); STAGE_A(SA_OFF(0, 1), 1, t + 2);
;       WAIT_L(8); BAR; WAIT_L(0); MMA(0, 0, At, B0); BAR; SCHED;
;       LDB(B1, 1, 1); STAGE_B(SB_OFF(1, 0), 0, t + 3);
;       BAR; WAIT_L(0); MMA(0, 1, At, B1); BAR;
;       LDA(At, 1, 1); STAGE_A(SA_OFF(1, 0), 0, t + 3);
	v_mfma_f32_16x16x32_bf16 v[28:31], v[218:221], v[202:205], v[28:31]
	v_mfma_f32_16x16x32_bf16 v[24:27], v[218:221], v[210:213], v[24:27]
	v_mfma_f32_16x16x32_bf16 v[20:23], v[226:229], v[202:205], v[20:23]
	v_mfma_f32_16x16x32_bf16 v[16:19], v[226:229], v[210:213], v[16:19]
	v_mfma_f32_16x16x32_bf16 v[12:15], v[238:241], v[202:205], v[12:15]
	v_mfma_f32_16x16x32_bf16 v[8:11], v[238:241], v[210:213], v[8:11]
	v_mfma_f32_16x16x32_bf16 v[4:7], v[246:249], v[202:205], v[4:7]
	v_mfma_f32_16x16x32_bf16 v[0:3], v[246:249], v[210:213], v[0:3]
	v_mfma_f32_16x16x32_bf16 v[28:31], v[222:225], v[206:209], v[28:31]
	v_mfma_f32_16x16x32_bf16 v[24:27], v[222:225], v[214:217], v[24:27]
	v_mfma_f32_16x16x32_bf16 v[20:23], v[230:233], v[206:209], v[20:23]
	v_mfma_f32_16x16x32_bf16 v[16:19], v[230:233], v[214:217], v[16:19]
	v_mfma_f32_16x16x32_bf16 v[12:15], v[242:245], v[206:209], v[12:15]
	v_mfma_f32_16x16x32_bf16 v[8:11], v[242:245], v[214:217], v[8:11]
	v_mfma_f32_16x16x32_bf16 v[4:7], v[250:253], v[206:209], v[4:7]
	v_mfma_f32_16x16x32_bf16 v[0:3], v[250:253], v[214:217], v[0:3]
	s_barrier
	s_setprio 0
	ds_read_b128 v[218:221], v146 offset:49152
	ds_read_b128 v[222:225], v146 offset:50176
	ds_read_b128 v[226:229], v147 offset:49152
	ds_read_b128 v[230:233], v147 offset:50176
	ds_read_b128 v[238:241], v148 offset:49152
	ds_read_b128 v[242:245], v148 offset:50176
	s_or_b32 s35, s34, 0x80000
	s_mov_b32 m0, s16
	s_nop 0
	buffer_load_dwordx4 v131, s[48:51], s35 offen lds
	s_or_b32 s34, s34, 0xc0000
	s_mov_b32 m0, s17
	s_nop 0
	buffer_load_dwordx4 v131, s[48:51], s34 offen lds
	s_setprio 1
	s_barrier
	s_waitcnt lgkmcnt(6)
	v_mfma_f32_16x16x32_bf16 v[124:127], v[170:173], v[154:157], v[124:127]
	v_mfma_f32_16x16x32_bf16 v[120:123], v[170:173], v[162:165], v[120:123]
	v_mfma_f32_16x16x32_bf16 v[116:119], v[178:181], v[154:157], v[116:119]
	v_mfma_f32_16x16x32_bf16 v[112:115], v[178:181], v[162:165], v[112:115]
	v_mfma_f32_16x16x32_bf16 v[108:111], v[186:189], v[154:157], v[108:111]
	v_mfma_f32_16x16x32_bf16 v[104:107], v[186:189], v[162:165], v[104:107]
	v_mfma_f32_16x16x32_bf16 v[100:103], v[194:197], v[154:157], v[100:103]
	v_mfma_f32_16x16x32_bf16 v[96:99], v[194:197], v[162:165], v[96:99]
	v_mfma_f32_16x16x32_bf16 v[124:127], v[174:177], v[158:161], v[124:127]
	v_mfma_f32_16x16x32_bf16 v[120:123], v[174:177], v[166:169], v[120:123]
	v_mfma_f32_16x16x32_bf16 v[116:119], v[182:185], v[158:161], v[116:119]
	v_mfma_f32_16x16x32_bf16 v[112:115], v[182:185], v[166:169], v[112:115]
	v_mfma_f32_16x16x32_bf16 v[108:111], v[190:193], v[158:161], v[108:111]
	v_mfma_f32_16x16x32_bf16 v[104:107], v[190:193], v[166:169], v[104:107]
	v_mfma_f32_16x16x32_bf16 v[100:103], v[198:201], v[158:161], v[100:103]
	v_mfma_f32_16x16x32_bf16 v[96:99], v[198:201], v[166:169], v[96:99]
	s_barrier
	s_setprio 0
	ds_read_b128 v[202:205], v152
	ds_read_b128 v[206:209], v152 offset:1024
	ds_read_b128 v[210:213], v152 offset:2048
	ds_read_b128 v[214:217], v152 offset:3072
	ds_read_b128 v[246:249], v149 offset:49152
	ds_read_b128 v[250:253], v149 offset:50176
	s_add_i32 s34, s31, 0x180
	s_mov_b32 m0, s18
	s_nop 0
	buffer_load_dwordx4 v134, s[72:75], s34 offen lds
	s_add_i32 s34, s31, 0x80180
	s_mov_b32 m0, s19
	s_nop 0
	buffer_load_dwordx4 v134, s[72:75], s34 offen lds
	s_waitcnt vmcnt(6)
	s_setprio 1
	s_barrier
	s_waitcnt lgkmcnt(2)
	v_mfma_f32_16x16x32_bf16 v[92:95], v[170:173], v[202:205], v[92:95]
	v_mfma_f32_16x16x32_bf16 v[88:91], v[170:173], v[210:213], v[88:91]
	v_mfma_f32_16x16x32_bf16 v[84:87], v[178:181], v[202:205], v[84:87]
	v_mfma_f32_16x16x32_bf16 v[80:83], v[178:181], v[210:213], v[80:83]
	v_mfma_f32_16x16x32_bf16 v[76:79], v[186:189], v[202:205], v[76:79]
	v_mfma_f32_16x16x32_bf16 v[72:75], v[186:189], v[210:213], v[72:75]
	v_mfma_f32_16x16x32_bf16 v[68:71], v[194:197], v[202:205], v[68:71]
	v_mfma_f32_16x16x32_bf16 v[64:67], v[194:197], v[210:213], v[64:67]
	v_mfma_f32_16x16x32_bf16 v[92:95], v[174:177], v[206:209], v[92:95]
	v_mfma_f32_16x16x32_bf16 v[88:91], v[174:177], v[214:217], v[88:91]
	v_mfma_f32_16x16x32_bf16 v[84:87], v[182:185], v[206:209], v[84:87]
	v_mfma_f32_16x16x32_bf16 v[80:83], v[182:185], v[214:217], v[80:83]
	v_mfma_f32_16x16x32_bf16 v[76:79], v[190:193], v[206:209], v[76:79]
	v_mfma_f32_16x16x32_bf16 v[72:75], v[190:193], v[214:217], v[72:75]
	v_mfma_f32_16x16x32_bf16 v[68:71], v[198:201], v[206:209], v[68:71]
	v_mfma_f32_16x16x32_bf16 v[64:67], v[198:201], v[214:217], v[64:67]
	s_barrier
	s_setprio 0
	ds_read_b128 v[170:173], v146
	ds_read_b128 v[174:177], v146 offset:1024
	ds_read_b128 v[178:181], v147
	ds_read_b128 v[182:185], v147 offset:1024
	ds_read_b128 v[186:189], v148
	ds_read_b128 v[190:193], v148 offset:1024
	s_add_i32 s34, s30, 0x180
	s_mov_b32 m0, s20
	s_nop 0
	buffer_load_dwordx4 v131, s[48:51], s34 offen lds
	s_add_i32 s30, s30, 0x40180
	s_mov_b32 m0, s21
	s_nop 0
	buffer_load_dwordx4 v131, s[48:51], s30 offen lds
	s_waitcnt vmcnt(10)
	s_setprio 1
	s_barrier
	s_waitcnt lgkmcnt(6)
	v_mfma_f32_16x16x32_bf16 v[60:63], v[218:221], v[154:157], v[60:63]
	v_mfma_f32_16x16x32_bf16 v[56:59], v[218:221], v[162:165], v[56:59]
	v_mfma_f32_16x16x32_bf16 v[52:55], v[226:229], v[154:157], v[52:55]
	v_mfma_f32_16x16x32_bf16 v[48:51], v[226:229], v[162:165], v[48:51]
	v_mfma_f32_16x16x32_bf16 v[44:47], v[238:241], v[154:157], v[44:47]
	v_mfma_f32_16x16x32_bf16 v[40:43], v[238:241], v[162:165], v[40:43]
	v_mfma_f32_16x16x32_bf16 v[36:39], v[246:249], v[154:157], v[36:39]
	v_mfma_f32_16x16x32_bf16 v[32:35], v[246:249], v[162:165], v[32:35]
	v_mfma_f32_16x16x32_bf16 v[60:63], v[222:225], v[158:161], v[60:63]
	v_mfma_f32_16x16x32_bf16 v[56:59], v[222:225], v[166:169], v[56:59]
	v_mfma_f32_16x16x32_bf16 v[52:55], v[230:233], v[158:161], v[52:55]
	v_mfma_f32_16x16x32_bf16 v[48:51], v[230:233], v[166:169], v[48:51]
	v_mfma_f32_16x16x32_bf16 v[44:47], v[242:245], v[158:161], v[44:47]
	v_mfma_f32_16x16x32_bf16 v[40:43], v[242:245], v[166:169], v[40:43]
	v_mfma_f32_16x16x32_bf16 v[36:39], v[250:253], v[158:161], v[36:39]
	v_mfma_f32_16x16x32_bf16 v[32:35], v[250:253], v[166:169], v[32:35]
	s_barrier
; #define STAGE_A(POFF, h, kt) STAGE_AX(POFF, h, kt, brow)
; #define STAGE_B(POFF, h, kt) STAGE_BX(POFF, h, kt, bcol)
; #define LDA(dst, b, h) _Pragma("unroll") for (int m = 0; m < 4; ++m) _Pragma("unroll") for (int k = 0; k < 2; ++k) \
;     dst[m][k] = *reinterpret_cast<const bf16x8*>((char*)SA(b, h) + lds_byte(wr * 64 + m * 16 + fr, k * 32 + fq * 8))
; #define LDB(dst, b, h) _Pragma("unroll") for (int n = 0; n < 2; ++n) _Pragma("unroll") for (int k = 0; k < 2; ++k) \
;     dst[n][k] = *reinterpret_cast<const bf16x8*>((char*)SB(b, h) + lds_byte(wc * 32 + n * 16 + fr, k * 32 + fq * 8))
; #define MMA(ai, bj, At_, Bt_) do { __builtin_amdgcn_s_setprio(1); \
;     _Pragma("unroll") for (int k = 0; k < 2; ++k) _Pragma("unroll") for (int m = 0; m < 4; ++m) _Pragma("unroll") for (int n = 0; n < 2; ++n) \
;       acc[ai][bj][m][n] = __builtin_amdgcn_mfma_f32_16x16x32_bf16(At_[m][k], Bt_[n][k], acc[ai][bj][m][n], 0, 0, 0); \
;     __builtin_amdgcn_s_setprio(0); } while (0)
; #define WAIT_V(n) asm volatile("s_waitcnt vmcnt(" #n ")" ::: "memory")
; #define BAR __builtin_amdgcn_s_barrier()
; #define SCHED __builtin_amdgcn_sched_barrier(0)
; template <int EPI, int N, int K>
; __device__ __forceinline__ void gemm_phase(const bf16_t* __restrict__ A, const bf16_t* __restrict__ Bt, const EpiArgs ea) {
;     ...
;       LDA(At, 1, 1); STAGE_A(SA_OFF(1, 0), 0, t + 3);
;       BAR; WAIT_L(0); MMA(1, 0, At, B0); BAR; SCHED;
;       STAGE_B(SB_OFF(1, 1), 1, t + 3);
;       WAIT_V(6); BAR; MMA(1, 1, At, B1); BAR;
;     }
;     { LDB(B0, 0, 0); LDA(At, 0, 0); STAGE_A(SA_OFF(1, 1), 1, nt - 1);
;       BAR; WAIT_L(0); MMA(0, 0, At, B0); BAR;
;       LDB(B1, 0, 1); BAR; WAIT_L(0); MMA(0, 1, At, B1); BAR;
	s_setprio 0
	ds_read_b128 v[154:157], v145
	ds_read_b128 v[158:161], v145 offset:1024
	ds_read_b128 v[162:165], v145 offset:2048
	ds_read_b128 v[166:169], v145 offset:3072
	ds_read_b128 v[194:197], v149
	ds_read_b128 v[198:201], v149 offset:1024
	s_add_i32 s30, s31, 0x2180
	s_mov_b32 m0, s22
	s_nop 0
	buffer_load_dwordx4 v134, s[72:75], s30 offen lds
	s_add_i32 s31, s31, 0x82180
	s_mov_b32 m0, s23
	s_nop 0
	buffer_load_dwordx4 v134, s[72:75], s31 offen lds
	s_waitcnt vmcnt(6)
	s_setprio 1
	s_barrier
	v_mfma_f32_16x16x32_bf16 v[28:31], v[218:221], v[202:205], v[28:31]
	v_mfma_f32_16x16x32_bf16 v[24:27], v[218:221], v[210:213], v[24:27]
	v_mfma_f32_16x16x32_bf16 v[20:23], v[226:229], v[202:205], v[20:23]
	v_mfma_f32_16x16x32_bf16 v[16:19], v[226:229], v[210:213], v[16:19]
	v_mfma_f32_16x16x32_bf16 v[12:15], v[238:241], v[202:205], v[12:15]
	v_mfma_f32_16x16x32_bf16 v[8:11], v[238:241], v[210:213], v[8:11]
	v_mfma_f32_16x16x32_bf16 v[4:7], v[246:249], v[202:205], v[4:7]
	v_mfma_f32_16x16x32_bf16 v[0:3], v[246:249], v[210:213], v[0:3]
	v_mfma_f32_16x16x32_bf16 v[28:31], v[222:225], v[206:209], v[28:31]
	v_mfma_f32_16x16x32_bf16 v[24:27], v[222:225], v[214:217], v[24:27]
	v_mfma_f32_16x16x32_bf16 v[20:23], v[230:233], v[206:209], v[20:23]
	v_mfma_f32_16x16x32_bf16 v[16:19], v[230:233], v[214:217], v[16:19]
	v_mfma_f32_16x16x32_bf16 v[12:15], v[242:245], v[206:209], v[12:15]
	v_mfma_f32_16x16x32_bf16 v[8:11], v[242:245], v[214:217], v[8:11]
	v_mfma_f32_16x16x32_bf16 v[4:7], v[250:253], v[206:209], v[4:7]
	v_mfma_f32_16x16x32_bf16 v[0:3], v[250:253], v[214:217], v[0:3]
	s_barrier
	s_setprio 0
	s_add_i32 s28, s28, 2
	s_addk_i32 s29, 0x100
	s_cmp_lt_u32 s28, 28
	s_cbranch_scc1 .LBB0_133
	s_and_b32 s1, s1, 0x700
	s_lshl_b32 s0, s0, 11
	s_or_b32 s27, s1, s0
	s_lshl_b32 s0, s27, 12
	s_or_b32 s1, s0, 0x80f80
	s_mov_b32 m0, s24
	s_nop 0
	buffer_load_dwordx4 v131, s[48:51], s1 offen lds
	s_or_b32 s0, s0, 0xc0f80
	s_mov_b32 m0, s25
	s_nop 0
	buffer_load_dwordx4 v131, s[48:51], s0 offen lds
	s_barrier
	s_waitcnt lgkmcnt(0)
	s_setprio 1
	v_mfma_f32_16x16x32_bf16 v[124:127], v[170:173], v[154:157], v[124:127]
	v_mfma_f32_16x16x32_bf16 v[120:123], v[170:173], v[162:165], v[120:123]
	v_mfma_f32_16x16x32_bf16 v[116:119], v[178:181], v[154:157], v[116:119]
	v_mfma_f32_16x16x32_bf16 v[112:115], v[178:181], v[162:165], v[112:115]
	v_mfma_f32_16x16x32_bf16 v[108:111], v[186:189], v[154:157], v[108:111]
	v_mfma_f32_16x16x32_bf16 v[104:107], v[186:189], v[162:165], v[104:107]
	v_mfma_f32_16x16x32_bf16 v[100:103], v[194:197], v[154:157], v[100:103]
	v_mfma_f32_16x16x32_bf16 v[96:99], v[194:197], v[162:165], v[96:99]
	v_mfma_f32_16x16x32_bf16 v[124:127], v[174:177], v[158:161], v[124:127]
	v_mfma_f32_16x16x32_bf16 v[120:123], v[174:177], v[166:169], v[120:123]
	v_mfma_f32_16x16x32_bf16 v[116:119], v[182:185], v[158:161], v[116:119]
	v_mfma_f32_16x16x32_bf16 v[112:115], v[182:185], v[166:169], v[112:115]
	v_mfma_f32_16x16x32_bf16 v[108:111], v[190:193], v[158:161], v[108:111]
	v_mfma_f32_16x16x32_bf16 v[104:107], v[190:193], v[166:169], v[104:107]
	v_mfma_f32_16x16x32_bf16 v[100:103], v[198:201], v[158:161], v[100:103]
	v_mfma_f32_16x16x32_bf16 v[96:99], v[198:201], v[166:169], v[96:99]
	s_setprio 0
	s_barrier
	ds_read_b128 v[202:205], v150
	ds_read_b128 v[206:209], v150 offset:1024
	ds_read_b128 v[210:213], v150 offset:2048
	ds_read_b128 v[214:217], v150 offset:3072
	s_barrier
	s_waitcnt lgkmcnt(0)
	s_setprio 1
	v_mfma_f32_16x16x32_bf16 v[92:95], v[170:173], v[202:205], v[92:95]
	v_mfma_f32_16x16x32_bf16 v[88:91], v[170:173], v[210:213], v[88:91]
	v_mfma_f32_16x16x32_bf16 v[76:79], v[186:189], v[202:205], v[76:79]
	v_mfma_f32_16x16x32_bf16 v[72:75], v[186:189], v[210:213], v[72:75]
	v_mfma_f32_16x16x32_bf16 v[68:71], v[194:197], v[202:205], v[68:71]
	v_mfma_f32_16x16x32_bf16 v[64:67], v[194:197], v[210:213], v[64:67]
	v_mfma_f32_16x16x32_bf16 v[84:87], v[178:181], v[202:205], v[84:87]
	v_mfma_f32_16x16x32_bf16 v[80:83], v[178:181], v[210:213], v[80:83]
	v_mfma_f32_16x16x32_bf16 v[92:95], v[174:177], v[206:209], v[92:95]
	v_mfma_f32_16x16x32_bf16 v[88:91], v[174:177], v[214:217], v[88:91]
	v_mfma_f32_16x16x32_bf16 v[76:79], v[190:193], v[206:209], v[76:79]
	v_mfma_f32_16x16x32_bf16 v[72:75], v[190:193], v[214:217], v[72:75]
	v_mfma_f32_16x16x32_bf16 v[68:71], v[198:201], v[206:209], v[68:71]
	v_mfma_f32_16x16x32_bf16 v[64:67], v[198:201], v[214:217], v[64:67]
	v_mfma_f32_16x16x32_bf16 v[170:173], v[182:185], v[206:209], v[84:87]
	v_mfma_f32_16x16x32_bf16 v[174:177], v[182:185], v[214:217], v[80:83]
	s_setprio 0
	s_barrier
	s_nop 0
	ds_read_b128 v[80:83], v146 offset:16384
	ds_read_b128 v[84:87], v146 offset:17408
	ds_read_b128 v[178:181], v147 offset:16384
	ds_read_b128 v[182:185], v147 offset:17408
	ds_read_b128 v[186:189], v148 offset:16384
	ds_read_b128 v[190:193], v148 offset:17408
	ds_read_b128 v[194:197], v149 offset:16384
	ds_read_b128 v[198:201], v149 offset:17408
	s_waitcnt vmcnt(4)
	s_barrier
; #define LDA(dst, b, h) _Pragma("unroll") for (int m = 0; m < 4; ++m) _Pragma("unroll") for (int k = 0; k < 2; ++k) \
;     dst[m][k] = *reinterpret_cast<const bf16x8*>((char*)SA(b, h) + lds_byte(wr * 64 + m * 16 + fr, k * 32 + fq * 8))
; #define LDB(dst, b, h) _Pragma("unroll") for (int n = 0; n < 2; ++n) _Pragma("unroll") for (int k = 0; k < 2; ++k) \
;     dst[n][k] = *reinterpret_cast<const bf16x8*>((char*)SB(b, h) + lds_byte(wc * 32 + n * 16 + fr, k * 32 + fq * 8))
; #define MMA(ai, bj, At_, Bt_) do { __builtin_amdgcn_s_setprio(1); \
;     _Pragma("unroll") for (int k = 0; k < 2; ++k) _Pragma("unroll") for (int m = 0; m < 4; ++m) _Pragma("unroll") for (int n = 0; n < 2; ++n) \
;       acc[ai][bj][m][n] = __builtin_amdgcn_mfma_f32_16x16x32_bf16(At_[m][k], Bt_[n][k], acc[ai][bj][m][n], 0, 0, 0); \
;     __builtin_amdgcn_s_setprio(0); } while (0)
; #define WAIT_V(n) asm volatile("s_waitcnt vmcnt(" #n ")" ::: "memory")
; #define BAR __builtin_amdgcn_s_barrier()
; template <int EPI, int N, int K>
; __device__ __forceinline__ void gemm_phase(const bf16_t* __restrict__ A, const bf16_t* __restrict__ Bt, const EpiArgs ea) {
;     ...
;       LDA(At, 0, 1); WAIT_V(4); BAR; WAIT_L(0); MMA(1, 0, At, B0); MMA(1, 1, At, B1); BAR; }
;     { LDB(B0, 1, 0); LDA(At, 1, 0); WAIT_V(2); BAR; WAIT_L(0); MMA(0, 0, At, B0); BAR;
	s_waitcnt lgkmcnt(0)
	s_setprio 1
	v_mfma_f32_16x16x32_bf16 v[52:55], v[178:181], v[154:157], v[52:55]
	v_mfma_f32_16x16x32_bf16 v[48:51], v[178:181], v[162:165], v[48:51]
	v_mfma_f32_16x16x32_bf16 v[44:47], v[186:189], v[154:157], v[44:47]
	v_mfma_f32_16x16x32_bf16 v[40:43], v[186:189], v[162:165], v[40:43]
	v_mfma_f32_16x16x32_bf16 v[36:39], v[194:197], v[154:157], v[36:39]
	v_mfma_f32_16x16x32_bf16 v[32:35], v[194:197], v[162:165], v[32:35]
	v_mfma_f32_16x16x32_bf16 v[60:63], v[80:83], v[154:157], v[60:63]
	v_mfma_f32_16x16x32_bf16 v[56:59], v[80:83], v[162:165], v[56:59]
	v_mfma_f32_16x16x32_bf16 v[52:55], v[182:185], v[158:161], v[52:55]
	v_mfma_f32_16x16x32_bf16 v[48:51], v[182:185], v[166:169], v[48:51]
	v_mfma_f32_16x16x32_bf16 v[44:47], v[190:193], v[158:161], v[44:47]
	v_mfma_f32_16x16x32_bf16 v[40:43], v[190:193], v[166:169], v[40:43]
	v_mfma_f32_16x16x32_bf16 v[36:39], v[198:201], v[158:161], v[36:39]
	v_mfma_f32_16x16x32_bf16 v[32:35], v[198:201], v[166:169], v[32:35]
	v_mfma_f32_16x16x32_bf16 v[154:157], v[84:87], v[158:161], v[60:63]
	v_mfma_f32_16x16x32_bf16 v[162:165], v[84:87], v[166:169], v[56:59]
	s_setprio 0
	s_setprio 1
	v_mfma_f32_16x16x32_bf16 v[28:31], v[80:83], v[202:205], v[28:31]
	v_mfma_f32_16x16x32_bf16 v[24:27], v[80:83], v[210:213], v[24:27]
	v_mfma_f32_16x16x32_bf16 v[12:15], v[186:189], v[202:205], v[12:15]
	v_mfma_f32_16x16x32_bf16 v[8:11], v[186:189], v[210:213], v[8:11]
	v_mfma_f32_16x16x32_bf16 v[20:23], v[178:181], v[202:205], v[20:23]
	v_mfma_f32_16x16x32_bf16 v[16:19], v[178:181], v[210:213], v[16:19]
	v_mfma_f32_16x16x32_bf16 v[4:7], v[194:197], v[202:205], v[4:7]
	v_mfma_f32_16x16x32_bf16 v[0:3], v[194:197], v[210:213], v[0:3]
	v_mfma_f32_16x16x32_bf16 v[28:31], v[84:87], v[206:209], v[28:31]
	v_mfma_f32_16x16x32_bf16 v[24:27], v[84:87], v[214:217], v[24:27]
	v_mfma_f32_16x16x32_bf16 v[12:15], v[190:193], v[206:209], v[12:15]
	v_mfma_f32_16x16x32_bf16 v[8:11], v[190:193], v[214:217], v[8:11]
	v_mfma_f32_16x16x32_bf16 v[158:161], v[182:185], v[206:209], v[20:23]
	v_mfma_f32_16x16x32_bf16 v[166:169], v[182:185], v[214:217], v[16:19]
	v_mfma_f32_16x16x32_bf16 v[178:181], v[198:201], v[206:209], v[4:7]
	v_mfma_f32_16x16x32_bf16 v[182:185], v[198:201], v[214:217], v[0:3]
	s_setprio 0
	s_barrier
	s_nop 0
	ds_read_b128 v[0:3], v151
	ds_read_b128 v[4:7], v151 offset:1024
	ds_read_b128 v[16:19], v151 offset:2048
	ds_read_b128 v[186:189], v151 offset:3072
	ds_read_b128 v[20:23], v146 offset:32768
	ds_read_b128 v[190:193], v146 offset:33792
	ds_read_b128 v[194:197], v147 offset:32768
	ds_read_b128 v[198:201], v147 offset:33792
	ds_read_b128 v[202:205], v148 offset:32768
	ds_read_b128 v[206:209], v148 offset:33792
	ds_read_b128 v[210:213], v149 offset:32768
	ds_read_b128 v[214:217], v149 offset:33792
	s_waitcnt vmcnt(2)
	s_barrier
	s_waitcnt lgkmcnt(0)
	s_setprio 1
	v_mfma_f32_16x16x32_bf16 v[56:59], v[20:23], v[0:3], v[124:127]
	v_mfma_f32_16x16x32_bf16 v[60:63], v[20:23], v[16:19], v[120:123]
	v_mfma_f32_16x16x32_bf16 v[80:83], v[194:197], v[0:3], v[116:119]
	v_mfma_f32_16x16x32_bf16 v[84:87], v[194:197], v[16:19], v[112:115]
	v_mfma_f32_16x16x32_bf16 v[108:111], v[202:205], v[0:3], v[108:111]
	v_mfma_f32_16x16x32_bf16 v[104:107], v[202:205], v[16:19], v[104:107]
	v_mfma_f32_16x16x32_bf16 v[120:123], v[210:213], v[0:3], v[100:103]
	v_mfma_f32_16x16x32_bf16 v[124:127], v[210:213], v[16:19], v[96:99]
	v_mfma_f32_16x16x32_bf16 v[116:119], v[190:193], v[4:7], v[56:59]
	v_mfma_f32_16x16x32_bf16 v[112:115], v[190:193], v[186:189], v[60:63]
	v_mfma_f32_16x16x32_bf16 v[100:103], v[198:201], v[4:7], v[80:83]
	v_mfma_f32_16x16x32_bf16 v[96:99], v[198:201], v[186:189], v[84:87]
	v_mfma_f32_16x16x32_bf16 v[84:87], v[206:209], v[4:7], v[108:111]
	v_mfma_f32_16x16x32_bf16 v[80:83], v[206:209], v[186:189], v[104:107]
	v_mfma_f32_16x16x32_bf16 v[60:63], v[214:217], v[4:7], v[120:123]
	v_mfma_f32_16x16x32_bf16 v[56:59], v[214:217], v[186:189], v[124:127]
	s_setprio 0
	s_barrier
; #define LDA(dst, b, h) _Pragma("unroll") for (int m = 0; m < 4; ++m) _Pragma("unroll") for (int k = 0; k < 2; ++k) \
;     dst[m][k] = *reinterpret_cast<const bf16x8*>((char*)SA(b, h) + lds_byte(wr * 64 + m * 16 + fr, k * 32 + fq * 8))
; #define LDB(dst, b, h) _Pragma("unroll") for (int n = 0; n < 2; ++n) _Pragma("unroll") for (int k = 0; k < 2; ++k) \
;     dst[n][k] = *reinterpret_cast<const bf16x8*>((char*)SB(b, h) + lds_byte(wc * 32 + n * 16 + fr, k * 32 + fq * 8))
; #define MMA(ai, bj, At_, Bt_) do { __builtin_amdgcn_s_setprio(1); \
;     _Pragma("unroll") for (int k = 0; k < 2; ++k) _Pragma("unroll") for (int m = 0; m < 4; ++m) _Pragma("unroll") for (int n = 0; n < 2; ++n) \
;       acc[ai][bj][m][n] = __builtin_amdgcn_mfma_f32_16x16x32_bf16(At_[m][k], Bt_[n][k], acc[ai][bj][m][n], 0, 0, 0); \
;     __builtin_amdgcn_s_setprio(0); } while (0)
; #define WAIT_V(n) asm volatile("s_waitcnt vmcnt(" #n ")" ::: "memory")
; #define BAR __builtin_amdgcn_s_barrier()
; template <int EPI, int N, int K>
; __device__ __forceinline__ void gemm_phase(const bf16_t* __restrict__ A, const bf16_t* __restrict__ Bt, const EpiArgs ea) {
;     ...
;     { LDB(B0, 1, 0); LDA(At, 1, 0); WAIT_V(2); BAR; WAIT_L(0); MMA(0, 0, At, B0); BAR;
;       LDB(B1, 1, 1); WAIT_V(0); BAR; WAIT_L(0); MMA(0, 1, At, B1); BAR;
;       LDA(At, 1, 1); BAR; WAIT_L(0); MMA(1, 0, At, B0); MMA(1, 1, At, B1); BAR; }
;     if (wr == 0) BAR;
	ds_read_b128 v[218:221], v152
	ds_read_b128 v[222:225], v152 offset:1024
	ds_read_b128 v[226:229], v152 offset:2048
	ds_read_b128 v[230:233], v152 offset:3072
	s_waitcnt vmcnt(0)
	s_barrier
	s_waitcnt lgkmcnt(0)
	s_setprio 1
	v_mfma_f32_16x16x32_bf16 v[92:95], v[20:23], v[218:221], v[92:95]
	v_mfma_f32_16x16x32_bf16 v[20:23], v[20:23], v[226:229], v[88:91]
	v_mfma_f32_16x16x32_bf16 v[88:91], v[194:197], v[218:221], v[170:173]
	v_mfma_f32_16x16x32_bf16 v[104:107], v[194:197], v[226:229], v[174:177]
	v_mfma_f32_16x16x32_bf16 v[76:79], v[202:205], v[218:221], v[76:79]
	v_mfma_f32_16x16x32_bf16 v[72:75], v[202:205], v[226:229], v[72:75]
	v_mfma_f32_16x16x32_bf16 v[68:71], v[210:213], v[218:221], v[68:71]
	v_mfma_f32_16x16x32_bf16 v[64:67], v[210:213], v[226:229], v[64:67]
	v_mfma_f32_16x16x32_bf16 v[124:127], v[190:193], v[222:225], v[92:95]
	v_mfma_f32_16x16x32_bf16 v[120:123], v[190:193], v[230:233], v[20:23]
	v_mfma_f32_16x16x32_bf16 v[108:111], v[198:201], v[222:225], v[88:91]
	v_mfma_f32_16x16x32_bf16 v[104:107], v[198:201], v[230:233], v[104:107]
	v_mfma_f32_16x16x32_bf16 v[92:95], v[206:209], v[222:225], v[76:79]
	v_mfma_f32_16x16x32_bf16 v[88:91], v[206:209], v[230:233], v[72:75]
	v_mfma_f32_16x16x32_bf16 v[76:79], v[214:217], v[222:225], v[68:71]
	v_mfma_f32_16x16x32_bf16 v[72:75], v[214:217], v[230:233], v[64:67]
	s_setprio 0
	s_barrier
	s_nop 0
	ds_read_b128 v[64:67], v146 offset:49152
	ds_read_b128 v[170:173], v146 offset:50176
	ds_read_b128 v[68:71], v147 offset:49152
	ds_read_b128 v[174:177], v147 offset:50176
	ds_read_b128 v[190:193], v148 offset:49152
	ds_read_b128 v[194:197], v148 offset:50176
	ds_read_b128 v[198:201], v149 offset:49152
	ds_read_b128 v[202:205], v149 offset:50176
	s_barrier
	s_waitcnt lgkmcnt(0)
	s_setprio 1
	v_mfma_f32_16x16x32_bf16 v[20:23], v[64:67], v[0:3], v[154:157]
	v_mfma_f32_16x16x32_bf16 v[154:157], v[64:67], v[16:19], v[162:165]
	v_mfma_f32_16x16x32_bf16 v[162:165], v[68:71], v[0:3], v[52:55]
	v_mfma_f32_16x16x32_bf16 v[206:209], v[68:71], v[16:19], v[48:51]
	v_mfma_f32_16x16x32_bf16 v[44:47], v[190:193], v[0:3], v[44:47]
	v_mfma_f32_16x16x32_bf16 v[40:43], v[190:193], v[16:19], v[40:43]
	v_mfma_f32_16x16x32_bf16 v[0:3], v[198:201], v[0:3], v[36:39]
	v_mfma_f32_16x16x32_bf16 v[210:213], v[198:201], v[16:19], v[32:35]
	v_mfma_f32_16x16x32_bf16 v[52:55], v[170:173], v[4:7], v[20:23]
	v_mfma_f32_16x16x32_bf16 v[48:51], v[170:173], v[186:189], v[154:157]
	v_mfma_f32_16x16x32_bf16 v[36:39], v[174:177], v[4:7], v[162:165]
	v_mfma_f32_16x16x32_bf16 v[32:35], v[174:177], v[186:189], v[206:209]
	v_mfma_f32_16x16x32_bf16 v[20:23], v[194:197], v[4:7], v[44:47]
	v_mfma_f32_16x16x32_bf16 v[16:19], v[194:197], v[186:189], v[40:43]
	v_mfma_f32_16x16x32_bf16 v[4:7], v[202:205], v[4:7], v[0:3]
	v_mfma_f32_16x16x32_bf16 v[0:3], v[202:205], v[186:189], v[210:213]
	s_setprio 0
	s_setprio 1
	v_mfma_f32_16x16x32_bf16 v[28:31], v[64:67], v[218:221], v[28:31]
	v_mfma_f32_16x16x32_bf16 v[24:27], v[64:67], v[226:229], v[24:27]
	v_mfma_f32_16x16x32_bf16 v[40:43], v[68:71], v[218:221], v[158:161]
	v_mfma_f32_16x16x32_bf16 v[154:157], v[68:71], v[226:229], v[166:169]
	v_mfma_f32_16x16x32_bf16 v[12:15], v[190:193], v[218:221], v[12:15]
	v_mfma_f32_16x16x32_bf16 v[8:11], v[190:193], v[226:229], v[8:11]
	v_mfma_f32_16x16x32_bf16 v[158:161], v[198:201], v[218:221], v[178:181]
	v_mfma_f32_16x16x32_bf16 v[162:165], v[198:201], v[226:229], v[182:185]
	v_mfma_f32_16x16x32_bf16 v[68:71], v[170:173], v[222:225], v[28:31]
	v_mfma_f32_16x16x32_bf16 v[64:67], v[170:173], v[230:233], v[24:27]
	v_mfma_f32_16x16x32_bf16 v[44:47], v[174:177], v[222:225], v[40:43]
	v_mfma_f32_16x16x32_bf16 v[40:43], v[174:177], v[230:233], v[154:157]
	v_mfma_f32_16x16x32_bf16 v[28:31], v[194:197], v[222:225], v[12:15]
	v_mfma_f32_16x16x32_bf16 v[24:27], v[194:197], v[230:233], v[8:11]
	v_mfma_f32_16x16x32_bf16 v[12:15], v[202:205], v[222:225], v[158:161]
	v_mfma_f32_16x16x32_bf16 v[8:11], v[202:205], v[230:233], v[162:165]
	s_setprio 0
	s_barrier
	s_and_saveexec_b64 s[0:1], s[6:7]
	s_cbranch_execz .LBB0_136
	s_barrier

; #define STAGE_A(POFF, h, kt) STAGE_AX(POFF, h, kt, brow)
; #define STAGE_B(POFF, h, kt) STAGE_BX(POFF, h, kt, bcol)
; #define LDA(dst, b, h) _Pragma("unroll") for (int m = 0; m < 4; ++m) _Pragma("unroll") for (int k = 0; k < 2; ++k) \
;     dst[m][k] = *reinterpret_cast<const bf16x8*>((char*)SA(b, h) + lds_byte(wr * 64 + m * 16 + fr, k * 32 + fq * 8))
; #define LDB(dst, b, h) _Pragma("unroll") for (int n = 0; n < 2; ++n) _Pragma("unroll") for (int k = 0; k < 2; ++k) \
;     dst[n][k] = *reinterpret_cast<const bf16x8*>((char*)SB(b, h) + lds_byte(wc * 32 + n * 16 + fr, k * 32 + fq * 8))
; #define MMA(ai, bj, At_, Bt_) do { __builtin_amdgcn_s_setprio(1); \
;     _Pragma("unroll") for (int k = 0; k < 2; ++k) _Pragma("unroll") for (int m = 0; m < 4; ++m) _Pragma("unroll") for (int n = 0; n < 2; ++n) \
;       acc[ai][bj][m][n] = __builtin_amdgcn_mfma_f32_16x16x32_bf16(At_[m][k], Bt_[n][k], acc[ai][bj][m][n], 0, 0, 0); \
;     __builtin_amdgcn_s_setprio(0); } while (0)
; #define WAIT_V(n) asm volatile("s_waitcnt vmcnt(" #n ")" ::: "memory")
; #define BAR __builtin_amdgcn_s_barrier()
; #define SCHED __builtin_amdgcn_sched_barrier(0)
; template <int EPI, int N, int K>
; __device__ __forceinline__ void gemm_phase(const bf16_t* __restrict__ A, const bf16_t* __restrict__ Bt, const EpiArgs ea) {
;     ...
;       LDB(B0, 0, 0); SCHED; LDA(At, 0, 0); STAGE_A(SA_OFF(1, 1), 1, t + 1);
;       WAIT_L(8); BAR; WAIT_L(0); MMA(0, 0, At, B0); BAR; SCHED;
;       LDB(B1, 0, 1); STAGE_B(SB_OFF(0, 0), 0, t + 2);
;       BAR; WAIT_L(0); MMA(0, 1, At, B1); BAR;
;       LDA(At, 0, 1); STAGE_A(SA_OFF(0, 0), 0, t + 2);
;       BAR; WAIT_L(0); MMA(1, 0, At, B0); BAR; SCHED;
;       STAGE_B(SB_OFF(0, 1), 1, t + 2);
;       WAIT_V(6); BAR; MMA(1, 1, At, B1); BAR;
.LBB0_270:
	ds_read_b128 v[218:221], v146 offset:16384
	ds_read_b128 v[222:225], v146 offset:17408
	ds_read_b128 v[226:229], v147 offset:16384
	ds_read_b128 v[230:233], v147 offset:17408
	ds_read_b128 v[238:241], v148 offset:16384
	ds_read_b128 v[242:245], v148 offset:17408
	s_add_i32 s30, s27, s29
	s_or_b32 s31, s30, 0x80080
	s_mov_b32 m0, s24
	s_nop 0
	buffer_load_dwordx4 v131, s[48:51], s31 offen lds
	s_or_b32 s31, s30, 0xc0080
	s_mov_b32 m0, s25
	s_nop 0
	buffer_load_dwordx4 v131, s[48:51], s31 offen lds
	s_setprio 1
	s_barrier
	s_waitcnt lgkmcnt(6)
	v_mfma_f32_16x16x32_bf16 v[124:127], v[170:173], v[154:157], v[124:127]
	v_mfma_f32_16x16x32_bf16 v[120:123], v[170:173], v[162:165], v[120:123]
	v_mfma_f32_16x16x32_bf16 v[116:119], v[178:181], v[154:157], v[116:119]
	v_mfma_f32_16x16x32_bf16 v[112:115], v[178:181], v[162:165], v[112:115]
	v_mfma_f32_16x16x32_bf16 v[108:111], v[186:189], v[154:157], v[108:111]
	v_mfma_f32_16x16x32_bf16 v[104:107], v[186:189], v[162:165], v[104:107]
	v_mfma_f32_16x16x32_bf16 v[100:103], v[194:197], v[154:157], v[100:103]
	v_mfma_f32_16x16x32_bf16 v[96:99], v[194:197], v[162:165], v[96:99]
	v_mfma_f32_16x16x32_bf16 v[124:127], v[174:177], v[158:161], v[124:127]
	v_mfma_f32_16x16x32_bf16 v[120:123], v[174:177], v[166:169], v[120:123]
	v_mfma_f32_16x16x32_bf16 v[116:119], v[182:185], v[158:161], v[116:119]
	v_mfma_f32_16x16x32_bf16 v[112:115], v[182:185], v[166:169], v[112:115]
	v_mfma_f32_16x16x32_bf16 v[108:111], v[190:193], v[158:161], v[108:111]
	v_mfma_f32_16x16x32_bf16 v[104:107], v[190:193], v[166:169], v[104:107]
	v_mfma_f32_16x16x32_bf16 v[100:103], v[198:201], v[158:161], v[100:103]
	v_mfma_f32_16x16x32_bf16 v[96:99], v[198:201], v[166:169], v[96:99]
	s_barrier
	s_setprio 0
	ds_read_b128 v[202:205], v150
	ds_read_b128 v[206:209], v150 offset:1024
	ds_read_b128 v[210:213], v150 offset:2048
	ds_read_b128 v[214:217], v150 offset:3072
	ds_read_b128 v[246:249], v149 offset:16384
	ds_read_b128 v[250:253], v149 offset:17408
	s_add_i32 s31, s3, s29
	s_add_i32 s34, s31, 0x100
	s_mov_b32 m0, s11
	s_nop 0
	buffer_load_dwordx4 v134, s[56:59], s34 offen lds
	s_add_i32 s34, s31, 0x80100
	s_mov_b32 m0, s12
	s_nop 0
	buffer_load_dwordx4 v134, s[56:59], s34 offen lds
	s_waitcnt vmcnt(6)
	s_setprio 1
	s_barrier
	s_waitcnt lgkmcnt(2)
	v_mfma_f32_16x16x32_bf16 v[92:95], v[170:173], v[202:205], v[92:95]
	v_mfma_f32_16x16x32_bf16 v[88:91], v[170:173], v[210:213], v[88:91]
	v_mfma_f32_16x16x32_bf16 v[84:87], v[178:181], v[202:205], v[84:87]
	v_mfma_f32_16x16x32_bf16 v[80:83], v[178:181], v[210:213], v[80:83]
	v_mfma_f32_16x16x32_bf16 v[76:79], v[186:189], v[202:205], v[76:79]
	v_mfma_f32_16x16x32_bf16 v[72:75], v[186:189], v[210:213], v[72:75]
	v_mfma_f32_16x16x32_bf16 v[68:71], v[194:197], v[202:205], v[68:71]
	v_mfma_f32_16x16x32_bf16 v[64:67], v[194:197], v[210:213], v[64:67]
	v_mfma_f32_16x16x32_bf16 v[92:95], v[174:177], v[206:209], v[92:95]
	v_mfma_f32_16x16x32_bf16 v[88:91], v[174:177], v[214:217], v[88:91]
	v_mfma_f32_16x16x32_bf16 v[84:87], v[182:185], v[206:209], v[84:87]
	v_mfma_f32_16x16x32_bf16 v[80:83], v[182:185], v[214:217], v[80:83]
	v_mfma_f32_16x16x32_bf16 v[76:79], v[190:193], v[206:209], v[76:79]
	v_mfma_f32_16x16x32_bf16 v[72:75], v[190:193], v[214:217], v[72:75]
	v_mfma_f32_16x16x32_bf16 v[68:71], v[198:201], v[206:209], v[68:71]
	v_mfma_f32_16x16x32_bf16 v[64:67], v[198:201], v[214:217], v[64:67]
	s_barrier
	s_setprio 0
	ds_read_b128 v[170:173], v146 offset:32768
	ds_read_b128 v[174:177], v146 offset:33792
	ds_read_b128 v[178:181], v147 offset:32768
	ds_read_b128 v[182:185], v147 offset:33792
	ds_read_b128 v[186:189], v148 offset:32768
	ds_read_b128 v[190:193], v148 offset:33792
	s_add_i32 s34, s30, 0x100
	s_mov_b32 m0, s10
	s_nop 0
	buffer_load_dwordx4 v131, s[48:51], s34 offen lds
	s_add_i32 s35, s30, 0x40100
	s_mov_b32 m0, s13
	s_nop 0
	buffer_load_dwordx4 v131, s[48:51], s35 offen lds
	s_waitcnt vmcnt(10)
	s_setprio 1
	s_barrier
	s_waitcnt lgkmcnt(6)
	v_mfma_f32_16x16x32_bf16 v[60:63], v[218:221], v[154:157], v[60:63]
	v_mfma_f32_16x16x32_bf16 v[56:59], v[218:221], v[162:165], v[56:59]
	v_mfma_f32_16x16x32_bf16 v[52:55], v[226:229], v[154:157], v[52:55]
	v_mfma_f32_16x16x32_bf16 v[48:51], v[226:229], v[162:165], v[48:51]
	v_mfma_f32_16x16x32_bf16 v[44:47], v[238:241], v[154:157], v[44:47]
	v_mfma_f32_16x16x32_bf16 v[40:43], v[238:241], v[162:165], v[40:43]
	v_mfma_f32_16x16x32_bf16 v[36:39], v[246:249], v[154:157], v[36:39]
	v_mfma_f32_16x16x32_bf16 v[32:35], v[246:249], v[162:165], v[32:35]
	v_mfma_f32_16x16x32_bf16 v[60:63], v[222:225], v[158:161], v[60:63]
	v_mfma_f32_16x16x32_bf16 v[56:59], v[222:225], v[166:169], v[56:59]
	v_mfma_f32_16x16x32_bf16 v[52:55], v[230:233], v[158:161], v[52:55]
	v_mfma_f32_16x16x32_bf16 v[48:51], v[230:233], v[166:169], v[48:51]
	v_mfma_f32_16x16x32_bf16 v[44:47], v[242:245], v[158:161], v[44:47]
	v_mfma_f32_16x16x32_bf16 v[40:43], v[242:245], v[166:169], v[40:43]
	v_mfma_f32_16x16x32_bf16 v[36:39], v[250:253], v[158:161], v[36:39]
	v_mfma_f32_16x16x32_bf16 v[32:35], v[250:253], v[166:169], v[32:35]
	s_barrier
	s_setprio 0
	ds_read_b128 v[154:157], v151
	ds_read_b128 v[158:161], v151 offset:1024
	ds_read_b128 v[162:165], v151 offset:2048
	ds_read_b128 v[166:169], v151 offset:3072
	ds_read_b128 v[194:197], v149 offset:32768
	ds_read_b128 v[198:201], v149 offset:33792
	s_add_i32 s35, s31, 0x2100
	s_mov_b32 m0, s14
	s_nop 0
	buffer_load_dwordx4 v134, s[56:59], s35 offen lds
	s_add_i32 s35, s31, 0x82100
	s_mov_b32 m0, s15
	s_nop 0
	buffer_load_dwordx4 v134, s[56:59], s35 offen lds
	s_waitcnt vmcnt(6)
	s_setprio 1
	s_barrier
; #define STAGE_A(POFF, h, kt) STAGE_AX(POFF, h, kt, brow)
; #define STAGE_B(POFF, h, kt) STAGE_BX(POFF, h, kt, bcol)
; #define LDA(dst, b, h) _Pragma("unroll") for (int m = 0; m < 4; ++m) _Pragma("unroll") for (int k = 0; k < 2; ++k) \
;     dst[m][k] = *reinterpret_cast<const bf16x8*>((char*)SA(b, h) + lds_byte(wr * 64 + m * 16 + fr, k * 32 + fq * 8))
; #define LDB(dst, b, h) _Pragma("unroll") for (int n = 0; n < 2; ++n) _Pragma("unroll") for (int k = 0; k < 2; ++k) \
;     dst[n][k] = *reinterpret_cast<const bf16x8*>((char*)SB(b, h) + lds_byte(wc * 32 + n * 16 + fr, k * 32 + fq * 8))
; #define MMA(ai, bj, At_, Bt_) do { __builtin_amdgcn_s_setprio(1); \
;     _Pragma("unroll") for (int k = 0; k < 2; ++k) _Pragma("unroll") for (int m = 0; m < 4; ++m) _Pragma("unroll") for (int n = 0; n < 2; ++n) \
;       acc[ai][bj][m][n] = __builtin_amdgcn_mfma_f32_16x16x32_bf16(At_[m][k], Bt_[n][k], acc[ai][bj][m][n], 0, 0, 0); \
;     __builtin_amdgcn_s_setprio(0); } while (0)
; #define WAIT_V(n) asm volatile("s_waitcnt vmcnt(" #n ")" ::: "memory")
; #define BAR __builtin_amdgcn_s_barrier()
; #define SCHED __builtin_amdgcn_sched_barrier(0)
; template <int EPI, int N, int K>
; __device__ __forceinline__ void gemm_phase(const bf16_t* __restrict__ A, const bf16_t* __restrict__ Bt, const EpiArgs ea) {
;     ...
;       WAIT_V(6); BAR; MMA(1, 1, At, B1); BAR;
;       LDB(B0, 1, 0); SCHED; LDA(At, 1, 0); STAGE_A(SA_OFF(0, 1), 1, t + 2);
;       WAIT_L(8); BAR; WAIT_L(0); MMA(0, 0, At, B0); BAR; SCHED;
;       LDB(B1, 1, 1); STAGE_B(SB_OFF(1, 0), 0, t + 3);
;       BAR; WAIT_L(0); MMA(0, 1, At, B1); BAR;
;       LDA(At, 1, 1); STAGE_A(SA_OFF(1, 0), 0, t + 3);
	v_mfma_f32_16x16x32_bf16 v[28:31], v[218:221], v[202:205], v[28:31]
	v_mfma_f32_16x16x32_bf16 v[24:27], v[218:221], v[210:213], v[24:27]
	v_mfma_f32_16x16x32_bf16 v[20:23], v[226:229], v[202:205], v[20:23]
	v_mfma_f32_16x16x32_bf16 v[16:19], v[226:229], v[210:213], v[16:19]
	v_mfma_f32_16x16x32_bf16 v[12:15], v[238:241], v[202:205], v[12:15]
	v_mfma_f32_16x16x32_bf16 v[8:11], v[238:241], v[210:213], v[8:11]
	v_mfma_f32_16x16x32_bf16 v[4:7], v[246:249], v[202:205], v[4:7]
	v_mfma_f32_16x16x32_bf16 v[0:3], v[246:249], v[210:213], v[0:3]
	v_mfma_f32_16x16x32_bf16 v[28:31], v[222:225], v[206:209], v[28:31]
	v_mfma_f32_16x16x32_bf16 v[24:27], v[222:225], v[214:217], v[24:27]
	v_mfma_f32_16x16x32_bf16 v[20:23], v[230:233], v[206:209], v[20:23]
	v_mfma_f32_16x16x32_bf16 v[16:19], v[230:233], v[214:217], v[16:19]
	v_mfma_f32_16x16x32_bf16 v[12:15], v[242:245], v[206:209], v[12:15]
	v_mfma_f32_16x16x32_bf16 v[8:11], v[242:245], v[214:217], v[8:11]
	v_mfma_f32_16x16x32_bf16 v[4:7], v[250:253], v[206:209], v[4:7]
	v_mfma_f32_16x16x32_bf16 v[0:3], v[250:253], v[214:217], v[0:3]
	s_barrier
	s_setprio 0
	ds_read_b128 v[218:221], v146 offset:49152
	ds_read_b128 v[222:225], v146 offset:50176
	ds_read_b128 v[226:229], v147 offset:49152
	ds_read_b128 v[230:233], v147 offset:50176
	ds_read_b128 v[238:241], v148 offset:49152
	ds_read_b128 v[242:245], v148 offset:50176
	s_or_b32 s35, s34, 0x80000
	s_mov_b32 m0, s16
	s_nop 0
	buffer_load_dwordx4 v131, s[48:51], s35 offen lds
	s_or_b32 s34, s34, 0xc0000
	s_mov_b32 m0, s17
	s_nop 0
	buffer_load_dwordx4 v131, s[48:51], s34 offen lds
	s_setprio 1
	s_barrier
	s_waitcnt lgkmcnt(6)
	v_mfma_f32_16x16x32_bf16 v[124:127], v[170:173], v[154:157], v[124:127]
	v_mfma_f32_16x16x32_bf16 v[120:123], v[170:173], v[162:165], v[120:123]
	v_mfma_f32_16x16x32_bf16 v[116:119], v[178:181], v[154:157], v[116:119]
	v_mfma_f32_16x16x32_bf16 v[112:115], v[178:181], v[162:165], v[112:115]
	v_mfma_f32_16x16x32_bf16 v[108:111], v[186:189], v[154:157], v[108:111]
	v_mfma_f32_16x16x32_bf16 v[104:107], v[186:189], v[162:165], v[104:107]
	v_mfma_f32_16x16x32_bf16 v[100:103], v[194:197], v[154:157], v[100:103]
	v_mfma_f32_16x16x32_bf16 v[96:99], v[194:197], v[162:165], v[96:99]
	v_mfma_f32_16x16x32_bf16 v[124:127], v[174:177], v[158:161], v[124:127]
	v_mfma_f32_16x16x32_bf16 v[120:123], v[174:177], v[166:169], v[120:123]
	v_mfma_f32_16x16x32_bf16 v[116:119], v[182:185], v[158:161], v[116:119]
	v_mfma_f32_16x16x32_bf16 v[112:115], v[182:185], v[166:169], v[112:115]
	v_mfma_f32_16x16x32_bf16 v[108:111], v[190:193], v[158:161], v[108:111]
	v_mfma_f32_16x16x32_bf16 v[104:107], v[190:193], v[166:169], v[104:107]
	v_mfma_f32_16x16x32_bf16 v[100:103], v[198:201], v[158:161], v[100:103]
	v_mfma_f32_16x16x32_bf16 v[96:99], v[198:201], v[166:169], v[96:99]
	s_barrier
	s_setprio 0
	ds_read_b128 v[202:205], v152
	ds_read_b128 v[206:209], v152 offset:1024
	ds_read_b128 v[210:213], v152 offset:2048
	ds_read_b128 v[214:217], v152 offset:3072
	ds_read_b128 v[246:249], v149 offset:49152
	ds_read_b128 v[250:253], v149 offset:50176
	s_add_i32 s34, s31, 0x180
	s_mov_b32 m0, s18
	s_nop 0
	buffer_load_dwordx4 v134, s[56:59], s34 offen lds
	s_add_i32 s34, s31, 0x80180
	s_mov_b32 m0, s19
	s_nop 0
	buffer_load_dwordx4 v134, s[56:59], s34 offen lds
	s_waitcnt vmcnt(6)
	s_setprio 1
	s_barrier
	s_waitcnt lgkmcnt(2)
	v_mfma_f32_16x16x32_bf16 v[92:95], v[170:173], v[202:205], v[92:95]
	v_mfma_f32_16x16x32_bf16 v[88:91], v[170:173], v[210:213], v[88:91]
	v_mfma_f32_16x16x32_bf16 v[84:87], v[178:181], v[202:205], v[84:87]
	v_mfma_f32_16x16x32_bf16 v[80:83], v[178:181], v[210:213], v[80:83]
	v_mfma_f32_16x16x32_bf16 v[76:79], v[186:189], v[202:205], v[76:79]
	v_mfma_f32_16x16x32_bf16 v[72:75], v[186:189], v[210:213], v[72:75]
	v_mfma_f32_16x16x32_bf16 v[68:71], v[194:197], v[202:205], v[68:71]
	v_mfma_f32_16x16x32_bf16 v[64:67], v[194:197], v[210:213], v[64:67]
	v_mfma_f32_16x16x32_bf16 v[92:95], v[174:177], v[206:209], v[92:95]
	v_mfma_f32_16x16x32_bf16 v[88:91], v[174:177], v[214:217], v[88:91]
	v_mfma_f32_16x16x32_bf16 v[84:87], v[182:185], v[206:209], v[84:87]
	v_mfma_f32_16x16x32_bf16 v[80:83], v[182:185], v[214:217], v[80:83]
	v_mfma_f32_16x16x32_bf16 v[76:79], v[190:193], v[206:209], v[76:79]
	v_mfma_f32_16x16x32_bf16 v[72:75], v[190:193], v[214:217], v[72:75]
	v_mfma_f32_16x16x32_bf16 v[68:71], v[198:201], v[206:209], v[68:71]
	v_mfma_f32_16x16x32_bf16 v[64:67], v[198:201], v[214:217], v[64:67]
	s_barrier
	s_setprio 0
	ds_read_b128 v[170:173], v146
	ds_read_b128 v[174:177], v146 offset:1024
	ds_read_b128 v[178:181], v147
	ds_read_b128 v[182:185], v147 offset:1024
	ds_read_b128 v[186:189], v148
	ds_read_b128 v[190:193], v148 offset:1024
	s_add_i32 s34, s30, 0x180
	s_mov_b32 m0, s20
	s_nop 0
	buffer_load_dwordx4 v131, s[48:51], s34 offen lds
	s_add_i32 s30, s30, 0x40180
	s_mov_b32 m0, s21
	s_nop 0
	buffer_load_dwordx4 v131, s[48:51], s30 offen lds
	s_waitcnt vmcnt(10)
	s_setprio 1
	s_barrier
	s_waitcnt lgkmcnt(6)
	v_mfma_f32_16x16x32_bf16 v[60:63], v[218:221], v[154:157], v[60:63]
	v_mfma_f32_16x16x32_bf16 v[56:59], v[218:221], v[162:165], v[56:59]
	v_mfma_f32_16x16x32_bf16 v[52:55], v[226:229], v[154:157], v[52:55]
	v_mfma_f32_16x16x32_bf16 v[48:51], v[226:229], v[162:165], v[48:51]
	v_mfma_f32_16x16x32_bf16 v[44:47], v[238:241], v[154:157], v[44:47]
	v_mfma_f32_16x16x32_bf16 v[40:43], v[238:241], v[162:165], v[40:43]
	v_mfma_f32_16x16x32_bf16 v[36:39], v[246:249], v[154:157], v[36:39]
	v_mfma_f32_16x16x32_bf16 v[32:35], v[246:249], v[162:165], v[32:35]
	v_mfma_f32_16x16x32_bf16 v[60:63], v[222:225], v[158:161], v[60:63]
	v_mfma_f32_16x16x32_bf16 v[56:59], v[222:225], v[166:169], v[56:59]
	v_mfma_f32_16x16x32_bf16 v[52:55], v[230:233], v[158:161], v[52:55]
	v_mfma_f32_16x16x32_bf16 v[48:51], v[230:233], v[166:169], v[48:51]
	v_mfma_f32_16x16x32_bf16 v[44:47], v[242:245], v[158:161], v[44:47]
	v_mfma_f32_16x16x32_bf16 v[40:43], v[242:245], v[166:169], v[40:43]
	v_mfma_f32_16x16x32_bf16 v[36:39], v[250:253], v[158:161], v[36:39]
	v_mfma_f32_16x16x32_bf16 v[32:35], v[250:253], v[166:169], v[32:35]
	s_barrier
; #define STAGE_A(POFF, h, kt) STAGE_AX(POFF, h, kt, brow)
; #define STAGE_B(POFF, h, kt) STAGE_BX(POFF, h, kt, bcol)
; #define LDA(dst, b, h) _Pragma("unroll") for (int m = 0; m < 4; ++m) _Pragma("unroll") for (int k = 0; k < 2; ++k) \
;     dst[m][k] = *reinterpret_cast<const bf16x8*>((char*)SA(b, h) + lds_byte(wr * 64 + m * 16 + fr, k * 32 + fq * 8))
; #define LDB(dst, b, h) _Pragma("unroll") for (int n = 0; n < 2; ++n) _Pragma("unroll") for (int k = 0; k < 2; ++k) \
;     dst[n][k] = *reinterpret_cast<const bf16x8*>((char*)SB(b, h) + lds_byte(wc * 32 + n * 16 + fr, k * 32 + fq * 8))
; #define MMA(ai, bj, At_, Bt_) do { __builtin_amdgcn_s_setprio(1); \
;     _Pragma("unroll") for (int k = 0; k < 2; ++k) _Pragma("unroll") for (int m = 0; m < 4; ++m) _Pragma("unroll") for (int n = 0; n < 2; ++n) \
;       acc[ai][bj][m][n] = __builtin_amdgcn_mfma_f32_16x16x32_bf16(At_[m][k], Bt_[n][k], acc[ai][bj][m][n], 0, 0, 0); \
;     __builtin_amdgcn_s_setprio(0); } while (0)
; #define WAIT_V(n) asm volatile("s_waitcnt vmcnt(" #n ")" ::: "memory")
; #define BAR __builtin_amdgcn_s_barrier()
; #define SCHED __builtin_amdgcn_sched_barrier(0)
; template <int EPI, int N, int K>
; __device__ __forceinline__ void gemm_phase(const bf16_t* __restrict__ A, const bf16_t* __restrict__ Bt, const EpiArgs ea) {
;     ...
;       LDA(At, 1, 1); STAGE_A(SA_OFF(1, 0), 0, t + 3);
;       BAR; WAIT_L(0); MMA(1, 0, At, B0); BAR; SCHED;
;       STAGE_B(SB_OFF(1, 1), 1, t + 3);
;       WAIT_V(6); BAR; MMA(1, 1, At, B1); BAR;
;     }
;     { LDB(B0, 0, 0); LDA(At, 0, 0); STAGE_A(SA_OFF(1, 1), 1, nt - 1);
;       BAR; WAIT_L(0); MMA(0, 0, At, B0); BAR;
;       LDB(B1, 0, 1); BAR; WAIT_L(0); MMA(0, 1, At, B1); BAR;
	s_setprio 0
	ds_read_b128 v[154:157], v145
	ds_read_b128 v[158:161], v145 offset:1024
	ds_read_b128 v[162:165], v145 offset:2048
	ds_read_b128 v[166:169], v145 offset:3072
	ds_read_b128 v[194:197], v149
	ds_read_b128 v[198:201], v149 offset:1024
	s_add_i32 s30, s31, 0x2180
	s_mov_b32 m0, s22
	s_nop 0
	buffer_load_dwordx4 v134, s[56:59], s30 offen lds
	s_add_i32 s31, s31, 0x82180
	s_mov_b32 m0, s23
	s_nop 0
	buffer_load_dwordx4 v134, s[56:59], s31 offen lds
	s_waitcnt vmcnt(6)
	s_setprio 1
	s_barrier
	v_mfma_f32_16x16x32_bf16 v[28:31], v[218:221], v[202:205], v[28:31]
	v_mfma_f32_16x16x32_bf16 v[24:27], v[218:221], v[210:213], v[24:27]
	v_mfma_f32_16x16x32_bf16 v[20:23], v[226:229], v[202:205], v[20:23]
	v_mfma_f32_16x16x32_bf16 v[16:19], v[226:229], v[210:213], v[16:19]
	v_mfma_f32_16x16x32_bf16 v[12:15], v[238:241], v[202:205], v[12:15]
	v_mfma_f32_16x16x32_bf16 v[8:11], v[238:241], v[210:213], v[8:11]
	v_mfma_f32_16x16x32_bf16 v[4:7], v[246:249], v[202:205], v[4:7]
	v_mfma_f32_16x16x32_bf16 v[0:3], v[246:249], v[210:213], v[0:3]
	v_mfma_f32_16x16x32_bf16 v[28:31], v[222:225], v[206:209], v[28:31]
	v_mfma_f32_16x16x32_bf16 v[24:27], v[222:225], v[214:217], v[24:27]
	v_mfma_f32_16x16x32_bf16 v[20:23], v[230:233], v[206:209], v[20:23]
	v_mfma_f32_16x16x32_bf16 v[16:19], v[230:233], v[214:217], v[16:19]
	v_mfma_f32_16x16x32_bf16 v[12:15], v[242:245], v[206:209], v[12:15]
	v_mfma_f32_16x16x32_bf16 v[8:11], v[242:245], v[214:217], v[8:11]
	v_mfma_f32_16x16x32_bf16 v[4:7], v[250:253], v[206:209], v[4:7]
	v_mfma_f32_16x16x32_bf16 v[0:3], v[250:253], v[214:217], v[0:3]
	s_barrier
	s_setprio 0
	s_add_i32 s28, s28, 2
	s_addk_i32 s29, 0x100
	s_cmp_lt_u32 s28, 28
	s_cbranch_scc1 .LBB0_270
	s_and_b32 s1, s1, 0x700
	s_lshl_b32 s0, s0, 11
	s_or_b32 s27, s1, s0
	s_lshl_b32 s0, s27, 12
	s_or_b32 s1, s0, 0x80f80
	s_mov_b32 m0, s24
	s_nop 0
	buffer_load_dwordx4 v131, s[48:51], s1 offen lds
	s_or_b32 s0, s0, 0xc0f80
	s_mov_b32 m0, s25
	s_nop 0
	buffer_load_dwordx4 v131, s[48:51], s0 offen lds
	s_barrier
	s_waitcnt lgkmcnt(0)
	s_setprio 1
	v_mfma_f32_16x16x32_bf16 v[124:127], v[170:173], v[154:157], v[124:127]
	v_mfma_f32_16x16x32_bf16 v[120:123], v[170:173], v[162:165], v[120:123]
	v_mfma_f32_16x16x32_bf16 v[116:119], v[178:181], v[154:157], v[116:119]
	v_mfma_f32_16x16x32_bf16 v[112:115], v[178:181], v[162:165], v[112:115]
	v_mfma_f32_16x16x32_bf16 v[108:111], v[186:189], v[154:157], v[108:111]
	v_mfma_f32_16x16x32_bf16 v[104:107], v[186:189], v[162:165], v[104:107]
	v_mfma_f32_16x16x32_bf16 v[100:103], v[194:197], v[154:157], v[100:103]
	v_mfma_f32_16x16x32_bf16 v[96:99], v[194:197], v[162:165], v[96:99]
	v_mfma_f32_16x16x32_bf16 v[124:127], v[174:177], v[158:161], v[124:127]
	v_mfma_f32_16x16x32_bf16 v[120:123], v[174:177], v[166:169], v[120:123]
	v_mfma_f32_16x16x32_bf16 v[116:119], v[182:185], v[158:161], v[116:119]
	v_mfma_f32_16x16x32_bf16 v[112:115], v[182:185], v[166:169], v[112:115]
	v_mfma_f32_16x16x32_bf16 v[108:111], v[190:193], v[158:161], v[108:111]
	v_mfma_f32_16x16x32_bf16 v[104:107], v[190:193], v[166:169], v[104:107]
	v_mfma_f32_16x16x32_bf16 v[100:103], v[198:201], v[158:161], v[100:103]
	v_mfma_f32_16x16x32_bf16 v[96:99], v[198:201], v[166:169], v[96:99]
	s_setprio 0
	s_barrier
	ds_read_b128 v[202:205], v150
	ds_read_b128 v[206:209], v150 offset:1024
	ds_read_b128 v[210:213], v150 offset:2048
	ds_read_b128 v[214:217], v150 offset:3072
	s_barrier
	s_waitcnt lgkmcnt(0)
	s_setprio 1
	v_mfma_f32_16x16x32_bf16 v[92:95], v[170:173], v[202:205], v[92:95]
	v_mfma_f32_16x16x32_bf16 v[88:91], v[170:173], v[210:213], v[88:91]
	v_mfma_f32_16x16x32_bf16 v[76:79], v[186:189], v[202:205], v[76:79]
	v_mfma_f32_16x16x32_bf16 v[72:75], v[186:189], v[210:213], v[72:75]
	v_mfma_f32_16x16x32_bf16 v[68:71], v[194:197], v[202:205], v[68:71]
	v_mfma_f32_16x16x32_bf16 v[64:67], v[194:197], v[210:213], v[64:67]
	v_mfma_f32_16x16x32_bf16 v[84:87], v[178:181], v[202:205], v[84:87]
	v_mfma_f32_16x16x32_bf16 v[80:83], v[178:181], v[210:213], v[80:83]
	v_mfma_f32_16x16x32_bf16 v[92:95], v[174:177], v[206:209], v[92:95]
	v_mfma_f32_16x16x32_bf16 v[88:91], v[174:177], v[214:217], v[88:91]
	v_mfma_f32_16x16x32_bf16 v[76:79], v[190:193], v[206:209], v[76:79]
	v_mfma_f32_16x16x32_bf16 v[72:75], v[190:193], v[214:217], v[72:75]
	v_mfma_f32_16x16x32_bf16 v[68:71], v[198:201], v[206:209], v[68:71]
	v_mfma_f32_16x16x32_bf16 v[64:67], v[198:201], v[214:217], v[64:67]
	v_mfma_f32_16x16x32_bf16 v[170:173], v[182:185], v[206:209], v[84:87]
	v_mfma_f32_16x16x32_bf16 v[174:177], v[182:185], v[214:217], v[80:83]
	s_setprio 0
	s_barrier
	s_nop 0
	ds_read_b128 v[80:83], v146 offset:16384
	ds_read_b128 v[84:87], v146 offset:17408
	ds_read_b128 v[178:181], v147 offset:16384
	ds_read_b128 v[182:185], v147 offset:17408
	ds_read_b128 v[186:189], v148 offset:16384
	ds_read_b128 v[190:193], v148 offset:17408
	ds_read_b128 v[194:197], v149 offset:16384
	ds_read_b128 v[198:201], v149 offset:17408
	s_waitcnt vmcnt(4)
	s_barrier
; #define LDA(dst, b, h) _Pragma("unroll") for (int m = 0; m < 4; ++m) _Pragma("unroll") for (int k = 0; k < 2; ++k) \
;     dst[m][k] = *reinterpret_cast<const bf16x8*>((char*)SA(b, h) + lds_byte(wr * 64 + m * 16 + fr, k * 32 + fq * 8))
; #define LDB(dst, b, h) _Pragma("unroll") for (int n = 0; n < 2; ++n) _Pragma("unroll") for (int k = 0; k < 2; ++k) \
;     dst[n][k] = *reinterpret_cast<const bf16x8*>((char*)SB(b, h) + lds_byte(wc * 32 + n * 16 + fr, k * 32 + fq * 8))
; #define MMA(ai, bj, At_, Bt_) do { __builtin_amdgcn_s_setprio(1); \
;     _Pragma("unroll") for (int k = 0; k < 2; ++k) _Pragma("unroll") for (int m = 0; m < 4; ++m) _Pragma("unroll") for (int n = 0; n < 2; ++n) \
;       acc[ai][bj][m][n] = __builtin_amdgcn_mfma_f32_16x16x32_bf16(At_[m][k], Bt_[n][k], acc[ai][bj][m][n], 0, 0, 0); \
;     __builtin_amdgcn_s_setprio(0); } while (0)
; #define WAIT_V(n) asm volatile("s_waitcnt vmcnt(" #n ")" ::: "memory")
; #define BAR __builtin_amdgcn_s_barrier()
; template <int EPI, int N, int K>
; __device__ __forceinline__ void gemm_phase(const bf16_t* __restrict__ A, const bf16_t* __restrict__ Bt, const EpiArgs ea) {
;     ...
;       LDA(At, 0, 1); WAIT_V(4); BAR; WAIT_L(0); MMA(1, 0, At, B0); MMA(1, 1, At, B1); BAR; }
;     { LDB(B0, 1, 0); LDA(At, 1, 0); WAIT_V(2); BAR; WAIT_L(0); MMA(0, 0, At, B0); BAR;
	s_waitcnt lgkmcnt(0)
	s_setprio 1
	v_mfma_f32_16x16x32_bf16 v[52:55], v[178:181], v[154:157], v[52:55]
	v_mfma_f32_16x16x32_bf16 v[48:51], v[178:181], v[162:165], v[48:51]
	v_mfma_f32_16x16x32_bf16 v[44:47], v[186:189], v[154:157], v[44:47]
	v_mfma_f32_16x16x32_bf16 v[40:43], v[186:189], v[162:165], v[40:43]
	v_mfma_f32_16x16x32_bf16 v[36:39], v[194:197], v[154:157], v[36:39]
	v_mfma_f32_16x16x32_bf16 v[32:35], v[194:197], v[162:165], v[32:35]
	v_mfma_f32_16x16x32_bf16 v[60:63], v[80:83], v[154:157], v[60:63]
	v_mfma_f32_16x16x32_bf16 v[56:59], v[80:83], v[162:165], v[56:59]
	v_mfma_f32_16x16x32_bf16 v[52:55], v[182:185], v[158:161], v[52:55]
	v_mfma_f32_16x16x32_bf16 v[48:51], v[182:185], v[166:169], v[48:51]
	v_mfma_f32_16x16x32_bf16 v[44:47], v[190:193], v[158:161], v[44:47]
	v_mfma_f32_16x16x32_bf16 v[40:43], v[190:193], v[166:169], v[40:43]
	v_mfma_f32_16x16x32_bf16 v[36:39], v[198:201], v[158:161], v[36:39]
	v_mfma_f32_16x16x32_bf16 v[32:35], v[198:201], v[166:169], v[32:35]
	v_mfma_f32_16x16x32_bf16 v[154:157], v[84:87], v[158:161], v[60:63]
	v_mfma_f32_16x16x32_bf16 v[162:165], v[84:87], v[166:169], v[56:59]
	s_setprio 0
	s_setprio 1
	v_mfma_f32_16x16x32_bf16 v[28:31], v[80:83], v[202:205], v[28:31]
	v_mfma_f32_16x16x32_bf16 v[24:27], v[80:83], v[210:213], v[24:27]
	v_mfma_f32_16x16x32_bf16 v[12:15], v[186:189], v[202:205], v[12:15]
	v_mfma_f32_16x16x32_bf16 v[8:11], v[186:189], v[210:213], v[8:11]
	v_mfma_f32_16x16x32_bf16 v[20:23], v[178:181], v[202:205], v[20:23]
	v_mfma_f32_16x16x32_bf16 v[16:19], v[178:181], v[210:213], v[16:19]
	v_mfma_f32_16x16x32_bf16 v[4:7], v[194:197], v[202:205], v[4:7]
	v_mfma_f32_16x16x32_bf16 v[0:3], v[194:197], v[210:213], v[0:3]
	v_mfma_f32_16x16x32_bf16 v[28:31], v[84:87], v[206:209], v[28:31]
	v_mfma_f32_16x16x32_bf16 v[24:27], v[84:87], v[214:217], v[24:27]
	v_mfma_f32_16x16x32_bf16 v[12:15], v[190:193], v[206:209], v[12:15]
	v_mfma_f32_16x16x32_bf16 v[8:11], v[190:193], v[214:217], v[8:11]
	v_mfma_f32_16x16x32_bf16 v[158:161], v[182:185], v[206:209], v[20:23]
	v_mfma_f32_16x16x32_bf16 v[166:169], v[182:185], v[214:217], v[16:19]
	v_mfma_f32_16x16x32_bf16 v[178:181], v[198:201], v[206:209], v[4:7]
	v_mfma_f32_16x16x32_bf16 v[182:185], v[198:201], v[214:217], v[0:3]
	s_setprio 0
	s_barrier
	s_nop 0
	ds_read_b128 v[0:3], v151
	ds_read_b128 v[4:7], v151 offset:1024
	ds_read_b128 v[16:19], v151 offset:2048
	ds_read_b128 v[186:189], v151 offset:3072
	ds_read_b128 v[20:23], v146 offset:32768
	ds_read_b128 v[190:193], v146 offset:33792
	ds_read_b128 v[194:197], v147 offset:32768
	ds_read_b128 v[198:201], v147 offset:33792
	ds_read_b128 v[202:205], v148 offset:32768
	ds_read_b128 v[206:209], v148 offset:33792
	ds_read_b128 v[210:213], v149 offset:32768
	ds_read_b128 v[214:217], v149 offset:33792
	s_waitcnt vmcnt(2)
	s_barrier
	s_waitcnt lgkmcnt(0)
	s_setprio 1
	v_mfma_f32_16x16x32_bf16 v[56:59], v[20:23], v[0:3], v[124:127]
	v_mfma_f32_16x16x32_bf16 v[60:63], v[20:23], v[16:19], v[120:123]
	v_mfma_f32_16x16x32_bf16 v[80:83], v[194:197], v[0:3], v[116:119]
	v_mfma_f32_16x16x32_bf16 v[84:87], v[194:197], v[16:19], v[112:115]
	v_mfma_f32_16x16x32_bf16 v[108:111], v[202:205], v[0:3], v[108:111]
	v_mfma_f32_16x16x32_bf16 v[104:107], v[202:205], v[16:19], v[104:107]
	v_mfma_f32_16x16x32_bf16 v[120:123], v[210:213], v[0:3], v[100:103]
	v_mfma_f32_16x16x32_bf16 v[124:127], v[210:213], v[16:19], v[96:99]
	v_mfma_f32_16x16x32_bf16 v[116:119], v[190:193], v[4:7], v[56:59]
	v_mfma_f32_16x16x32_bf16 v[112:115], v[190:193], v[186:189], v[60:63]
	v_mfma_f32_16x16x32_bf16 v[100:103], v[198:201], v[4:7], v[80:83]
	v_mfma_f32_16x16x32_bf16 v[96:99], v[198:201], v[186:189], v[84:87]
	v_mfma_f32_16x16x32_bf16 v[84:87], v[206:209], v[4:7], v[108:111]
	v_mfma_f32_16x16x32_bf16 v[80:83], v[206:209], v[186:189], v[104:107]
	v_mfma_f32_16x16x32_bf16 v[60:63], v[214:217], v[4:7], v[120:123]
	v_mfma_f32_16x16x32_bf16 v[56:59], v[214:217], v[186:189], v[124:127]
	s_setprio 0
	s_barrier
; #define LDA(dst, b, h) _Pragma("unroll") for (int m = 0; m < 4; ++m) _Pragma("unroll") for (int k = 0; k < 2; ++k) \
;     dst[m][k] = *reinterpret_cast<const bf16x8*>((char*)SA(b, h) + lds_byte(wr * 64 + m * 16 + fr, k * 32 + fq * 8))
; #define LDB(dst, b, h) _Pragma("unroll") for (int n = 0; n < 2; ++n) _Pragma("unroll") for (int k = 0; k < 2; ++k) \
;     dst[n][k] = *reinterpret_cast<const bf16x8*>((char*)SB(b, h) + lds_byte(wc * 32 + n * 16 + fr, k * 32 + fq * 8))
; #define MMA(ai, bj, At_, Bt_) do { __builtin_amdgcn_s_setprio(1); \
;     _Pragma("unroll") for (int k = 0; k < 2; ++k) _Pragma("unroll") for (int m = 0; m < 4; ++m) _Pragma("unroll") for (int n = 0; n < 2; ++n) \
;       acc[ai][bj][m][n] = __builtin_amdgcn_mfma_f32_16x16x32_bf16(At_[m][k], Bt_[n][k], acc[ai][bj][m][n], 0, 0, 0); \
;     __builtin_amdgcn_s_setprio(0); } while (0)
; #define WAIT_V(n) asm volatile("s_waitcnt vmcnt(" #n ")" ::: "memory")
; #define BAR __builtin_amdgcn_s_barrier()
; template <int EPI, int N, int K>
; __device__ __forceinline__ void gemm_phase(const bf16_t* __restrict__ A, const bf16_t* __restrict__ Bt, const EpiArgs ea) {
;     ...
;     { LDB(B0, 1, 0); LDA(At, 1, 0); WAIT_V(2); BAR; WAIT_L(0); MMA(0, 0, At, B0); BAR;
;       LDB(B1, 1, 1); WAIT_V(0); BAR; WAIT_L(0); MMA(0, 1, At, B1); BAR;
;       LDA(At, 1, 1); BAR; WAIT_L(0); MMA(1, 0, At, B0); MMA(1, 1, At, B1); BAR; }
;     if (wr == 0) BAR;
	ds_read_b128 v[218:221], v152
	ds_read_b128 v[222:225], v152 offset:1024
	ds_read_b128 v[226:229], v152 offset:2048
	ds_read_b128 v[230:233], v152 offset:3072
	s_waitcnt vmcnt(0)
	s_barrier
	s_waitcnt lgkmcnt(0)
	s_setprio 1
	v_mfma_f32_16x16x32_bf16 v[92:95], v[20:23], v[218:221], v[92:95]
	v_mfma_f32_16x16x32_bf16 v[20:23], v[20:23], v[226:229], v[88:91]
	v_mfma_f32_16x16x32_bf16 v[88:91], v[194:197], v[218:221], v[170:173]
	v_mfma_f32_16x16x32_bf16 v[104:107], v[194:197], v[226:229], v[174:177]
	v_mfma_f32_16x16x32_bf16 v[76:79], v[202:205], v[218:221], v[76:79]
	v_mfma_f32_16x16x32_bf16 v[72:75], v[202:205], v[226:229], v[72:75]
	v_mfma_f32_16x16x32_bf16 v[68:71], v[210:213], v[218:221], v[68:71]
	v_mfma_f32_16x16x32_bf16 v[64:67], v[210:213], v[226:229], v[64:67]
	v_mfma_f32_16x16x32_bf16 v[124:127], v[190:193], v[222:225], v[92:95]
	v_mfma_f32_16x16x32_bf16 v[120:123], v[190:193], v[230:233], v[20:23]
	v_mfma_f32_16x16x32_bf16 v[108:111], v[198:201], v[222:225], v[88:91]
	v_mfma_f32_16x16x32_bf16 v[104:107], v[198:201], v[230:233], v[104:107]
	v_mfma_f32_16x16x32_bf16 v[92:95], v[206:209], v[222:225], v[76:79]
	v_mfma_f32_16x16x32_bf16 v[88:91], v[206:209], v[230:233], v[72:75]
	v_mfma_f32_16x16x32_bf16 v[76:79], v[214:217], v[222:225], v[68:71]
	v_mfma_f32_16x16x32_bf16 v[72:75], v[214:217], v[230:233], v[64:67]
	s_setprio 0
	s_barrier
	s_nop 0
	ds_read_b128 v[64:67], v146 offset:49152
	ds_read_b128 v[170:173], v146 offset:50176
	ds_read_b128 v[68:71], v147 offset:49152
	ds_read_b128 v[174:177], v147 offset:50176
	ds_read_b128 v[190:193], v148 offset:49152
	ds_read_b128 v[194:197], v148 offset:50176
	ds_read_b128 v[198:201], v149 offset:49152
	ds_read_b128 v[202:205], v149 offset:50176
	s_barrier
	s_waitcnt lgkmcnt(0)
	s_setprio 1
	v_mfma_f32_16x16x32_bf16 v[20:23], v[64:67], v[0:3], v[154:157]
	v_mfma_f32_16x16x32_bf16 v[154:157], v[64:67], v[16:19], v[162:165]
	v_mfma_f32_16x16x32_bf16 v[162:165], v[68:71], v[0:3], v[52:55]
	v_mfma_f32_16x16x32_bf16 v[206:209], v[68:71], v[16:19], v[48:51]
	v_mfma_f32_16x16x32_bf16 v[44:47], v[190:193], v[0:3], v[44:47]
	v_mfma_f32_16x16x32_bf16 v[40:43], v[190:193], v[16:19], v[40:43]
	v_mfma_f32_16x16x32_bf16 v[0:3], v[198:201], v[0:3], v[36:39]
	v_mfma_f32_16x16x32_bf16 v[210:213], v[198:201], v[16:19], v[32:35]
	v_mfma_f32_16x16x32_bf16 v[52:55], v[170:173], v[4:7], v[20:23]
	v_mfma_f32_16x16x32_bf16 v[48:51], v[170:173], v[186:189], v[154:157]
	v_mfma_f32_16x16x32_bf16 v[36:39], v[174:177], v[4:7], v[162:165]
	v_mfma_f32_16x16x32_bf16 v[32:35], v[174:177], v[186:189], v[206:209]
	v_mfma_f32_16x16x32_bf16 v[20:23], v[194:197], v[4:7], v[44:47]
	v_mfma_f32_16x16x32_bf16 v[16:19], v[194:197], v[186:189], v[40:43]
	v_mfma_f32_16x16x32_bf16 v[4:7], v[202:205], v[4:7], v[0:3]
	v_mfma_f32_16x16x32_bf16 v[0:3], v[202:205], v[186:189], v[210:213]
	s_setprio 0
	s_setprio 1
	v_mfma_f32_16x16x32_bf16 v[28:31], v[64:67], v[218:221], v[28:31]
	v_mfma_f32_16x16x32_bf16 v[24:27], v[64:67], v[226:229], v[24:27]
	v_mfma_f32_16x16x32_bf16 v[40:43], v[68:71], v[218:221], v[158:161]
	v_mfma_f32_16x16x32_bf16 v[154:157], v[68:71], v[226:229], v[166:169]
	v_mfma_f32_16x16x32_bf16 v[12:15], v[190:193], v[218:221], v[12:15]
	v_mfma_f32_16x16x32_bf16 v[8:11], v[190:193], v[226:229], v[8:11]
	v_mfma_f32_16x16x32_bf16 v[158:161], v[198:201], v[218:221], v[178:181]
	v_mfma_f32_16x16x32_bf16 v[162:165], v[198:201], v[226:229], v[182:185]
	v_mfma_f32_16x16x32_bf16 v[68:71], v[170:173], v[222:225], v[28:31]
	v_mfma_f32_16x16x32_bf16 v[64:67], v[170:173], v[230:233], v[24:27]
	v_mfma_f32_16x16x32_bf16 v[44:47], v[174:177], v[222:225], v[40:43]
	v_mfma_f32_16x16x32_bf16 v[40:43], v[174:177], v[230:233], v[154:157]
	v_mfma_f32_16x16x32_bf16 v[28:31], v[194:197], v[222:225], v[12:15]
	v_mfma_f32_16x16x32_bf16 v[24:27], v[194:197], v[230:233], v[8:11]
	v_mfma_f32_16x16x32_bf16 v[12:15], v[202:205], v[222:225], v[158:161]
	v_mfma_f32_16x16x32_bf16 v[8:11], v[202:205], v[230:233], v[162:165]
	s_setprio 0
	s_barrier
	s_and_saveexec_b64 s[0:1], s[6:7]
	s_cbranch_execz .LBB0_273
	s_barrier

; #define STAGE_A(POFF, h, kt) STAGE_AX(POFF, h, kt, brow)
; #define STAGE_B(POFF, h, kt) STAGE_BX(POFF, h, kt, bcol)
; #define LDA(dst, b, h) _Pragma("unroll") for (int m = 0; m < 4; ++m) _Pragma("unroll") for (int k = 0; k < 2; ++k) \
;     dst[m][k] = *reinterpret_cast<const bf16x8*>((char*)SA(b, h) + lds_byte(wr * 64 + m * 16 + fr, k * 32 + fq * 8))
; #define LDB(dst, b, h) _Pragma("unroll") for (int n = 0; n < 2; ++n) _Pragma("unroll") for (int k = 0; k < 2; ++k) \
;     dst[n][k] = *reinterpret_cast<const bf16x8*>((char*)SB(b, h) + lds_byte(wc * 32 + n * 16 + fr, k * 32 + fq * 8))
; #define MMA(ai, bj, At_, Bt_) do { __builtin_amdgcn_s_setprio(1); \
;     _Pragma("unroll") for (int k = 0; k < 2; ++k) _Pragma("unroll") for (int m = 0; m < 4; ++m) _Pragma("unroll") for (int n = 0; n < 2; ++n) \
;       acc[ai][bj][m][n] = __builtin_amdgcn_mfma_f32_16x16x32_bf16(At_[m][k], Bt_[n][k], acc[ai][bj][m][n], 0, 0, 0); \
;     __builtin_amdgcn_s_setprio(0); } while (0)
; #define WAIT_V(n) asm volatile("s_waitcnt vmcnt(" #n ")" ::: "memory")
; #define BAR __builtin_amdgcn_s_barrier()
; #define SCHED __builtin_amdgcn_sched_barrier(0)
; template <int EPI, int N, int K>
; __device__ __forceinline__ void gemm_phase(const bf16_t* __restrict__ A, const bf16_t* __restrict__ Bt, const EpiArgs ea) {
;     ...
;     for (int t = 0; t < nt - 2; t += 2) {
;       LDB(B0, 0, 0); SCHED; LDA(At, 0, 0); STAGE_A(SA_OFF(1, 1), 1, t + 1);
;       WAIT_L(8); BAR; WAIT_L(0); MMA(0, 0, At, B0); BAR; SCHED;
;       LDB(B1, 0, 1); STAGE_B(SB_OFF(0, 0), 0, t + 2);
;       BAR; WAIT_L(0); MMA(0, 1, At, B1); BAR;
;       LDA(At, 0, 1); STAGE_A(SA_OFF(0, 0), 0, t + 2);
;       BAR; WAIT_L(0); MMA(1, 0, At, B0); BAR; SCHED;
;       STAGE_B(SB_OFF(0, 1), 1, t + 2);
;       WAIT_V(6); BAR; MMA(1, 1, At, B1); BAR;
.LBB0_390:
	ds_read_b128 v[218:221], v148 offset:16384
	ds_read_b128 v[222:225], v148 offset:17408
	ds_read_b128 v[226:229], v149 offset:16384
	ds_read_b128 v[230:233], v149 offset:17408
	ds_read_b128 v[238:241], v150 offset:16384
	ds_read_b128 v[242:245], v150 offset:17408
	s_add_i32 s36, s31, s35
	s_or_b32 s37, s36, 0x80080
	s_mov_b32 s62, s50
	s_mov_b32 s63, s51
	s_mov_b32 m0, s28
	s_nop 0
	buffer_load_dwordx4 v131, s[60:63], s37 offen lds
	s_or_b32 s37, s36, 0xc0080
	s_mov_b32 m0, s29
	s_nop 0
	buffer_load_dwordx4 v131, s[60:63], s37 offen lds
	s_setprio 1
	s_barrier
	s_waitcnt lgkmcnt(6)
	v_mfma_f32_16x16x32_bf16 v[124:127], v[168:171], v[132:135], v[124:127]
	v_mfma_f32_16x16x32_bf16 v[120:123], v[168:171], v[160:163], v[120:123]
	v_mfma_f32_16x16x32_bf16 v[116:119], v[176:179], v[132:135], v[116:119]
	v_mfma_f32_16x16x32_bf16 v[112:115], v[176:179], v[160:163], v[112:115]
	v_mfma_f32_16x16x32_bf16 v[108:111], v[184:187], v[132:135], v[108:111]
	v_mfma_f32_16x16x32_bf16 v[104:107], v[184:187], v[160:163], v[104:107]
	v_mfma_f32_16x16x32_bf16 v[100:103], v[192:195], v[132:135], v[100:103]
	v_mfma_f32_16x16x32_bf16 v[96:99], v[192:195], v[160:163], v[96:99]
	v_mfma_f32_16x16x32_bf16 v[124:127], v[172:175], v[156:159], v[124:127]
	v_mfma_f32_16x16x32_bf16 v[120:123], v[172:175], v[164:167], v[120:123]
	v_mfma_f32_16x16x32_bf16 v[116:119], v[180:183], v[156:159], v[116:119]
	v_mfma_f32_16x16x32_bf16 v[112:115], v[180:183], v[164:167], v[112:115]
	v_mfma_f32_16x16x32_bf16 v[108:111], v[188:191], v[156:159], v[108:111]
	v_mfma_f32_16x16x32_bf16 v[104:107], v[188:191], v[164:167], v[104:107]
	v_mfma_f32_16x16x32_bf16 v[100:103], v[196:199], v[156:159], v[100:103]
	v_mfma_f32_16x16x32_bf16 v[96:99], v[196:199], v[164:167], v[96:99]
	s_barrier
	s_setprio 0
	ds_read_b128 v[200:203], v152
	ds_read_b128 v[204:207], v152 offset:1024
	ds_read_b128 v[208:211], v152 offset:2048
	ds_read_b128 v[212:215], v152 offset:3072
	ds_read_b128 v[246:249], v151 offset:16384
	ds_read_b128 v[250:253], v151 offset:17408
	s_add_i32 s37, s13, s35
	s_add_i32 s38, s37, 0x100
	s_mov_b32 m0, s15
	s_nop 0
	buffer_load_dwordx4 v144, s[76:79], s38 offen lds
	s_add_i32 s38, s37, 0x80100
	s_mov_b32 m0, s16
	s_nop 0
	buffer_load_dwordx4 v144, s[76:79], s38 offen lds
	s_waitcnt vmcnt(6)
	s_setprio 1
	s_barrier
	s_waitcnt lgkmcnt(2)
	v_mfma_f32_16x16x32_bf16 v[92:95], v[168:171], v[200:203], v[92:95]
	v_mfma_f32_16x16x32_bf16 v[88:91], v[168:171], v[208:211], v[88:91]
	v_mfma_f32_16x16x32_bf16 v[84:87], v[176:179], v[200:203], v[84:87]
	v_mfma_f32_16x16x32_bf16 v[80:83], v[176:179], v[208:211], v[80:83]
	v_mfma_f32_16x16x32_bf16 v[76:79], v[184:187], v[200:203], v[76:79]
	v_mfma_f32_16x16x32_bf16 v[72:75], v[184:187], v[208:211], v[72:75]
	v_mfma_f32_16x16x32_bf16 v[68:71], v[192:195], v[200:203], v[68:71]
	v_mfma_f32_16x16x32_bf16 v[64:67], v[192:195], v[208:211], v[64:67]
	v_mfma_f32_16x16x32_bf16 v[92:95], v[172:175], v[204:207], v[92:95]
	v_mfma_f32_16x16x32_bf16 v[88:91], v[172:175], v[212:215], v[88:91]
	v_mfma_f32_16x16x32_bf16 v[84:87], v[180:183], v[204:207], v[84:87]
	v_mfma_f32_16x16x32_bf16 v[80:83], v[180:183], v[212:215], v[80:83]
	v_mfma_f32_16x16x32_bf16 v[76:79], v[188:191], v[204:207], v[76:79]
	v_mfma_f32_16x16x32_bf16 v[72:75], v[188:191], v[212:215], v[72:75]
	v_mfma_f32_16x16x32_bf16 v[68:71], v[196:199], v[204:207], v[68:71]
	v_mfma_f32_16x16x32_bf16 v[64:67], v[196:199], v[212:215], v[64:67]
	s_barrier
	s_setprio 0
	ds_read_b128 v[168:171], v148 offset:32768
	ds_read_b128 v[172:175], v148 offset:33792
	ds_read_b128 v[176:179], v149 offset:32768
	ds_read_b128 v[180:183], v149 offset:33792
	ds_read_b128 v[184:187], v150 offset:32768
	ds_read_b128 v[188:191], v150 offset:33792
	s_add_i32 s38, s36, 0x100
	s_mov_b32 m0, s14
	s_nop 0
	buffer_load_dwordx4 v131, s[60:63], s38 offen lds
	s_add_i32 s39, s36, 0x40100
	s_mov_b32 m0, s17
	s_nop 0
	buffer_load_dwordx4 v131, s[60:63], s39 offen lds
	s_waitcnt vmcnt(10)
	s_setprio 1
	s_barrier
	s_waitcnt lgkmcnt(6)
	v_mfma_f32_16x16x32_bf16 v[60:63], v[218:221], v[132:135], v[60:63]
	v_mfma_f32_16x16x32_bf16 v[56:59], v[218:221], v[160:163], v[56:59]
	v_mfma_f32_16x16x32_bf16 v[52:55], v[226:229], v[132:135], v[52:55]
	v_mfma_f32_16x16x32_bf16 v[48:51], v[226:229], v[160:163], v[48:51]
	v_mfma_f32_16x16x32_bf16 v[44:47], v[238:241], v[132:135], v[44:47]
	v_mfma_f32_16x16x32_bf16 v[40:43], v[238:241], v[160:163], v[40:43]
	v_mfma_f32_16x16x32_bf16 v[36:39], v[246:249], v[132:135], v[36:39]
	v_mfma_f32_16x16x32_bf16 v[32:35], v[246:249], v[160:163], v[32:35]
	v_mfma_f32_16x16x32_bf16 v[60:63], v[222:225], v[156:159], v[60:63]
	v_mfma_f32_16x16x32_bf16 v[56:59], v[222:225], v[164:167], v[56:59]
	v_mfma_f32_16x16x32_bf16 v[52:55], v[230:233], v[156:159], v[52:55]
	v_mfma_f32_16x16x32_bf16 v[48:51], v[230:233], v[164:167], v[48:51]
	v_mfma_f32_16x16x32_bf16 v[44:47], v[242:245], v[156:159], v[44:47]
	v_mfma_f32_16x16x32_bf16 v[40:43], v[242:245], v[164:167], v[40:43]
	v_mfma_f32_16x16x32_bf16 v[36:39], v[250:253], v[156:159], v[36:39]
	v_mfma_f32_16x16x32_bf16 v[32:35], v[250:253], v[164:167], v[32:35]
	s_barrier
	s_setprio 0
	ds_read_b128 v[132:135], v153
	ds_read_b128 v[156:159], v153 offset:1024
	ds_read_b128 v[160:163], v153 offset:2048
	ds_read_b128 v[164:167], v153 offset:3072
	ds_read_b128 v[192:195], v151 offset:32768
	ds_read_b128 v[196:199], v151 offset:33792
	s_add_i32 s39, s37, 0x2100
	s_mov_b32 m0, s18
	s_nop 0
	buffer_load_dwordx4 v144, s[76:79], s39 offen lds
	s_add_i32 s39, s37, 0x82100
	s_mov_b32 m0, s19
	s_nop 0
	buffer_load_dwordx4 v144, s[76:79], s39 offen lds
	s_waitcnt vmcnt(6)
	s_setprio 1
	s_barrier
; #define STAGE_A(POFF, h, kt) STAGE_AX(POFF, h, kt, brow)
; #define STAGE_B(POFF, h, kt) STAGE_BX(POFF, h, kt, bcol)
; #define LDA(dst, b, h) _Pragma("unroll") for (int m = 0; m < 4; ++m) _Pragma("unroll") for (int k = 0; k < 2; ++k) \
;     dst[m][k] = *reinterpret_cast<const bf16x8*>((char*)SA(b, h) + lds_byte(wr * 64 + m * 16 + fr, k * 32 + fq * 8))
; #define LDB(dst, b, h) _Pragma("unroll") for (int n = 0; n < 2; ++n) _Pragma("unroll") for (int k = 0; k < 2; ++k) \
;     dst[n][k] = *reinterpret_cast<const bf16x8*>((char*)SB(b, h) + lds_byte(wc * 32 + n * 16 + fr, k * 32 + fq * 8))
; #define MMA(ai, bj, At_, Bt_) do { __builtin_amdgcn_s_setprio(1); \
;     _Pragma("unroll") for (int k = 0; k < 2; ++k) _Pragma("unroll") for (int m = 0; m < 4; ++m) _Pragma("unroll") for (int n = 0; n < 2; ++n) \
;       acc[ai][bj][m][n] = __builtin_amdgcn_mfma_f32_16x16x32_bf16(At_[m][k], Bt_[n][k], acc[ai][bj][m][n], 0, 0, 0); \
;     __builtin_amdgcn_s_setprio(0); } while (0)
; #define WAIT_V(n) asm volatile("s_waitcnt vmcnt(" #n ")" ::: "memory")
; #define BAR __builtin_amdgcn_s_barrier()
; #define SCHED __builtin_amdgcn_sched_barrier(0)
; template <int EPI, int N, int K>
; __device__ __forceinline__ void gemm_phase(const bf16_t* __restrict__ A, const bf16_t* __restrict__ Bt, const EpiArgs ea) {
;     ...
;       WAIT_V(6); BAR; MMA(1, 1, At, B1); BAR;
;       LDB(B0, 1, 0); SCHED; LDA(At, 1, 0); STAGE_A(SA_OFF(0, 1), 1, t + 2);
;       WAIT_L(8); BAR; WAIT_L(0); MMA(0, 0, At, B0); BAR; SCHED;
;       LDB(B1, 1, 1); STAGE_B(SB_OFF(1, 0), 0, t + 3);
;       BAR; WAIT_L(0); MMA(0, 1, At, B1); BAR;
;       LDA(At, 1, 1); STAGE_A(SA_OFF(1, 0), 0, t + 3);
;       BAR; WAIT_L(0); MMA(1, 0, At, B0); BAR; SCHED;
;       STAGE_B(SB_OFF(1, 1), 1, t + 3);
;       WAIT_V(6); BAR; MMA(1, 1, At, B1); BAR;
	v_mfma_f32_16x16x32_bf16 v[28:31], v[218:221], v[200:203], v[28:31]
	v_mfma_f32_16x16x32_bf16 v[24:27], v[218:221], v[208:211], v[24:27]
	v_mfma_f32_16x16x32_bf16 v[20:23], v[226:229], v[200:203], v[20:23]
	v_mfma_f32_16x16x32_bf16 v[16:19], v[226:229], v[208:211], v[16:19]
	v_mfma_f32_16x16x32_bf16 v[12:15], v[238:241], v[200:203], v[12:15]
	v_mfma_f32_16x16x32_bf16 v[8:11], v[238:241], v[208:211], v[8:11]
	v_mfma_f32_16x16x32_bf16 v[4:7], v[246:249], v[200:203], v[4:7]
	v_mfma_f32_16x16x32_bf16 v[0:3], v[246:249], v[208:211], v[0:3]
	v_mfma_f32_16x16x32_bf16 v[28:31], v[222:225], v[204:207], v[28:31]
	v_mfma_f32_16x16x32_bf16 v[24:27], v[222:225], v[212:215], v[24:27]
	v_mfma_f32_16x16x32_bf16 v[20:23], v[230:233], v[204:207], v[20:23]
	v_mfma_f32_16x16x32_bf16 v[16:19], v[230:233], v[212:215], v[16:19]
	v_mfma_f32_16x16x32_bf16 v[12:15], v[242:245], v[204:207], v[12:15]
	v_mfma_f32_16x16x32_bf16 v[8:11], v[242:245], v[212:215], v[8:11]
	v_mfma_f32_16x16x32_bf16 v[4:7], v[250:253], v[204:207], v[4:7]
	v_mfma_f32_16x16x32_bf16 v[0:3], v[250:253], v[212:215], v[0:3]
	s_barrier
	s_setprio 0
	ds_read_b128 v[218:221], v148 offset:49152
	ds_read_b128 v[222:225], v148 offset:50176
	ds_read_b128 v[226:229], v149 offset:49152
	ds_read_b128 v[230:233], v149 offset:50176
	ds_read_b128 v[238:241], v150 offset:49152
	ds_read_b128 v[242:245], v150 offset:50176
	s_or_b32 s39, s38, 0x80000
	s_mov_b32 m0, s20
	s_nop 0
	buffer_load_dwordx4 v131, s[60:63], s39 offen lds
	s_or_b32 s38, s38, 0xc0000
	s_mov_b32 m0, s21
	s_nop 0
	buffer_load_dwordx4 v131, s[60:63], s38 offen lds
	s_setprio 1
	s_barrier
	s_waitcnt lgkmcnt(6)
	v_mfma_f32_16x16x32_bf16 v[124:127], v[168:171], v[132:135], v[124:127]
	v_mfma_f32_16x16x32_bf16 v[120:123], v[168:171], v[160:163], v[120:123]
	v_mfma_f32_16x16x32_bf16 v[116:119], v[176:179], v[132:135], v[116:119]
	v_mfma_f32_16x16x32_bf16 v[112:115], v[176:179], v[160:163], v[112:115]
	v_mfma_f32_16x16x32_bf16 v[108:111], v[184:187], v[132:135], v[108:111]
	v_mfma_f32_16x16x32_bf16 v[104:107], v[184:187], v[160:163], v[104:107]
	v_mfma_f32_16x16x32_bf16 v[100:103], v[192:195], v[132:135], v[100:103]
	v_mfma_f32_16x16x32_bf16 v[96:99], v[192:195], v[160:163], v[96:99]
	v_mfma_f32_16x16x32_bf16 v[124:127], v[172:175], v[156:159], v[124:127]
	v_mfma_f32_16x16x32_bf16 v[120:123], v[172:175], v[164:167], v[120:123]
	v_mfma_f32_16x16x32_bf16 v[116:119], v[180:183], v[156:159], v[116:119]
	v_mfma_f32_16x16x32_bf16 v[112:115], v[180:183], v[164:167], v[112:115]
	v_mfma_f32_16x16x32_bf16 v[108:111], v[188:191], v[156:159], v[108:111]
	v_mfma_f32_16x16x32_bf16 v[104:107], v[188:191], v[164:167], v[104:107]
	v_mfma_f32_16x16x32_bf16 v[100:103], v[196:199], v[156:159], v[100:103]
	v_mfma_f32_16x16x32_bf16 v[96:99], v[196:199], v[164:167], v[96:99]
	s_barrier
	s_setprio 0
	ds_read_b128 v[200:203], v154
	ds_read_b128 v[204:207], v154 offset:1024
	ds_read_b128 v[208:211], v154 offset:2048
	ds_read_b128 v[212:215], v154 offset:3072
	ds_read_b128 v[246:249], v151 offset:49152
	ds_read_b128 v[250:253], v151 offset:50176
	s_add_i32 s38, s37, 0x180
	s_mov_b32 m0, s22
	s_nop 0
	buffer_load_dwordx4 v144, s[76:79], s38 offen lds
	s_add_i32 s38, s37, 0x80180
	s_mov_b32 m0, s23
	s_nop 0
	buffer_load_dwordx4 v144, s[76:79], s38 offen lds
	s_waitcnt vmcnt(6)
	s_setprio 1
	s_barrier
	s_waitcnt lgkmcnt(2)
	v_mfma_f32_16x16x32_bf16 v[92:95], v[168:171], v[200:203], v[92:95]
	v_mfma_f32_16x16x32_bf16 v[88:91], v[168:171], v[208:211], v[88:91]
	v_mfma_f32_16x16x32_bf16 v[84:87], v[176:179], v[200:203], v[84:87]
	v_mfma_f32_16x16x32_bf16 v[80:83], v[176:179], v[208:211], v[80:83]
	v_mfma_f32_16x16x32_bf16 v[76:79], v[184:187], v[200:203], v[76:79]
	v_mfma_f32_16x16x32_bf16 v[72:75], v[184:187], v[208:211], v[72:75]
	v_mfma_f32_16x16x32_bf16 v[68:71], v[192:195], v[200:203], v[68:71]
	v_mfma_f32_16x16x32_bf16 v[64:67], v[192:195], v[208:211], v[64:67]
	v_mfma_f32_16x16x32_bf16 v[92:95], v[172:175], v[204:207], v[92:95]
	v_mfma_f32_16x16x32_bf16 v[88:91], v[172:175], v[212:215], v[88:91]
	v_mfma_f32_16x16x32_bf16 v[84:87], v[180:183], v[204:207], v[84:87]
	v_mfma_f32_16x16x32_bf16 v[80:83], v[180:183], v[212:215], v[80:83]
	v_mfma_f32_16x16x32_bf16 v[76:79], v[188:191], v[204:207], v[76:79]
	v_mfma_f32_16x16x32_bf16 v[72:75], v[188:191], v[212:215], v[72:75]
	v_mfma_f32_16x16x32_bf16 v[68:71], v[196:199], v[204:207], v[68:71]
	v_mfma_f32_16x16x32_bf16 v[64:67], v[196:199], v[212:215], v[64:67]
	s_barrier
	s_setprio 0
	ds_read_b128 v[168:171], v148
	ds_read_b128 v[172:175], v148 offset:1024
	ds_read_b128 v[176:179], v149
	ds_read_b128 v[180:183], v149 offset:1024
	ds_read_b128 v[184:187], v150
	ds_read_b128 v[188:191], v150 offset:1024
	s_add_i32 s38, s36, 0x180
	s_mov_b32 m0, s24
	s_nop 0
	buffer_load_dwordx4 v131, s[60:63], s38 offen lds
	s_add_i32 s36, s36, 0x40180
	s_mov_b32 m0, s25
	s_nop 0
	buffer_load_dwordx4 v131, s[60:63], s36 offen lds
	s_waitcnt vmcnt(10)
	s_setprio 1
	s_barrier
	s_waitcnt lgkmcnt(6)
	v_mfma_f32_16x16x32_bf16 v[60:63], v[218:221], v[132:135], v[60:63]
	v_mfma_f32_16x16x32_bf16 v[56:59], v[218:221], v[160:163], v[56:59]
	v_mfma_f32_16x16x32_bf16 v[52:55], v[226:229], v[132:135], v[52:55]
	v_mfma_f32_16x16x32_bf16 v[48:51], v[226:229], v[160:163], v[48:51]
	v_mfma_f32_16x16x32_bf16 v[44:47], v[238:241], v[132:135], v[44:47]
	v_mfma_f32_16x16x32_bf16 v[40:43], v[238:241], v[160:163], v[40:43]
	v_mfma_f32_16x16x32_bf16 v[36:39], v[246:249], v[132:135], v[36:39]
	v_mfma_f32_16x16x32_bf16 v[32:35], v[246:249], v[160:163], v[32:35]
	v_mfma_f32_16x16x32_bf16 v[60:63], v[222:225], v[156:159], v[60:63]
	v_mfma_f32_16x16x32_bf16 v[56:59], v[222:225], v[164:167], v[56:59]
	v_mfma_f32_16x16x32_bf16 v[52:55], v[230:233], v[156:159], v[52:55]
	v_mfma_f32_16x16x32_bf16 v[48:51], v[230:233], v[164:167], v[48:51]
	v_mfma_f32_16x16x32_bf16 v[44:47], v[242:245], v[156:159], v[44:47]
	v_mfma_f32_16x16x32_bf16 v[40:43], v[242:245], v[164:167], v[40:43]
	v_mfma_f32_16x16x32_bf16 v[36:39], v[250:253], v[156:159], v[36:39]
	v_mfma_f32_16x16x32_bf16 v[32:35], v[250:253], v[164:167], v[32:35]
	s_barrier
; #define STAGE_A(POFF, h, kt) STAGE_AX(POFF, h, kt, brow)
; #define LDA(dst, b, h) _Pragma("unroll") for (int m = 0; m < 4; ++m) _Pragma("unroll") for (int k = 0; k < 2; ++k) \
;     dst[m][k] = *reinterpret_cast<const bf16x8*>((char*)SA(b, h) + lds_byte(wr * 64 + m * 16 + fr, k * 32 + fq * 8))
; #define LDB(dst, b, h) _Pragma("unroll") for (int n = 0; n < 2; ++n) _Pragma("unroll") for (int k = 0; k < 2; ++k) \
;     dst[n][k] = *reinterpret_cast<const bf16x8*>((char*)SB(b, h) + lds_byte(wc * 32 + n * 16 + fr, k * 32 + fq * 8))
; #define MMA(ai, bj, At_, Bt_) do { __builtin_amdgcn_s_setprio(1); \
;     _Pragma("unroll") for (int k = 0; k < 2; ++k) _Pragma("unroll") for (int m = 0; m < 4; ++m) _Pragma("unroll") for (int n = 0; n < 2; ++n) \
;       acc[ai][bj][m][n] = __builtin_amdgcn_mfma_f32_16x16x32_bf16(At_[m][k], Bt_[n][k], acc[ai][bj][m][n], 0, 0, 0); \
;     __builtin_amdgcn_s_setprio(0); } while (0)
; #define WAIT_V(n) asm volatile("s_waitcnt vmcnt(" #n ")" ::: "memory")
; #define BAR __builtin_amdgcn_s_barrier()
; template <int EPI, int N, int K>
; __device__ __forceinline__ void gemm_phase(const bf16_t* __restrict__ A, const bf16_t* __restrict__ Bt, const EpiArgs ea) {
;     ...
;       WAIT_V(6); BAR; MMA(1, 1, At, B1); BAR;
;     }
;     { LDB(B0, 0, 0); LDA(At, 0, 0); STAGE_A(SA_OFF(1, 1), 1, nt - 1);
;       BAR; WAIT_L(0); MMA(0, 0, At, B0); BAR;
;       LDB(B1, 0, 1); BAR; WAIT_L(0); MMA(0, 1, At, B1); BAR;
;       LDA(At, 0, 1); WAIT_V(4); BAR; WAIT_L(0); MMA(1, 0, At, B0); MMA(1, 1, At, B1); BAR; }
;     { LDB(B0, 1, 0); LDA(At, 1, 0); WAIT_V(2); BAR; WAIT_L(0); MMA(0, 0, At, B0); BAR;
	s_setprio 0
	ds_read_b128 v[132:135], v147
	ds_read_b128 v[156:159], v147 offset:1024
	ds_read_b128 v[160:163], v147 offset:2048
	ds_read_b128 v[164:167], v147 offset:3072
	ds_read_b128 v[192:195], v151
	ds_read_b128 v[196:199], v151 offset:1024
	s_add_i32 s36, s37, 0x2180
	s_mov_b32 m0, s26
	s_nop 0
	buffer_load_dwordx4 v144, s[76:79], s36 offen lds
	s_add_i32 s37, s37, 0x82180
	s_mov_b32 m0, s27
	s_nop 0
	buffer_load_dwordx4 v144, s[76:79], s37 offen lds
	s_waitcnt vmcnt(6)
	s_setprio 1
	s_barrier
	v_mfma_f32_16x16x32_bf16 v[28:31], v[218:221], v[200:203], v[28:31]
	v_mfma_f32_16x16x32_bf16 v[24:27], v[218:221], v[208:211], v[24:27]
	v_mfma_f32_16x16x32_bf16 v[20:23], v[226:229], v[200:203], v[20:23]
	v_mfma_f32_16x16x32_bf16 v[16:19], v[226:229], v[208:211], v[16:19]
	v_mfma_f32_16x16x32_bf16 v[12:15], v[238:241], v[200:203], v[12:15]
	v_mfma_f32_16x16x32_bf16 v[8:11], v[238:241], v[208:211], v[8:11]
	v_mfma_f32_16x16x32_bf16 v[4:7], v[246:249], v[200:203], v[4:7]
	v_mfma_f32_16x16x32_bf16 v[0:3], v[246:249], v[208:211], v[0:3]
	v_mfma_f32_16x16x32_bf16 v[28:31], v[222:225], v[204:207], v[28:31]
	v_mfma_f32_16x16x32_bf16 v[24:27], v[222:225], v[212:215], v[24:27]
	v_mfma_f32_16x16x32_bf16 v[20:23], v[230:233], v[204:207], v[20:23]
	v_mfma_f32_16x16x32_bf16 v[16:19], v[230:233], v[212:215], v[16:19]
	v_mfma_f32_16x16x32_bf16 v[12:15], v[242:245], v[204:207], v[12:15]
	v_mfma_f32_16x16x32_bf16 v[8:11], v[242:245], v[212:215], v[8:11]
	v_mfma_f32_16x16x32_bf16 v[4:7], v[250:253], v[204:207], v[4:7]
	v_mfma_f32_16x16x32_bf16 v[0:3], v[250:253], v[212:215], v[0:3]
	s_barrier
	s_setprio 0
	s_add_i32 s34, s34, 2
	s_addk_i32 s35, 0x100
	s_cmp_lt_u32 s34, 28
	s_cbranch_scc1 .LBB0_390
	s_and_b32 s3, s3, 0x700
	s_lshl_b32 s2, s2, 11
	s_or_b32 s31, s3, s2
	s_lshl_b32 s2, s31, 12
	s_or_b32 s3, s2, 0x80f80
	s_mov_b32 m0, s28
	s_nop 0
	buffer_load_dwordx4 v131, s[60:63], s3 offen lds
	s_or_b32 s2, s2, 0xc0f80
	s_mov_b32 m0, s29
	s_nop 0
	buffer_load_dwordx4 v131, s[60:63], s2 offen lds
	s_barrier
	s_waitcnt lgkmcnt(0)
	s_setprio 1
	v_mfma_f32_16x16x32_bf16 v[124:127], v[168:171], v[132:135], v[124:127]
	v_mfma_f32_16x16x32_bf16 v[120:123], v[168:171], v[160:163], v[120:123]
	v_mfma_f32_16x16x32_bf16 v[116:119], v[176:179], v[132:135], v[116:119]
	v_mfma_f32_16x16x32_bf16 v[112:115], v[176:179], v[160:163], v[112:115]
	v_mfma_f32_16x16x32_bf16 v[108:111], v[184:187], v[132:135], v[108:111]
	v_mfma_f32_16x16x32_bf16 v[104:107], v[184:187], v[160:163], v[104:107]
	v_mfma_f32_16x16x32_bf16 v[100:103], v[192:195], v[132:135], v[100:103]
	v_mfma_f32_16x16x32_bf16 v[96:99], v[192:195], v[160:163], v[96:99]
	v_mfma_f32_16x16x32_bf16 v[124:127], v[172:175], v[156:159], v[124:127]
	v_mfma_f32_16x16x32_bf16 v[120:123], v[172:175], v[164:167], v[120:123]
	v_mfma_f32_16x16x32_bf16 v[116:119], v[180:183], v[156:159], v[116:119]
	v_mfma_f32_16x16x32_bf16 v[112:115], v[180:183], v[164:167], v[112:115]
	v_mfma_f32_16x16x32_bf16 v[108:111], v[188:191], v[156:159], v[108:111]
	v_mfma_f32_16x16x32_bf16 v[104:107], v[188:191], v[164:167], v[104:107]
	v_mfma_f32_16x16x32_bf16 v[100:103], v[196:199], v[156:159], v[100:103]
	v_mfma_f32_16x16x32_bf16 v[96:99], v[196:199], v[164:167], v[96:99]
	s_setprio 0
	s_barrier
	ds_read_b128 v[200:203], v152
	ds_read_b128 v[204:207], v152 offset:1024
	ds_read_b128 v[208:211], v152 offset:2048
	ds_read_b128 v[212:215], v152 offset:3072
	s_barrier
	s_waitcnt lgkmcnt(0)
	s_setprio 1
	v_mfma_f32_16x16x32_bf16 v[92:95], v[168:171], v[200:203], v[92:95]
	v_mfma_f32_16x16x32_bf16 v[88:91], v[168:171], v[208:211], v[88:91]
	v_mfma_f32_16x16x32_bf16 v[76:79], v[184:187], v[200:203], v[76:79]
	v_mfma_f32_16x16x32_bf16 v[72:75], v[184:187], v[208:211], v[72:75]
	v_mfma_f32_16x16x32_bf16 v[84:87], v[176:179], v[200:203], v[84:87]
	v_mfma_f32_16x16x32_bf16 v[80:83], v[176:179], v[208:211], v[80:83]
	v_mfma_f32_16x16x32_bf16 v[68:71], v[192:195], v[200:203], v[68:71]
	v_mfma_f32_16x16x32_bf16 v[64:67], v[192:195], v[208:211], v[64:67]
	v_mfma_f32_16x16x32_bf16 v[92:95], v[172:175], v[204:207], v[92:95]
	v_mfma_f32_16x16x32_bf16 v[88:91], v[172:175], v[212:215], v[88:91]
	v_mfma_f32_16x16x32_bf16 v[76:79], v[188:191], v[204:207], v[76:79]
	v_mfma_f32_16x16x32_bf16 v[72:75], v[188:191], v[212:215], v[72:75]
	v_mfma_f32_16x16x32_bf16 v[168:171], v[180:183], v[204:207], v[84:87]
	v_mfma_f32_16x16x32_bf16 v[172:175], v[180:183], v[212:215], v[80:83]
	v_mfma_f32_16x16x32_bf16 v[176:179], v[196:199], v[204:207], v[68:71]
	v_mfma_f32_16x16x32_bf16 v[180:183], v[196:199], v[212:215], v[64:67]
	s_setprio 0
	s_barrier
	s_nop 0
	ds_read_b128 v[64:67], v148 offset:16384
	ds_read_b128 v[68:71], v148 offset:17408
	ds_read_b128 v[80:83], v149 offset:16384
	ds_read_b128 v[84:87], v149 offset:17408
	ds_read_b128 v[184:187], v150 offset:16384
	ds_read_b128 v[188:191], v150 offset:17408
	ds_read_b128 v[192:195], v151 offset:16384
	ds_read_b128 v[196:199], v151 offset:17408
	s_waitcnt vmcnt(4)
	s_barrier
; #define LDA(dst, b, h) _Pragma("unroll") for (int m = 0; m < 4; ++m) _Pragma("unroll") for (int k = 0; k < 2; ++k) \
;     dst[m][k] = *reinterpret_cast<const bf16x8*>((char*)SA(b, h) + lds_byte(wr * 64 + m * 16 + fr, k * 32 + fq * 8))
; #define LDB(dst, b, h) _Pragma("unroll") for (int n = 0; n < 2; ++n) _Pragma("unroll") for (int k = 0; k < 2; ++k) \
;     dst[n][k] = *reinterpret_cast<const bf16x8*>((char*)SB(b, h) + lds_byte(wc * 32 + n * 16 + fr, k * 32 + fq * 8))
; #define MMA(ai, bj, At_, Bt_) do { __builtin_amdgcn_s_setprio(1); \
;     _Pragma("unroll") for (int k = 0; k < 2; ++k) _Pragma("unroll") for (int m = 0; m < 4; ++m) _Pragma("unroll") for (int n = 0; n < 2; ++n) \
;       acc[ai][bj][m][n] = __builtin_amdgcn_mfma_f32_16x16x32_bf16(At_[m][k], Bt_[n][k], acc[ai][bj][m][n], 0, 0, 0); \
;     __builtin_amdgcn_s_setprio(0); } while (0)
; #define WAIT_V(n) asm volatile("s_waitcnt vmcnt(" #n ")" ::: "memory")
; #define BAR __builtin_amdgcn_s_barrier()
; template <int EPI, int N, int K>
; __device__ __forceinline__ void gemm_phase(const bf16_t* __restrict__ A, const bf16_t* __restrict__ Bt, const EpiArgs ea) {
;     ...
;       LDA(At, 0, 1); WAIT_V(4); BAR; WAIT_L(0); MMA(1, 0, At, B0); MMA(1, 1, At, B1); BAR; }
;     { LDB(B0, 1, 0); LDA(At, 1, 0); WAIT_V(2); BAR; WAIT_L(0); MMA(0, 0, At, B0); BAR;
;       LDB(B1, 1, 1); WAIT_V(0); BAR; WAIT_L(0); MMA(0, 1, At, B1); BAR;
	s_waitcnt lgkmcnt(0)
	s_setprio 1
	v_mfma_f32_16x16x32_bf16 v[60:63], v[64:67], v[132:135], v[60:63]
	v_mfma_f32_16x16x32_bf16 v[56:59], v[64:67], v[160:163], v[56:59]
	v_mfma_f32_16x16x32_bf16 v[52:55], v[80:83], v[132:135], v[52:55]
	v_mfma_f32_16x16x32_bf16 v[48:51], v[80:83], v[160:163], v[48:51]
	v_mfma_f32_16x16x32_bf16 v[44:47], v[184:187], v[132:135], v[44:47]
	v_mfma_f32_16x16x32_bf16 v[40:43], v[184:187], v[160:163], v[40:43]
	v_mfma_f32_16x16x32_bf16 v[36:39], v[192:195], v[132:135], v[36:39]
	v_mfma_f32_16x16x32_bf16 v[32:35], v[192:195], v[160:163], v[32:35]
	v_mfma_f32_16x16x32_bf16 v[60:63], v[68:71], v[156:159], v[60:63]
	v_mfma_f32_16x16x32_bf16 v[56:59], v[68:71], v[164:167], v[56:59]
	v_mfma_f32_16x16x32_bf16 v[52:55], v[84:87], v[156:159], v[52:55]
	v_mfma_f32_16x16x32_bf16 v[48:51], v[84:87], v[164:167], v[48:51]
	v_mfma_f32_16x16x32_bf16 v[44:47], v[188:191], v[156:159], v[44:47]
	v_mfma_f32_16x16x32_bf16 v[40:43], v[188:191], v[164:167], v[40:43]
	v_mfma_f32_16x16x32_bf16 v[36:39], v[196:199], v[156:159], v[36:39]
	v_mfma_f32_16x16x32_bf16 v[32:35], v[196:199], v[164:167], v[32:35]
	s_setprio 0
	s_setprio 1
	v_mfma_f32_16x16x32_bf16 v[28:31], v[64:67], v[200:203], v[28:31]
	v_mfma_f32_16x16x32_bf16 v[24:27], v[64:67], v[208:211], v[24:27]
	v_mfma_f32_16x16x32_bf16 v[4:7], v[192:195], v[200:203], v[4:7]
	v_mfma_f32_16x16x32_bf16 v[0:3], v[192:195], v[208:211], v[0:3]
	v_mfma_f32_16x16x32_bf16 v[20:23], v[80:83], v[200:203], v[20:23]
	v_mfma_f32_16x16x32_bf16 v[16:19], v[80:83], v[208:211], v[16:19]
	v_mfma_f32_16x16x32_bf16 v[12:15], v[184:187], v[200:203], v[12:15]
	v_mfma_f32_16x16x32_bf16 v[8:11], v[184:187], v[208:211], v[8:11]
	v_mfma_f32_16x16x32_bf16 v[28:31], v[68:71], v[204:207], v[28:31]
	v_mfma_f32_16x16x32_bf16 v[24:27], v[68:71], v[212:215], v[24:27]
	v_mfma_f32_16x16x32_bf16 v[4:7], v[196:199], v[204:207], v[4:7]
	v_mfma_f32_16x16x32_bf16 v[0:3], v[196:199], v[212:215], v[0:3]
	v_mfma_f32_16x16x32_bf16 v[132:135], v[84:87], v[204:207], v[20:23]
	v_mfma_f32_16x16x32_bf16 v[156:159], v[84:87], v[212:215], v[16:19]
	v_mfma_f32_16x16x32_bf16 v[160:163], v[188:191], v[204:207], v[12:15]
	v_mfma_f32_16x16x32_bf16 v[164:167], v[188:191], v[212:215], v[8:11]
	s_setprio 0
	s_barrier
	s_nop 0
	ds_read_b128 v[8:11], v153
	ds_read_b128 v[12:15], v153 offset:1024
	ds_read_b128 v[16:19], v153 offset:2048
	ds_read_b128 v[184:187], v153 offset:3072
	ds_read_b128 v[20:23], v148 offset:32768
	ds_read_b128 v[188:191], v148 offset:33792
	ds_read_b128 v[192:195], v149 offset:32768
	ds_read_b128 v[196:199], v149 offset:33792
	ds_read_b128 v[200:203], v150 offset:32768
	ds_read_b128 v[204:207], v150 offset:33792
	ds_read_b128 v[208:211], v151 offset:32768
	ds_read_b128 v[212:215], v151 offset:33792
	s_waitcnt vmcnt(2)
	s_barrier
	s_waitcnt lgkmcnt(0)
	s_setprio 1
	v_mfma_f32_16x16x32_bf16 v[64:67], v[20:23], v[8:11], v[124:127]
	v_mfma_f32_16x16x32_bf16 v[68:71], v[20:23], v[16:19], v[120:123]
	v_mfma_f32_16x16x32_bf16 v[80:83], v[192:195], v[8:11], v[116:119]
	v_mfma_f32_16x16x32_bf16 v[84:87], v[192:195], v[16:19], v[112:115]
	v_mfma_f32_16x16x32_bf16 v[108:111], v[200:203], v[8:11], v[108:111]
	v_mfma_f32_16x16x32_bf16 v[104:107], v[200:203], v[16:19], v[104:107]
	v_mfma_f32_16x16x32_bf16 v[120:123], v[208:211], v[8:11], v[100:103]
	v_mfma_f32_16x16x32_bf16 v[124:127], v[208:211], v[16:19], v[96:99]
	v_mfma_f32_16x16x32_bf16 v[116:119], v[188:191], v[12:15], v[64:67]
	v_mfma_f32_16x16x32_bf16 v[112:115], v[188:191], v[184:187], v[68:71]
	v_mfma_f32_16x16x32_bf16 v[100:103], v[196:199], v[12:15], v[80:83]
	v_mfma_f32_16x16x32_bf16 v[96:99], v[196:199], v[184:187], v[84:87]
	v_mfma_f32_16x16x32_bf16 v[84:87], v[204:207], v[12:15], v[108:111]
	v_mfma_f32_16x16x32_bf16 v[80:83], v[204:207], v[184:187], v[104:107]
	v_mfma_f32_16x16x32_bf16 v[68:71], v[212:215], v[12:15], v[120:123]
	v_mfma_f32_16x16x32_bf16 v[64:67], v[212:215], v[184:187], v[124:127]
	s_setprio 0
	s_barrier
; #define LDA(dst, b, h) _Pragma("unroll") for (int m = 0; m < 4; ++m) _Pragma("unroll") for (int k = 0; k < 2; ++k) \
;     dst[m][k] = *reinterpret_cast<const bf16x8*>((char*)SA(b, h) + lds_byte(wr * 64 + m * 16 + fr, k * 32 + fq * 8))
; #define LDB(dst, b, h) _Pragma("unroll") for (int n = 0; n < 2; ++n) _Pragma("unroll") for (int k = 0; k < 2; ++k) \
;     dst[n][k] = *reinterpret_cast<const bf16x8*>((char*)SB(b, h) + lds_byte(wc * 32 + n * 16 + fr, k * 32 + fq * 8))
; #define MMA(ai, bj, At_, Bt_) do { __builtin_amdgcn_s_setprio(1); \
;     _Pragma("unroll") for (int k = 0; k < 2; ++k) _Pragma("unroll") for (int m = 0; m < 4; ++m) _Pragma("unroll") for (int n = 0; n < 2; ++n) \
;       acc[ai][bj][m][n] = __builtin_amdgcn_mfma_f32_16x16x32_bf16(At_[m][k], Bt_[n][k], acc[ai][bj][m][n], 0, 0, 0); \
;     __builtin_amdgcn_s_setprio(0); } while (0)
; #define WAIT_V(n) asm volatile("s_waitcnt vmcnt(" #n ")" ::: "memory")
; #define BAR __builtin_amdgcn_s_barrier()
; template <int EPI, int N, int K>
; __device__ __forceinline__ void gemm_phase(const bf16_t* __restrict__ A, const bf16_t* __restrict__ Bt, const EpiArgs ea) {
;     ...
;     { LDB(B0, 1, 0); LDA(At, 1, 0); WAIT_V(2); BAR; WAIT_L(0); MMA(0, 0, At, B0); BAR;
;       LDB(B1, 1, 1); WAIT_V(0); BAR; WAIT_L(0); MMA(0, 1, At, B1); BAR;
;       LDA(At, 1, 1); BAR; WAIT_L(0); MMA(1, 0, At, B0); MMA(1, 1, At, B1); BAR; }
;     if (wr == 0) BAR;
	ds_read_b128 v[216:219], v154
	ds_read_b128 v[220:223], v154 offset:1024
	ds_read_b128 v[224:227], v154 offset:2048
	ds_read_b128 v[228:231], v154 offset:3072
	s_waitcnt vmcnt(0)
	s_barrier
	s_waitcnt lgkmcnt(0)
	s_setprio 1
	v_mfma_f32_16x16x32_bf16 v[92:95], v[20:23], v[216:219], v[92:95]
	v_mfma_f32_16x16x32_bf16 v[20:23], v[20:23], v[224:227], v[88:91]
	v_mfma_f32_16x16x32_bf16 v[88:91], v[192:195], v[216:219], v[168:171]
	v_mfma_f32_16x16x32_bf16 v[104:107], v[192:195], v[224:227], v[172:175]
	v_mfma_f32_16x16x32_bf16 v[76:79], v[200:203], v[216:219], v[76:79]
	v_mfma_f32_16x16x32_bf16 v[72:75], v[200:203], v[224:227], v[72:75]
	v_mfma_f32_16x16x32_bf16 v[168:171], v[208:211], v[216:219], v[176:179]
	v_mfma_f32_16x16x32_bf16 v[172:175], v[208:211], v[224:227], v[180:183]
	v_mfma_f32_16x16x32_bf16 v[124:127], v[188:191], v[220:223], v[92:95]
	v_mfma_f32_16x16x32_bf16 v[120:123], v[188:191], v[228:231], v[20:23]
	v_mfma_f32_16x16x32_bf16 v[108:111], v[196:199], v[220:223], v[88:91]
	v_mfma_f32_16x16x32_bf16 v[104:107], v[196:199], v[228:231], v[104:107]
	v_mfma_f32_16x16x32_bf16 v[92:95], v[204:207], v[220:223], v[76:79]
	v_mfma_f32_16x16x32_bf16 v[88:91], v[204:207], v[228:231], v[72:75]
	v_mfma_f32_16x16x32_bf16 v[76:79], v[212:215], v[220:223], v[168:171]
	v_mfma_f32_16x16x32_bf16 v[72:75], v[212:215], v[228:231], v[172:175]
	s_setprio 0
	s_barrier
	ds_read_b128 v[168:171], v148 offset:49152
	ds_read_b128 v[172:175], v148 offset:50176
	ds_read_b128 v[176:179], v149 offset:49152
	ds_read_b128 v[180:183], v149 offset:50176
	ds_read_b128 v[188:191], v150 offset:49152
	ds_read_b128 v[192:195], v150 offset:50176
	ds_read_b128 v[196:199], v151 offset:49152
	ds_read_b128 v[200:203], v151 offset:50176
	s_barrier
	s_waitcnt lgkmcnt(0)
	s_setprio 1
	v_mfma_f32_16x16x32_bf16 v[20:23], v[168:171], v[8:11], v[60:63]
	v_mfma_f32_16x16x32_bf16 v[56:59], v[168:171], v[16:19], v[56:59]
	v_mfma_f32_16x16x32_bf16 v[60:63], v[176:179], v[8:11], v[52:55]
	v_mfma_f32_16x16x32_bf16 v[204:207], v[176:179], v[16:19], v[48:51]
	v_mfma_f32_16x16x32_bf16 v[44:47], v[188:191], v[8:11], v[44:47]
	v_mfma_f32_16x16x32_bf16 v[40:43], v[188:191], v[16:19], v[40:43]
	v_mfma_f32_16x16x32_bf16 v[8:11], v[196:199], v[8:11], v[36:39]
	v_mfma_f32_16x16x32_bf16 v[208:211], v[196:199], v[16:19], v[32:35]
	v_mfma_f32_16x16x32_bf16 v[52:55], v[172:175], v[12:15], v[20:23]
	v_mfma_f32_16x16x32_bf16 v[48:51], v[172:175], v[184:187], v[56:59]
	v_mfma_f32_16x16x32_bf16 v[36:39], v[180:183], v[12:15], v[60:63]
	v_mfma_f32_16x16x32_bf16 v[32:35], v[180:183], v[184:187], v[204:207]
	v_mfma_f32_16x16x32_bf16 v[20:23], v[192:195], v[12:15], v[44:47]
	v_mfma_f32_16x16x32_bf16 v[16:19], v[192:195], v[184:187], v[40:43]
	v_mfma_f32_16x16x32_bf16 v[8:11], v[200:203], v[12:15], v[8:11]
	v_mfma_f32_16x16x32_bf16 v[12:15], v[200:203], v[184:187], v[208:211]
	s_setprio 0
	s_setprio 1
	v_mfma_f32_16x16x32_bf16 v[28:31], v[168:171], v[216:219], v[28:31]
	v_mfma_f32_16x16x32_bf16 v[24:27], v[168:171], v[224:227], v[24:27]
	v_mfma_f32_16x16x32_bf16 v[40:43], v[176:179], v[216:219], v[132:135]
	v_mfma_f32_16x16x32_bf16 v[132:135], v[176:179], v[224:227], v[156:159]
	v_mfma_f32_16x16x32_bf16 v[156:159], v[188:191], v[216:219], v[160:163]
	v_mfma_f32_16x16x32_bf16 v[160:163], v[188:191], v[224:227], v[164:167]
	v_mfma_f32_16x16x32_bf16 v[4:7], v[196:199], v[216:219], v[4:7]
	v_mfma_f32_16x16x32_bf16 v[0:3], v[196:199], v[224:227], v[0:3]
	v_mfma_f32_16x16x32_bf16 v[60:63], v[172:175], v[220:223], v[28:31]
	v_mfma_f32_16x16x32_bf16 v[56:59], v[172:175], v[228:231], v[24:27]
	v_mfma_f32_16x16x32_bf16 v[44:47], v[180:183], v[220:223], v[40:43]
	v_mfma_f32_16x16x32_bf16 v[40:43], v[180:183], v[228:231], v[132:135]
	v_mfma_f32_16x16x32_bf16 v[28:31], v[192:195], v[220:223], v[156:159]
	v_mfma_f32_16x16x32_bf16 v[24:27], v[192:195], v[228:231], v[160:163]
	v_mfma_f32_16x16x32_bf16 v[4:7], v[200:203], v[220:223], v[4:7]
	v_mfma_f32_16x16x32_bf16 v[0:3], v[200:203], v[228:231], v[0:3]
	s_setprio 0
	s_barrier
	s_and_saveexec_b64 s[2:3], s[8:9]
	s_cbranch_execz .LBB0_393
	s_barrier

; #define STAGE_A(POFF, h, kt) STAGE_AX(POFF, h, kt, brow)
; #define STAGE_B(POFF, h, kt) STAGE_BX(POFF, h, kt, bcol)
; #define LDA(dst, b, h) _Pragma("unroll") for (int m = 0; m < 4; ++m) _Pragma("unroll") for (int k = 0; k < 2; ++k) \
;     dst[m][k] = *reinterpret_cast<const bf16x8*>((char*)SA(b, h) + lds_byte(wr * 64 + m * 16 + fr, k * 32 + fq * 8))
; #define LDB(dst, b, h) _Pragma("unroll") for (int n = 0; n < 2; ++n) _Pragma("unroll") for (int k = 0; k < 2; ++k) \
;     dst[n][k] = *reinterpret_cast<const bf16x8*>((char*)SB(b, h) + lds_byte(wc * 32 + n * 16 + fr, k * 32 + fq * 8))
; #define MMA(ai, bj, At_, Bt_) do { __builtin_amdgcn_s_setprio(1); \
;     _Pragma("unroll") for (int k = 0; k < 2; ++k) _Pragma("unroll") for (int m = 0; m < 4; ++m) _Pragma("unroll") for (int n = 0; n < 2; ++n) \
;       acc[ai][bj][m][n] = __builtin_amdgcn_mfma_f32_16x16x32_bf16(At_[m][k], Bt_[n][k], acc[ai][bj][m][n], 0, 0, 0); \
;     __builtin_amdgcn_s_setprio(0); } while (0)
; #define WAIT_V(n) asm volatile("s_waitcnt vmcnt(" #n ")" ::: "memory")
; #define BAR __builtin_amdgcn_s_barrier()
; #define SCHED __builtin_amdgcn_sched_barrier(0)
; template <int EPI, int N, int K>
; __device__ __forceinline__ void gemm_phase(const bf16_t* __restrict__ A, const bf16_t* __restrict__ Bt, const EpiArgs ea) {
;     ...
;     for (int t = 0; t < nt - 2; t += 2) {
;       LDB(B0, 0, 0); SCHED; LDA(At, 0, 0); STAGE_A(SA_OFF(1, 1), 1, t + 1);
;       WAIT_L(8); BAR; WAIT_L(0); MMA(0, 0, At, B0); BAR; SCHED;
;       LDB(B1, 0, 1); STAGE_B(SB_OFF(0, 0), 0, t + 2);
;       BAR; WAIT_L(0); MMA(0, 1, At, B1); BAR;
;       LDA(At, 0, 1); STAGE_A(SA_OFF(0, 0), 0, t + 2);
;       BAR; WAIT_L(0); MMA(1, 0, At, B0); BAR; SCHED;
;       STAGE_B(SB_OFF(0, 1), 1, t + 2);
;       WAIT_V(6); BAR; MMA(1, 1, At, B1); BAR;
.LBB0_509:
	ds_read_b128 v[218:221], v149 offset:16384
	ds_read_b128 v[222:225], v149 offset:17408
	ds_read_b128 v[226:229], v150 offset:16384
	ds_read_b128 v[230:233], v150 offset:17408
	ds_read_b128 v[238:241], v151 offset:16384
	ds_read_b128 v[242:245], v151 offset:17408
	s_add_i32 s37, s34, s36
	s_or_b32 s38, s37, 0x80080
	s_mov_b32 m0, s29
	s_nop 0
	buffer_load_dwordx4 v136, s[48:51], s38 offen lds
	s_or_b32 s38, s37, 0xc0080
	s_mov_b32 m0, s30
	s_nop 0
	buffer_load_dwordx4 v136, s[48:51], s38 offen lds
	s_setprio 1
	s_barrier
	s_waitcnt lgkmcnt(6)
	v_mfma_f32_16x16x32_bf16 v[124:127], v[168:171], v[132:135], v[124:127]
	v_mfma_f32_16x16x32_bf16 v[120:123], v[168:171], v[160:163], v[120:123]
	v_mfma_f32_16x16x32_bf16 v[116:119], v[176:179], v[132:135], v[116:119]
	v_mfma_f32_16x16x32_bf16 v[112:115], v[176:179], v[160:163], v[112:115]
	v_mfma_f32_16x16x32_bf16 v[108:111], v[184:187], v[132:135], v[108:111]
	v_mfma_f32_16x16x32_bf16 v[104:107], v[184:187], v[160:163], v[104:107]
	v_mfma_f32_16x16x32_bf16 v[100:103], v[192:195], v[132:135], v[100:103]
	v_mfma_f32_16x16x32_bf16 v[96:99], v[192:195], v[160:163], v[96:99]
	v_mfma_f32_16x16x32_bf16 v[124:127], v[172:175], v[156:159], v[124:127]
	v_mfma_f32_16x16x32_bf16 v[120:123], v[172:175], v[164:167], v[120:123]
	v_mfma_f32_16x16x32_bf16 v[116:119], v[180:183], v[156:159], v[116:119]
	v_mfma_f32_16x16x32_bf16 v[112:115], v[180:183], v[164:167], v[112:115]
	v_mfma_f32_16x16x32_bf16 v[108:111], v[188:191], v[156:159], v[108:111]
	v_mfma_f32_16x16x32_bf16 v[104:107], v[188:191], v[164:167], v[104:107]
	v_mfma_f32_16x16x32_bf16 v[100:103], v[196:199], v[156:159], v[100:103]
	v_mfma_f32_16x16x32_bf16 v[96:99], v[196:199], v[164:167], v[96:99]
	s_barrier
	s_setprio 0
	ds_read_b128 v[200:203], v153
	ds_read_b128 v[204:207], v153 offset:1024
	ds_read_b128 v[208:211], v153 offset:2048
	ds_read_b128 v[212:215], v153 offset:3072
	ds_read_b128 v[246:249], v152 offset:16384
	ds_read_b128 v[250:253], v152 offset:17408
	s_add_i32 s38, s13, s36
	s_add_i32 s39, s38, 0x100
	s_mov_b32 m0, s15
	s_nop 0
	buffer_load_dwordx4 v137, s[80:83], s39 offen lds
	s_add_i32 s39, s38, 0x80100
	s_mov_b32 m0, s16
	s_nop 0
	buffer_load_dwordx4 v137, s[80:83], s39 offen lds
	s_waitcnt vmcnt(6)
	s_setprio 1
	s_barrier
	s_waitcnt lgkmcnt(2)
	v_mfma_f32_16x16x32_bf16 v[92:95], v[168:171], v[200:203], v[92:95]
	v_mfma_f32_16x16x32_bf16 v[88:91], v[168:171], v[208:211], v[88:91]
	v_mfma_f32_16x16x32_bf16 v[84:87], v[176:179], v[200:203], v[84:87]
	v_mfma_f32_16x16x32_bf16 v[80:83], v[176:179], v[208:211], v[80:83]
	v_mfma_f32_16x16x32_bf16 v[76:79], v[184:187], v[200:203], v[76:79]
	v_mfma_f32_16x16x32_bf16 v[72:75], v[184:187], v[208:211], v[72:75]
	v_mfma_f32_16x16x32_bf16 v[68:71], v[192:195], v[200:203], v[68:71]
	v_mfma_f32_16x16x32_bf16 v[64:67], v[192:195], v[208:211], v[64:67]
	v_mfma_f32_16x16x32_bf16 v[92:95], v[172:175], v[204:207], v[92:95]
	v_mfma_f32_16x16x32_bf16 v[88:91], v[172:175], v[212:215], v[88:91]
	v_mfma_f32_16x16x32_bf16 v[84:87], v[180:183], v[204:207], v[84:87]
	v_mfma_f32_16x16x32_bf16 v[80:83], v[180:183], v[212:215], v[80:83]
	v_mfma_f32_16x16x32_bf16 v[76:79], v[188:191], v[204:207], v[76:79]
	v_mfma_f32_16x16x32_bf16 v[72:75], v[188:191], v[212:215], v[72:75]
	v_mfma_f32_16x16x32_bf16 v[68:71], v[196:199], v[204:207], v[68:71]
	v_mfma_f32_16x16x32_bf16 v[64:67], v[196:199], v[212:215], v[64:67]
	s_barrier
	s_setprio 0
	ds_read_b128 v[168:171], v149 offset:32768
	ds_read_b128 v[172:175], v149 offset:33792
	ds_read_b128 v[176:179], v150 offset:32768
	ds_read_b128 v[180:183], v150 offset:33792
	ds_read_b128 v[184:187], v151 offset:32768
	ds_read_b128 v[188:191], v151 offset:33792
	s_add_i32 s39, s37, 0x100
	s_mov_b32 m0, s14
	s_nop 0
	buffer_load_dwordx4 v136, s[48:51], s39 offen lds
	s_add_i32 s40, s37, 0x40100
	s_mov_b32 m0, s17
	s_nop 0
	buffer_load_dwordx4 v136, s[48:51], s40 offen lds
	s_waitcnt vmcnt(10)
	s_setprio 1
	s_barrier
	s_waitcnt lgkmcnt(6)
	v_mfma_f32_16x16x32_bf16 v[60:63], v[218:221], v[132:135], v[60:63]
	v_mfma_f32_16x16x32_bf16 v[56:59], v[218:221], v[160:163], v[56:59]
	v_mfma_f32_16x16x32_bf16 v[52:55], v[226:229], v[132:135], v[52:55]
	v_mfma_f32_16x16x32_bf16 v[48:51], v[226:229], v[160:163], v[48:51]
	v_mfma_f32_16x16x32_bf16 v[44:47], v[238:241], v[132:135], v[44:47]
	v_mfma_f32_16x16x32_bf16 v[40:43], v[238:241], v[160:163], v[40:43]
	v_mfma_f32_16x16x32_bf16 v[36:39], v[246:249], v[132:135], v[36:39]
	v_mfma_f32_16x16x32_bf16 v[32:35], v[246:249], v[160:163], v[32:35]
	v_mfma_f32_16x16x32_bf16 v[60:63], v[222:225], v[156:159], v[60:63]
	v_mfma_f32_16x16x32_bf16 v[56:59], v[222:225], v[164:167], v[56:59]
	v_mfma_f32_16x16x32_bf16 v[52:55], v[230:233], v[156:159], v[52:55]
	v_mfma_f32_16x16x32_bf16 v[48:51], v[230:233], v[164:167], v[48:51]
	v_mfma_f32_16x16x32_bf16 v[44:47], v[242:245], v[156:159], v[44:47]
	v_mfma_f32_16x16x32_bf16 v[40:43], v[242:245], v[164:167], v[40:43]
	v_mfma_f32_16x16x32_bf16 v[36:39], v[250:253], v[156:159], v[36:39]
	v_mfma_f32_16x16x32_bf16 v[32:35], v[250:253], v[164:167], v[32:35]
	s_barrier
	s_setprio 0
	ds_read_b128 v[132:135], v154
	ds_read_b128 v[156:159], v154 offset:1024
	ds_read_b128 v[160:163], v154 offset:2048
	ds_read_b128 v[164:167], v154 offset:3072
	ds_read_b128 v[192:195], v152 offset:32768
	ds_read_b128 v[196:199], v152 offset:33792
	s_add_i32 s40, s38, 0x2100
	s_mov_b32 m0, s18
	s_nop 0
	buffer_load_dwordx4 v137, s[80:83], s40 offen lds
	s_add_i32 s40, s38, 0x82100
	s_mov_b32 m0, s19
	s_nop 0
	buffer_load_dwordx4 v137, s[80:83], s40 offen lds
	s_waitcnt vmcnt(6)
	s_setprio 1
	s_barrier
; #define STAGE_A(POFF, h, kt) STAGE_AX(POFF, h, kt, brow)
; #define STAGE_B(POFF, h, kt) STAGE_BX(POFF, h, kt, bcol)
; #define LDA(dst, b, h) _Pragma("unroll") for (int m = 0; m < 4; ++m) _Pragma("unroll") for (int k = 0; k < 2; ++k) \
;     dst[m][k] = *reinterpret_cast<const bf16x8*>((char*)SA(b, h) + lds_byte(wr * 64 + m * 16 + fr, k * 32 + fq * 8))
; #define LDB(dst, b, h) _Pragma("unroll") for (int n = 0; n < 2; ++n) _Pragma("unroll") for (int k = 0; k < 2; ++k) \
;     dst[n][k] = *reinterpret_cast<const bf16x8*>((char*)SB(b, h) + lds_byte(wc * 32 + n * 16 + fr, k * 32 + fq * 8))
; #define MMA(ai, bj, At_, Bt_) do { __builtin_amdgcn_s_setprio(1); \
;     _Pragma("unroll") for (int k = 0; k < 2; ++k) _Pragma("unroll") for (int m = 0; m < 4; ++m) _Pragma("unroll") for (int n = 0; n < 2; ++n) \
;       acc[ai][bj][m][n] = __builtin_amdgcn_mfma_f32_16x16x32_bf16(At_[m][k], Bt_[n][k], acc[ai][bj][m][n], 0, 0, 0); \
;     __builtin_amdgcn_s_setprio(0); } while (0)
; #define WAIT_V(n) asm volatile("s_waitcnt vmcnt(" #n ")" ::: "memory")
; #define BAR __builtin_amdgcn_s_barrier()
; #define SCHED __builtin_amdgcn_sched_barrier(0)
; template <int EPI, int N, int K>
; __device__ __forceinline__ void gemm_phase(const bf16_t* __restrict__ A, const bf16_t* __restrict__ Bt, const EpiArgs ea) {
;     ...
;       WAIT_V(6); BAR; MMA(1, 1, At, B1); BAR;
;       LDB(B0, 1, 0); SCHED; LDA(At, 1, 0); STAGE_A(SA_OFF(0, 1), 1, t + 2);
;       WAIT_L(8); BAR; WAIT_L(0); MMA(0, 0, At, B0); BAR; SCHED;
;       LDB(B1, 1, 1); STAGE_B(SB_OFF(1, 0), 0, t + 3);
;       BAR; WAIT_L(0); MMA(0, 1, At, B1); BAR;
;       LDA(At, 1, 1); STAGE_A(SA_OFF(1, 0), 0, t + 3);
;       BAR; WAIT_L(0); MMA(1, 0, At, B0); BAR; SCHED;
;       STAGE_B(SB_OFF(1, 1), 1, t + 3);
;       WAIT_V(6); BAR; MMA(1, 1, At, B1); BAR;
	v_mfma_f32_16x16x32_bf16 v[28:31], v[218:221], v[200:203], v[28:31]
	v_mfma_f32_16x16x32_bf16 v[24:27], v[218:221], v[208:211], v[24:27]
	v_mfma_f32_16x16x32_bf16 v[20:23], v[226:229], v[200:203], v[20:23]
	v_mfma_f32_16x16x32_bf16 v[16:19], v[226:229], v[208:211], v[16:19]
	v_mfma_f32_16x16x32_bf16 v[12:15], v[238:241], v[200:203], v[12:15]
	v_mfma_f32_16x16x32_bf16 v[8:11], v[238:241], v[208:211], v[8:11]
	v_mfma_f32_16x16x32_bf16 v[4:7], v[246:249], v[200:203], v[4:7]
	v_mfma_f32_16x16x32_bf16 v[0:3], v[246:249], v[208:211], v[0:3]
	v_mfma_f32_16x16x32_bf16 v[28:31], v[222:225], v[204:207], v[28:31]
	v_mfma_f32_16x16x32_bf16 v[24:27], v[222:225], v[212:215], v[24:27]
	v_mfma_f32_16x16x32_bf16 v[20:23], v[230:233], v[204:207], v[20:23]
	v_mfma_f32_16x16x32_bf16 v[16:19], v[230:233], v[212:215], v[16:19]
	v_mfma_f32_16x16x32_bf16 v[12:15], v[242:245], v[204:207], v[12:15]
	v_mfma_f32_16x16x32_bf16 v[8:11], v[242:245], v[212:215], v[8:11]
	v_mfma_f32_16x16x32_bf16 v[4:7], v[250:253], v[204:207], v[4:7]
	v_mfma_f32_16x16x32_bf16 v[0:3], v[250:253], v[212:215], v[0:3]
	s_barrier
	s_setprio 0
	ds_read_b128 v[218:221], v149 offset:49152
	ds_read_b128 v[222:225], v149 offset:50176
	ds_read_b128 v[226:229], v150 offset:49152
	ds_read_b128 v[230:233], v150 offset:50176
	ds_read_b128 v[238:241], v151 offset:49152
	ds_read_b128 v[242:245], v151 offset:50176
	s_or_b32 s40, s39, 0x80000
	s_mov_b32 m0, s21
	s_nop 0
	buffer_load_dwordx4 v136, s[48:51], s40 offen lds
	s_or_b32 s39, s39, 0xc0000
	s_mov_b32 m0, s22
	s_nop 0
	buffer_load_dwordx4 v136, s[48:51], s39 offen lds
	s_setprio 1
	s_barrier
	s_waitcnt lgkmcnt(6)
	v_mfma_f32_16x16x32_bf16 v[124:127], v[168:171], v[132:135], v[124:127]
	v_mfma_f32_16x16x32_bf16 v[120:123], v[168:171], v[160:163], v[120:123]
	v_mfma_f32_16x16x32_bf16 v[116:119], v[176:179], v[132:135], v[116:119]
	v_mfma_f32_16x16x32_bf16 v[112:115], v[176:179], v[160:163], v[112:115]
	v_mfma_f32_16x16x32_bf16 v[108:111], v[184:187], v[132:135], v[108:111]
	v_mfma_f32_16x16x32_bf16 v[104:107], v[184:187], v[160:163], v[104:107]
	v_mfma_f32_16x16x32_bf16 v[100:103], v[192:195], v[132:135], v[100:103]
	v_mfma_f32_16x16x32_bf16 v[96:99], v[192:195], v[160:163], v[96:99]
	v_mfma_f32_16x16x32_bf16 v[124:127], v[172:175], v[156:159], v[124:127]
	v_mfma_f32_16x16x32_bf16 v[120:123], v[172:175], v[164:167], v[120:123]
	v_mfma_f32_16x16x32_bf16 v[116:119], v[180:183], v[156:159], v[116:119]
	v_mfma_f32_16x16x32_bf16 v[112:115], v[180:183], v[164:167], v[112:115]
	v_mfma_f32_16x16x32_bf16 v[108:111], v[188:191], v[156:159], v[108:111]
	v_mfma_f32_16x16x32_bf16 v[104:107], v[188:191], v[164:167], v[104:107]
	v_mfma_f32_16x16x32_bf16 v[100:103], v[196:199], v[156:159], v[100:103]
	v_mfma_f32_16x16x32_bf16 v[96:99], v[196:199], v[164:167], v[96:99]
	s_barrier
	s_setprio 0
	ds_read_b128 v[200:203], v155
	ds_read_b128 v[204:207], v155 offset:1024
	ds_read_b128 v[208:211], v155 offset:2048
	ds_read_b128 v[212:215], v155 offset:3072
	ds_read_b128 v[246:249], v152 offset:49152
	ds_read_b128 v[250:253], v152 offset:50176
	s_add_i32 s39, s38, 0x180
	s_mov_b32 m0, s23
	s_nop 0
	buffer_load_dwordx4 v137, s[80:83], s39 offen lds
	s_add_i32 s39, s38, 0x80180
	s_mov_b32 m0, s24
	s_nop 0
	buffer_load_dwordx4 v137, s[80:83], s39 offen lds
	s_waitcnt vmcnt(6)
	s_setprio 1
	s_barrier
	s_waitcnt lgkmcnt(2)
	v_mfma_f32_16x16x32_bf16 v[92:95], v[168:171], v[200:203], v[92:95]
	v_mfma_f32_16x16x32_bf16 v[88:91], v[168:171], v[208:211], v[88:91]
	v_mfma_f32_16x16x32_bf16 v[84:87], v[176:179], v[200:203], v[84:87]
	v_mfma_f32_16x16x32_bf16 v[80:83], v[176:179], v[208:211], v[80:83]
	v_mfma_f32_16x16x32_bf16 v[76:79], v[184:187], v[200:203], v[76:79]
	v_mfma_f32_16x16x32_bf16 v[72:75], v[184:187], v[208:211], v[72:75]
	v_mfma_f32_16x16x32_bf16 v[68:71], v[192:195], v[200:203], v[68:71]
	v_mfma_f32_16x16x32_bf16 v[64:67], v[192:195], v[208:211], v[64:67]
	v_mfma_f32_16x16x32_bf16 v[92:95], v[172:175], v[204:207], v[92:95]
	v_mfma_f32_16x16x32_bf16 v[88:91], v[172:175], v[212:215], v[88:91]
	v_mfma_f32_16x16x32_bf16 v[84:87], v[180:183], v[204:207], v[84:87]
	v_mfma_f32_16x16x32_bf16 v[80:83], v[180:183], v[212:215], v[80:83]
	v_mfma_f32_16x16x32_bf16 v[76:79], v[188:191], v[204:207], v[76:79]
	v_mfma_f32_16x16x32_bf16 v[72:75], v[188:191], v[212:215], v[72:75]
	v_mfma_f32_16x16x32_bf16 v[68:71], v[196:199], v[204:207], v[68:71]
	v_mfma_f32_16x16x32_bf16 v[64:67], v[196:199], v[212:215], v[64:67]
	s_barrier
	s_setprio 0
	ds_read_b128 v[168:171], v149
	ds_read_b128 v[172:175], v149 offset:1024
	ds_read_b128 v[176:179], v150
	ds_read_b128 v[180:183], v150 offset:1024
	ds_read_b128 v[184:187], v151
	ds_read_b128 v[188:191], v151 offset:1024
	s_add_i32 s39, s37, 0x180
	s_mov_b32 m0, s25
	s_nop 0
	buffer_load_dwordx4 v136, s[48:51], s39 offen lds
	s_add_i32 s37, s37, 0x40180
	s_mov_b32 m0, s26
	s_nop 0
	buffer_load_dwordx4 v136, s[48:51], s37 offen lds
	s_waitcnt vmcnt(10)
	s_setprio 1
	s_barrier
	s_waitcnt lgkmcnt(6)
	v_mfma_f32_16x16x32_bf16 v[60:63], v[218:221], v[132:135], v[60:63]
	v_mfma_f32_16x16x32_bf16 v[56:59], v[218:221], v[160:163], v[56:59]
	v_mfma_f32_16x16x32_bf16 v[52:55], v[226:229], v[132:135], v[52:55]
	v_mfma_f32_16x16x32_bf16 v[48:51], v[226:229], v[160:163], v[48:51]
	v_mfma_f32_16x16x32_bf16 v[44:47], v[238:241], v[132:135], v[44:47]
	v_mfma_f32_16x16x32_bf16 v[40:43], v[238:241], v[160:163], v[40:43]
	v_mfma_f32_16x16x32_bf16 v[36:39], v[246:249], v[132:135], v[36:39]
	v_mfma_f32_16x16x32_bf16 v[32:35], v[246:249], v[160:163], v[32:35]
	v_mfma_f32_16x16x32_bf16 v[60:63], v[222:225], v[156:159], v[60:63]
	v_mfma_f32_16x16x32_bf16 v[56:59], v[222:225], v[164:167], v[56:59]
	v_mfma_f32_16x16x32_bf16 v[52:55], v[230:233], v[156:159], v[52:55]
	v_mfma_f32_16x16x32_bf16 v[48:51], v[230:233], v[164:167], v[48:51]
	v_mfma_f32_16x16x32_bf16 v[44:47], v[242:245], v[156:159], v[44:47]
	v_mfma_f32_16x16x32_bf16 v[40:43], v[242:245], v[164:167], v[40:43]
	v_mfma_f32_16x16x32_bf16 v[36:39], v[250:253], v[156:159], v[36:39]
	v_mfma_f32_16x16x32_bf16 v[32:35], v[250:253], v[164:167], v[32:35]
	s_barrier
; #define STAGE_A(POFF, h, kt) STAGE_AX(POFF, h, kt, brow)
; #define LDA(dst, b, h) _Pragma("unroll") for (int m = 0; m < 4; ++m) _Pragma("unroll") for (int k = 0; k < 2; ++k) \
;     dst[m][k] = *reinterpret_cast<const bf16x8*>((char*)SA(b, h) + lds_byte(wr * 64 + m * 16 + fr, k * 32 + fq * 8))
; #define LDB(dst, b, h) _Pragma("unroll") for (int n = 0; n < 2; ++n) _Pragma("unroll") for (int k = 0; k < 2; ++k) \
;     dst[n][k] = *reinterpret_cast<const bf16x8*>((char*)SB(b, h) + lds_byte(wc * 32 + n * 16 + fr, k * 32 + fq * 8))
; #define MMA(ai, bj, At_, Bt_) do { __builtin_amdgcn_s_setprio(1); \
;     _Pragma("unroll") for (int k = 0; k < 2; ++k) _Pragma("unroll") for (int m = 0; m < 4; ++m) _Pragma("unroll") for (int n = 0; n < 2; ++n) \
;       acc[ai][bj][m][n] = __builtin_amdgcn_mfma_f32_16x16x32_bf16(At_[m][k], Bt_[n][k], acc[ai][bj][m][n], 0, 0, 0); \
;     __builtin_amdgcn_s_setprio(0); } while (0)
; #define WAIT_V(n) asm volatile("s_waitcnt vmcnt(" #n ")" ::: "memory")
; #define BAR __builtin_amdgcn_s_barrier()
; template <int EPI, int N, int K>
; __device__ __forceinline__ void gemm_phase(const bf16_t* __restrict__ A, const bf16_t* __restrict__ Bt, const EpiArgs ea) {
;     ...
;       WAIT_V(6); BAR; MMA(1, 1, At, B1); BAR;
;     }
;     { LDB(B0, 0, 0); LDA(At, 0, 0); STAGE_A(SA_OFF(1, 1), 1, nt - 1);
;       BAR; WAIT_L(0); MMA(0, 0, At, B0); BAR;
;       LDB(B1, 0, 1); BAR; WAIT_L(0); MMA(0, 1, At, B1); BAR;
;       LDA(At, 0, 1); WAIT_V(4); BAR; WAIT_L(0); MMA(1, 0, At, B0); MMA(1, 1, At, B1); BAR; }
;     { LDB(B0, 1, 0); LDA(At, 1, 0); WAIT_V(2); BAR; WAIT_L(0); MMA(0, 0, At, B0); BAR;
	s_setprio 0
	ds_read_b128 v[132:135], v148
	ds_read_b128 v[156:159], v148 offset:1024
	ds_read_b128 v[160:163], v148 offset:2048
	ds_read_b128 v[164:167], v148 offset:3072
	ds_read_b128 v[192:195], v152
	ds_read_b128 v[196:199], v152 offset:1024
	s_add_i32 s37, s38, 0x2180
	s_mov_b32 m0, s27
	s_nop 0
	buffer_load_dwordx4 v137, s[80:83], s37 offen lds
	s_add_i32 s38, s38, 0x82180
	s_mov_b32 m0, s28
	s_nop 0
	buffer_load_dwordx4 v137, s[80:83], s38 offen lds
	s_waitcnt vmcnt(6)
	s_setprio 1
	s_barrier
	v_mfma_f32_16x16x32_bf16 v[28:31], v[218:221], v[200:203], v[28:31]
	v_mfma_f32_16x16x32_bf16 v[24:27], v[218:221], v[208:211], v[24:27]
	v_mfma_f32_16x16x32_bf16 v[20:23], v[226:229], v[200:203], v[20:23]
	v_mfma_f32_16x16x32_bf16 v[16:19], v[226:229], v[208:211], v[16:19]
	v_mfma_f32_16x16x32_bf16 v[12:15], v[238:241], v[200:203], v[12:15]
	v_mfma_f32_16x16x32_bf16 v[8:11], v[238:241], v[208:211], v[8:11]
	v_mfma_f32_16x16x32_bf16 v[4:7], v[246:249], v[200:203], v[4:7]
	v_mfma_f32_16x16x32_bf16 v[0:3], v[246:249], v[208:211], v[0:3]
	v_mfma_f32_16x16x32_bf16 v[28:31], v[222:225], v[204:207], v[28:31]
	v_mfma_f32_16x16x32_bf16 v[24:27], v[222:225], v[212:215], v[24:27]
	v_mfma_f32_16x16x32_bf16 v[20:23], v[230:233], v[204:207], v[20:23]
	v_mfma_f32_16x16x32_bf16 v[16:19], v[230:233], v[212:215], v[16:19]
	v_mfma_f32_16x16x32_bf16 v[12:15], v[242:245], v[204:207], v[12:15]
	v_mfma_f32_16x16x32_bf16 v[8:11], v[242:245], v[212:215], v[8:11]
	v_mfma_f32_16x16x32_bf16 v[4:7], v[250:253], v[204:207], v[4:7]
	v_mfma_f32_16x16x32_bf16 v[0:3], v[250:253], v[212:215], v[0:3]
	s_barrier
	s_setprio 0
	s_add_i32 s35, s35, 2
	s_addk_i32 s36, 0x100
	s_cmp_lt_u32 s35, 28
	s_cbranch_scc1 .LBB0_509
	s_and_b32 s3, s3, 0x700
	s_lshl_b32 s2, s2, 11
	s_or_b32 s34, s3, s2
	s_lshl_b32 s2, s34, 12
	s_or_b32 s3, s2, 0x80f80
	s_mov_b32 m0, s29
	s_nop 0
	buffer_load_dwordx4 v136, s[48:51], s3 offen lds
	s_or_b32 s2, s2, 0xc0f80
	s_mov_b32 m0, s30
	s_nop 0
	buffer_load_dwordx4 v136, s[48:51], s2 offen lds
	s_barrier
	s_waitcnt lgkmcnt(0)
	s_setprio 1
	v_mfma_f32_16x16x32_bf16 v[124:127], v[168:171], v[132:135], v[124:127]
	v_mfma_f32_16x16x32_bf16 v[120:123], v[168:171], v[160:163], v[120:123]
	v_mfma_f32_16x16x32_bf16 v[116:119], v[176:179], v[132:135], v[116:119]
	v_mfma_f32_16x16x32_bf16 v[112:115], v[176:179], v[160:163], v[112:115]
	v_mfma_f32_16x16x32_bf16 v[108:111], v[184:187], v[132:135], v[108:111]
	v_mfma_f32_16x16x32_bf16 v[104:107], v[184:187], v[160:163], v[104:107]
	v_mfma_f32_16x16x32_bf16 v[100:103], v[192:195], v[132:135], v[100:103]
	v_mfma_f32_16x16x32_bf16 v[96:99], v[192:195], v[160:163], v[96:99]
	v_mfma_f32_16x16x32_bf16 v[124:127], v[172:175], v[156:159], v[124:127]
	v_mfma_f32_16x16x32_bf16 v[120:123], v[172:175], v[164:167], v[120:123]
	v_mfma_f32_16x16x32_bf16 v[116:119], v[180:183], v[156:159], v[116:119]
	v_mfma_f32_16x16x32_bf16 v[112:115], v[180:183], v[164:167], v[112:115]
	v_mfma_f32_16x16x32_bf16 v[108:111], v[188:191], v[156:159], v[108:111]
	v_mfma_f32_16x16x32_bf16 v[104:107], v[188:191], v[164:167], v[104:107]
	v_mfma_f32_16x16x32_bf16 v[100:103], v[196:199], v[156:159], v[100:103]
	v_mfma_f32_16x16x32_bf16 v[96:99], v[196:199], v[164:167], v[96:99]
	s_setprio 0
	s_barrier
	ds_read_b128 v[200:203], v153
	ds_read_b128 v[204:207], v153 offset:1024
	ds_read_b128 v[208:211], v153 offset:2048
	ds_read_b128 v[212:215], v153 offset:3072
	s_barrier
	s_waitcnt lgkmcnt(0)
	s_setprio 1
	v_mfma_f32_16x16x32_bf16 v[92:95], v[168:171], v[200:203], v[92:95]
	v_mfma_f32_16x16x32_bf16 v[88:91], v[168:171], v[208:211], v[88:91]
	v_mfma_f32_16x16x32_bf16 v[76:79], v[184:187], v[200:203], v[76:79]
	v_mfma_f32_16x16x32_bf16 v[72:75], v[184:187], v[208:211], v[72:75]
	v_mfma_f32_16x16x32_bf16 v[84:87], v[176:179], v[200:203], v[84:87]
	v_mfma_f32_16x16x32_bf16 v[80:83], v[176:179], v[208:211], v[80:83]
	v_mfma_f32_16x16x32_bf16 v[68:71], v[192:195], v[200:203], v[68:71]
	v_mfma_f32_16x16x32_bf16 v[64:67], v[192:195], v[208:211], v[64:67]
	v_mfma_f32_16x16x32_bf16 v[92:95], v[172:175], v[204:207], v[92:95]
	v_mfma_f32_16x16x32_bf16 v[88:91], v[172:175], v[212:215], v[88:91]
	v_mfma_f32_16x16x32_bf16 v[76:79], v[188:191], v[204:207], v[76:79]
	v_mfma_f32_16x16x32_bf16 v[72:75], v[188:191], v[212:215], v[72:75]
	v_mfma_f32_16x16x32_bf16 v[168:171], v[180:183], v[204:207], v[84:87]
	v_mfma_f32_16x16x32_bf16 v[172:175], v[180:183], v[212:215], v[80:83]
	v_mfma_f32_16x16x32_bf16 v[176:179], v[196:199], v[204:207], v[68:71]
	v_mfma_f32_16x16x32_bf16 v[180:183], v[196:199], v[212:215], v[64:67]
	s_setprio 0
	s_barrier
	s_nop 0
	ds_read_b128 v[64:67], v149 offset:16384
	ds_read_b128 v[68:71], v149 offset:17408
	ds_read_b128 v[80:83], v150 offset:16384
	ds_read_b128 v[84:87], v150 offset:17408
	ds_read_b128 v[184:187], v151 offset:16384
	ds_read_b128 v[188:191], v151 offset:17408
	ds_read_b128 v[192:195], v152 offset:16384
	ds_read_b128 v[196:199], v152 offset:17408
	s_waitcnt vmcnt(4)
	s_barrier
; #define LDA(dst, b, h) _Pragma("unroll") for (int m = 0; m < 4; ++m) _Pragma("unroll") for (int k = 0; k < 2; ++k) \
;     dst[m][k] = *reinterpret_cast<const bf16x8*>((char*)SA(b, h) + lds_byte(wr * 64 + m * 16 + fr, k * 32 + fq * 8))
; #define LDB(dst, b, h) _Pragma("unroll") for (int n = 0; n < 2; ++n) _Pragma("unroll") for (int k = 0; k < 2; ++k) \
;     dst[n][k] = *reinterpret_cast<const bf16x8*>((char*)SB(b, h) + lds_byte(wc * 32 + n * 16 + fr, k * 32 + fq * 8))
; #define MMA(ai, bj, At_, Bt_) do { __builtin_amdgcn_s_setprio(1); \
;     _Pragma("unroll") for (int k = 0; k < 2; ++k) _Pragma("unroll") for (int m = 0; m < 4; ++m) _Pragma("unroll") for (int n = 0; n < 2; ++n) \
;       acc[ai][bj][m][n] = __builtin_amdgcn_mfma_f32_16x16x32_bf16(At_[m][k], Bt_[n][k], acc[ai][bj][m][n], 0, 0, 0); \
;     __builtin_amdgcn_s_setprio(0); } while (0)
; #define WAIT_V(n) asm volatile("s_waitcnt vmcnt(" #n ")" ::: "memory")
; #define BAR __builtin_amdgcn_s_barrier()
; template <int EPI, int N, int K>
; __device__ __forceinline__ void gemm_phase(const bf16_t* __restrict__ A, const bf16_t* __restrict__ Bt, const EpiArgs ea) {
;     ...
;       LDA(At, 0, 1); WAIT_V(4); BAR; WAIT_L(0); MMA(1, 0, At, B0); MMA(1, 1, At, B1); BAR; }
;     { LDB(B0, 1, 0); LDA(At, 1, 0); WAIT_V(2); BAR; WAIT_L(0); MMA(0, 0, At, B0); BAR;
;       LDB(B1, 1, 1); WAIT_V(0); BAR; WAIT_L(0); MMA(0, 1, At, B1); BAR;
	s_waitcnt lgkmcnt(0)
	s_setprio 1
	v_mfma_f32_16x16x32_bf16 v[60:63], v[64:67], v[132:135], v[60:63]
	v_mfma_f32_16x16x32_bf16 v[56:59], v[64:67], v[160:163], v[56:59]
	v_mfma_f32_16x16x32_bf16 v[52:55], v[80:83], v[132:135], v[52:55]
	v_mfma_f32_16x16x32_bf16 v[48:51], v[80:83], v[160:163], v[48:51]
	v_mfma_f32_16x16x32_bf16 v[44:47], v[184:187], v[132:135], v[44:47]
	v_mfma_f32_16x16x32_bf16 v[40:43], v[184:187], v[160:163], v[40:43]
	v_mfma_f32_16x16x32_bf16 v[36:39], v[192:195], v[132:135], v[36:39]
	v_mfma_f32_16x16x32_bf16 v[32:35], v[192:195], v[160:163], v[32:35]
	v_mfma_f32_16x16x32_bf16 v[60:63], v[68:71], v[156:159], v[60:63]
	v_mfma_f32_16x16x32_bf16 v[56:59], v[68:71], v[164:167], v[56:59]
	v_mfma_f32_16x16x32_bf16 v[52:55], v[84:87], v[156:159], v[52:55]
	v_mfma_f32_16x16x32_bf16 v[48:51], v[84:87], v[164:167], v[48:51]
	v_mfma_f32_16x16x32_bf16 v[44:47], v[188:191], v[156:159], v[44:47]
	v_mfma_f32_16x16x32_bf16 v[40:43], v[188:191], v[164:167], v[40:43]
	v_mfma_f32_16x16x32_bf16 v[36:39], v[196:199], v[156:159], v[36:39]
	v_mfma_f32_16x16x32_bf16 v[32:35], v[196:199], v[164:167], v[32:35]
	s_setprio 0
	s_setprio 1
	v_mfma_f32_16x16x32_bf16 v[28:31], v[64:67], v[200:203], v[28:31]
	v_mfma_f32_16x16x32_bf16 v[24:27], v[64:67], v[208:211], v[24:27]
	v_mfma_f32_16x16x32_bf16 v[12:15], v[184:187], v[200:203], v[12:15]
	v_mfma_f32_16x16x32_bf16 v[8:11], v[184:187], v[208:211], v[8:11]
	v_mfma_f32_16x16x32_bf16 v[20:23], v[80:83], v[200:203], v[20:23]
	v_mfma_f32_16x16x32_bf16 v[16:19], v[80:83], v[208:211], v[16:19]
	v_mfma_f32_16x16x32_bf16 v[4:7], v[192:195], v[200:203], v[4:7]
	v_mfma_f32_16x16x32_bf16 v[0:3], v[192:195], v[208:211], v[0:3]
	v_mfma_f32_16x16x32_bf16 v[28:31], v[68:71], v[204:207], v[28:31]
	v_mfma_f32_16x16x32_bf16 v[24:27], v[68:71], v[212:215], v[24:27]
	v_mfma_f32_16x16x32_bf16 v[12:15], v[188:191], v[204:207], v[12:15]
	v_mfma_f32_16x16x32_bf16 v[8:11], v[188:191], v[212:215], v[8:11]
	v_mfma_f32_16x16x32_bf16 v[132:135], v[84:87], v[204:207], v[20:23]
	v_mfma_f32_16x16x32_bf16 v[156:159], v[84:87], v[212:215], v[16:19]
	v_mfma_f32_16x16x32_bf16 v[160:163], v[196:199], v[204:207], v[4:7]
	v_mfma_f32_16x16x32_bf16 v[164:167], v[196:199], v[212:215], v[0:3]
	s_setprio 0
	s_barrier
	s_nop 0
	ds_read_b128 v[0:3], v154
	ds_read_b128 v[4:7], v154 offset:1024
	ds_read_b128 v[16:19], v154 offset:2048
	ds_read_b128 v[184:187], v154 offset:3072
	ds_read_b128 v[20:23], v149 offset:32768
	ds_read_b128 v[188:191], v149 offset:33792
	ds_read_b128 v[192:195], v150 offset:32768
	ds_read_b128 v[196:199], v150 offset:33792
	ds_read_b128 v[200:203], v151 offset:32768
	ds_read_b128 v[204:207], v151 offset:33792
	ds_read_b128 v[208:211], v152 offset:32768
	ds_read_b128 v[212:215], v152 offset:33792
	s_waitcnt vmcnt(2)
	s_barrier
	s_waitcnt lgkmcnt(0)
	s_setprio 1
	v_mfma_f32_16x16x32_bf16 v[64:67], v[20:23], v[0:3], v[124:127]
	v_mfma_f32_16x16x32_bf16 v[68:71], v[20:23], v[16:19], v[120:123]
	v_mfma_f32_16x16x32_bf16 v[80:83], v[192:195], v[0:3], v[116:119]
	v_mfma_f32_16x16x32_bf16 v[84:87], v[192:195], v[16:19], v[112:115]
	v_mfma_f32_16x16x32_bf16 v[108:111], v[200:203], v[0:3], v[108:111]
	v_mfma_f32_16x16x32_bf16 v[104:107], v[200:203], v[16:19], v[104:107]
	v_mfma_f32_16x16x32_bf16 v[120:123], v[208:211], v[0:3], v[100:103]
	v_mfma_f32_16x16x32_bf16 v[124:127], v[208:211], v[16:19], v[96:99]
	v_mfma_f32_16x16x32_bf16 v[112:115], v[188:191], v[4:7], v[64:67]
	v_mfma_f32_16x16x32_bf16 v[116:119], v[188:191], v[184:187], v[68:71]
	v_mfma_f32_16x16x32_bf16 v[96:99], v[196:199], v[4:7], v[80:83]
	v_mfma_f32_16x16x32_bf16 v[100:103], v[196:199], v[184:187], v[84:87]
	v_mfma_f32_16x16x32_bf16 v[80:83], v[204:207], v[4:7], v[108:111]
	v_mfma_f32_16x16x32_bf16 v[84:87], v[204:207], v[184:187], v[104:107]
	v_mfma_f32_16x16x32_bf16 v[64:67], v[212:215], v[4:7], v[120:123]
	v_mfma_f32_16x16x32_bf16 v[68:71], v[212:215], v[184:187], v[124:127]
	s_setprio 0
	s_barrier
; #define LDA(dst, b, h) _Pragma("unroll") for (int m = 0; m < 4; ++m) _Pragma("unroll") for (int k = 0; k < 2; ++k) \
;     dst[m][k] = *reinterpret_cast<const bf16x8*>((char*)SA(b, h) + lds_byte(wr * 64 + m * 16 + fr, k * 32 + fq * 8))
; #define LDB(dst, b, h) _Pragma("unroll") for (int n = 0; n < 2; ++n) _Pragma("unroll") for (int k = 0; k < 2; ++k) \
;     dst[n][k] = *reinterpret_cast<const bf16x8*>((char*)SB(b, h) + lds_byte(wc * 32 + n * 16 + fr, k * 32 + fq * 8))
; #define MMA(ai, bj, At_, Bt_) do { __builtin_amdgcn_s_setprio(1); \
;     _Pragma("unroll") for (int k = 0; k < 2; ++k) _Pragma("unroll") for (int m = 0; m < 4; ++m) _Pragma("unroll") for (int n = 0; n < 2; ++n) \
;       acc[ai][bj][m][n] = __builtin_amdgcn_mfma_f32_16x16x32_bf16(At_[m][k], Bt_[n][k], acc[ai][bj][m][n], 0, 0, 0); \
;     __builtin_amdgcn_s_setprio(0); } while (0)
; #define WAIT_V(n) asm volatile("s_waitcnt vmcnt(" #n ")" ::: "memory")
; #define BAR __builtin_amdgcn_s_barrier()
; template <int EPI, int N, int K>
; __device__ __forceinline__ void gemm_phase(const bf16_t* __restrict__ A, const bf16_t* __restrict__ Bt, const EpiArgs ea) {
;     ...
;     { LDB(B0, 1, 0); LDA(At, 1, 0); WAIT_V(2); BAR; WAIT_L(0); MMA(0, 0, At, B0); BAR;
;       LDB(B1, 1, 1); WAIT_V(0); BAR; WAIT_L(0); MMA(0, 1, At, B1); BAR;
;       LDA(At, 1, 1); BAR; WAIT_L(0); MMA(1, 0, At, B0); MMA(1, 1, At, B1); BAR; }
;     if (wr == 0) BAR;
	ds_read_b128 v[216:219], v155
	ds_read_b128 v[220:223], v155 offset:1024
	ds_read_b128 v[224:227], v155 offset:2048
	ds_read_b128 v[228:231], v155 offset:3072
	s_waitcnt vmcnt(0)
	s_barrier
	s_waitcnt lgkmcnt(0)
	s_setprio 1
	v_mfma_f32_16x16x32_bf16 v[92:95], v[20:23], v[216:219], v[92:95]
	v_mfma_f32_16x16x32_bf16 v[20:23], v[20:23], v[224:227], v[88:91]
	v_mfma_f32_16x16x32_bf16 v[88:91], v[192:195], v[216:219], v[168:171]
	v_mfma_f32_16x16x32_bf16 v[108:111], v[192:195], v[224:227], v[172:175]
	v_mfma_f32_16x16x32_bf16 v[76:79], v[200:203], v[216:219], v[76:79]
	v_mfma_f32_16x16x32_bf16 v[72:75], v[200:203], v[224:227], v[72:75]
	v_mfma_f32_16x16x32_bf16 v[168:171], v[208:211], v[216:219], v[176:179]
	v_mfma_f32_16x16x32_bf16 v[172:175], v[208:211], v[224:227], v[180:183]
	v_mfma_f32_16x16x32_bf16 v[120:123], v[188:191], v[220:223], v[92:95]
	v_mfma_f32_16x16x32_bf16 v[124:127], v[188:191], v[228:231], v[20:23]
	v_mfma_f32_16x16x32_bf16 v[104:107], v[196:199], v[220:223], v[88:91]
	v_mfma_f32_16x16x32_bf16 v[108:111], v[196:199], v[228:231], v[108:111]
	v_mfma_f32_16x16x32_bf16 v[88:91], v[204:207], v[220:223], v[76:79]
	v_mfma_f32_16x16x32_bf16 v[92:95], v[204:207], v[228:231], v[72:75]
	v_mfma_f32_16x16x32_bf16 v[72:75], v[212:215], v[220:223], v[168:171]
	v_mfma_f32_16x16x32_bf16 v[76:79], v[212:215], v[228:231], v[172:175]
	s_setprio 0
	s_barrier
	ds_read_b128 v[168:171], v149 offset:49152
	ds_read_b128 v[172:175], v149 offset:50176
	ds_read_b128 v[176:179], v150 offset:49152
	ds_read_b128 v[180:183], v150 offset:50176
	ds_read_b128 v[188:191], v151 offset:49152
	ds_read_b128 v[192:195], v151 offset:50176
	ds_read_b128 v[196:199], v152 offset:49152
	ds_read_b128 v[200:203], v152 offset:50176
	s_barrier
	s_waitcnt lgkmcnt(0)
	s_setprio 1
	v_mfma_f32_16x16x32_bf16 v[20:23], v[168:171], v[0:3], v[60:63]
	v_mfma_f32_16x16x32_bf16 v[56:59], v[168:171], v[16:19], v[56:59]
	v_mfma_f32_16x16x32_bf16 v[60:63], v[176:179], v[0:3], v[52:55]
	v_mfma_f32_16x16x32_bf16 v[204:207], v[176:179], v[16:19], v[48:51]
	v_mfma_f32_16x16x32_bf16 v[44:47], v[188:191], v[0:3], v[44:47]
	v_mfma_f32_16x16x32_bf16 v[40:43], v[188:191], v[16:19], v[40:43]
	v_mfma_f32_16x16x32_bf16 v[0:3], v[196:199], v[0:3], v[36:39]
	v_mfma_f32_16x16x32_bf16 v[208:211], v[196:199], v[16:19], v[32:35]
	v_mfma_f32_16x16x32_bf16 v[48:51], v[172:175], v[4:7], v[20:23]
	v_mfma_f32_16x16x32_bf16 v[52:55], v[172:175], v[184:187], v[56:59]
	v_mfma_f32_16x16x32_bf16 v[32:35], v[180:183], v[4:7], v[60:63]
	v_mfma_f32_16x16x32_bf16 v[36:39], v[180:183], v[184:187], v[204:207]
	v_mfma_f32_16x16x32_bf16 v[16:19], v[192:195], v[4:7], v[44:47]
	v_mfma_f32_16x16x32_bf16 v[20:23], v[192:195], v[184:187], v[40:43]
	v_mfma_f32_16x16x32_bf16 v[0:3], v[200:203], v[4:7], v[0:3]
	v_mfma_f32_16x16x32_bf16 v[4:7], v[200:203], v[184:187], v[208:211]
	s_setprio 0
	s_setprio 1
	v_mfma_f32_16x16x32_bf16 v[28:31], v[168:171], v[216:219], v[28:31]
	v_mfma_f32_16x16x32_bf16 v[24:27], v[168:171], v[224:227], v[24:27]
	v_mfma_f32_16x16x32_bf16 v[40:43], v[176:179], v[216:219], v[132:135]
	v_mfma_f32_16x16x32_bf16 v[44:47], v[176:179], v[224:227], v[156:159]
	v_mfma_f32_16x16x32_bf16 v[12:15], v[188:191], v[216:219], v[12:15]
	v_mfma_f32_16x16x32_bf16 v[8:11], v[188:191], v[224:227], v[8:11]
	v_mfma_f32_16x16x32_bf16 v[132:135], v[196:199], v[216:219], v[160:163]
	v_mfma_f32_16x16x32_bf16 v[156:159], v[196:199], v[224:227], v[164:167]
	v_mfma_f32_16x16x32_bf16 v[56:59], v[172:175], v[220:223], v[28:31]
	v_mfma_f32_16x16x32_bf16 v[60:63], v[172:175], v[228:231], v[24:27]
	v_mfma_f32_16x16x32_bf16 v[40:43], v[180:183], v[220:223], v[40:43]
	v_mfma_f32_16x16x32_bf16 v[44:47], v[180:183], v[228:231], v[44:47]
	v_mfma_f32_16x16x32_bf16 v[24:27], v[192:195], v[220:223], v[12:15]
	v_mfma_f32_16x16x32_bf16 v[28:31], v[192:195], v[228:231], v[8:11]
	v_mfma_f32_16x16x32_bf16 v[8:11], v[200:203], v[220:223], v[132:135]
	v_mfma_f32_16x16x32_bf16 v[12:15], v[200:203], v[228:231], v[156:159]
	s_setprio 0
	s_barrier
	s_and_saveexec_b64 s[2:3], s[8:9]
	s_cbranch_execz .LBB0_512
	s_barrier

; #define STAGE_A(POFF, h, kt) STAGE_AX(POFF, h, kt, brow)
; #define STAGE_B(POFF, h, kt) STAGE_BX(POFF, h, kt, bcol)
; #define LDA(dst, b, h) _Pragma("unroll") for (int m = 0; m < 4; ++m) _Pragma("unroll") for (int k = 0; k < 2; ++k) \
;     dst[m][k] = *reinterpret_cast<const bf16x8*>((char*)SA(b, h) + lds_byte(wr * 64 + m * 16 + fr, k * 32 + fq * 8))
; #define LDB(dst, b, h) _Pragma("unroll") for (int n = 0; n < 2; ++n) _Pragma("unroll") for (int k = 0; k < 2; ++k) \
;     dst[n][k] = *reinterpret_cast<const bf16x8*>((char*)SB(b, h) + lds_byte(wc * 32 + n * 16 + fr, k * 32 + fq * 8))
; #define MMA(ai, bj, At_, Bt_) do { __builtin_amdgcn_s_setprio(1); \
;     _Pragma("unroll") for (int k = 0; k < 2; ++k) _Pragma("unroll") for (int m = 0; m < 4; ++m) _Pragma("unroll") for (int n = 0; n < 2; ++n) \
;       acc[ai][bj][m][n] = __builtin_amdgcn_mfma_f32_16x16x32_bf16(At_[m][k], Bt_[n][k], acc[ai][bj][m][n], 0, 0, 0); \
;     __builtin_amdgcn_s_setprio(0); } while (0)
; #define WAIT_V(n) asm volatile("s_waitcnt vmcnt(" #n ")" ::: "memory")
; #define BAR __builtin_amdgcn_s_barrier()
; #define SCHED __builtin_amdgcn_sched_barrier(0)
; template <int EPI, int N, int K>
; __device__ __forceinline__ void gemm_phase(const bf16_t* __restrict__ A, const bf16_t* __restrict__ Bt, const EpiArgs ea) {
;     ...
;     for (int t = 0; t < nt - 2; t += 2) {
;       LDB(B0, 0, 0); SCHED; LDA(At, 0, 0); STAGE_A(SA_OFF(1, 1), 1, t + 1);
;       WAIT_L(8); BAR; WAIT_L(0); MMA(0, 0, At, B0); BAR; SCHED;
;       LDB(B1, 0, 1); STAGE_B(SB_OFF(0, 0), 0, t + 2);
;       BAR; WAIT_L(0); MMA(0, 1, At, B1); BAR;
;       LDA(At, 0, 1); STAGE_A(SA_OFF(0, 0), 0, t + 2);
;       BAR; WAIT_L(0); MMA(1, 0, At, B0); BAR; SCHED;
;       STAGE_B(SB_OFF(0, 1), 1, t + 2);
;       WAIT_V(6); BAR; MMA(1, 1, At, B1); BAR;
.LBB0_568:
	ds_read_b128 v[218:221], v148 offset:16384
	ds_read_b128 v[222:225], v148 offset:17408
	ds_read_b128 v[226:229], v149 offset:16384
	ds_read_b128 v[230:233], v149 offset:17408
	ds_read_b128 v[238:241], v150 offset:16384
	ds_read_b128 v[242:245], v150 offset:17408
	s_add_i32 s34, s29, s31
	s_or_b32 s35, s34, 0x200080
	s_mov_b32 m0, s26
	s_nop 0
	buffer_load_dwordx4 v131, s[64:67], s35 offen lds
	s_or_b32 s35, s34, 0x300080
	s_mov_b32 m0, s27
	s_nop 0
	buffer_load_dwordx4 v131, s[64:67], s35 offen lds
	s_setprio 1
	s_barrier
	s_waitcnt lgkmcnt(6)
	v_mfma_f32_16x16x32_bf16 v[124:127], v[168:171], v[132:135], v[124:127]
	v_mfma_f32_16x16x32_bf16 v[120:123], v[168:171], v[160:163], v[120:123]
	v_mfma_f32_16x16x32_bf16 v[116:119], v[176:179], v[132:135], v[116:119]
	v_mfma_f32_16x16x32_bf16 v[112:115], v[176:179], v[160:163], v[112:115]
	v_mfma_f32_16x16x32_bf16 v[108:111], v[184:187], v[132:135], v[108:111]
	v_mfma_f32_16x16x32_bf16 v[104:107], v[184:187], v[160:163], v[104:107]
	v_mfma_f32_16x16x32_bf16 v[100:103], v[192:195], v[132:135], v[100:103]
	v_mfma_f32_16x16x32_bf16 v[96:99], v[192:195], v[160:163], v[96:99]
	v_mfma_f32_16x16x32_bf16 v[124:127], v[172:175], v[156:159], v[124:127]
	v_mfma_f32_16x16x32_bf16 v[120:123], v[172:175], v[164:167], v[120:123]
	v_mfma_f32_16x16x32_bf16 v[116:119], v[180:183], v[156:159], v[116:119]
	v_mfma_f32_16x16x32_bf16 v[112:115], v[180:183], v[164:167], v[112:115]
	v_mfma_f32_16x16x32_bf16 v[108:111], v[188:191], v[156:159], v[108:111]
	v_mfma_f32_16x16x32_bf16 v[104:107], v[188:191], v[164:167], v[104:107]
	v_mfma_f32_16x16x32_bf16 v[100:103], v[196:199], v[156:159], v[100:103]
	v_mfma_f32_16x16x32_bf16 v[96:99], v[196:199], v[164:167], v[96:99]
	s_barrier
	s_setprio 0
	ds_read_b128 v[200:203], v152
	ds_read_b128 v[204:207], v152 offset:1024
	ds_read_b128 v[208:211], v152 offset:2048
	ds_read_b128 v[212:215], v152 offset:3072
	ds_read_b128 v[246:249], v151 offset:16384
	ds_read_b128 v[250:253], v151 offset:17408
	s_add_i32 s35, s11, s31
	s_add_i32 s36, s35, 0x100
	s_mov_b32 m0, s13
	s_nop 0
	buffer_load_dwordx4 v144, s[80:83], s36 offen lds
	s_add_i32 s36, s35, 0x200100
	s_mov_b32 m0, s14
	s_nop 0
	buffer_load_dwordx4 v144, s[80:83], s36 offen lds
	s_waitcnt vmcnt(6)
	s_setprio 1
	s_barrier
	s_waitcnt lgkmcnt(2)
	v_mfma_f32_16x16x32_bf16 v[92:95], v[168:171], v[200:203], v[92:95]
	v_mfma_f32_16x16x32_bf16 v[88:91], v[168:171], v[208:211], v[88:91]
	v_mfma_f32_16x16x32_bf16 v[84:87], v[176:179], v[200:203], v[84:87]
	v_mfma_f32_16x16x32_bf16 v[80:83], v[176:179], v[208:211], v[80:83]
	v_mfma_f32_16x16x32_bf16 v[76:79], v[184:187], v[200:203], v[76:79]
	v_mfma_f32_16x16x32_bf16 v[72:75], v[184:187], v[208:211], v[72:75]
	v_mfma_f32_16x16x32_bf16 v[68:71], v[192:195], v[200:203], v[68:71]
	v_mfma_f32_16x16x32_bf16 v[64:67], v[192:195], v[208:211], v[64:67]
	v_mfma_f32_16x16x32_bf16 v[92:95], v[172:175], v[204:207], v[92:95]
	v_mfma_f32_16x16x32_bf16 v[88:91], v[172:175], v[212:215], v[88:91]
	v_mfma_f32_16x16x32_bf16 v[84:87], v[180:183], v[204:207], v[84:87]
	v_mfma_f32_16x16x32_bf16 v[80:83], v[180:183], v[212:215], v[80:83]
	v_mfma_f32_16x16x32_bf16 v[76:79], v[188:191], v[204:207], v[76:79]
	v_mfma_f32_16x16x32_bf16 v[72:75], v[188:191], v[212:215], v[72:75]
	v_mfma_f32_16x16x32_bf16 v[68:71], v[196:199], v[204:207], v[68:71]
	v_mfma_f32_16x16x32_bf16 v[64:67], v[196:199], v[212:215], v[64:67]
	s_barrier
	s_setprio 0
	ds_read_b128 v[168:171], v148 offset:32768
	ds_read_b128 v[172:175], v148 offset:33792
	ds_read_b128 v[176:179], v149 offset:32768
	ds_read_b128 v[180:183], v149 offset:33792
	ds_read_b128 v[184:187], v150 offset:32768
	ds_read_b128 v[188:191], v150 offset:33792
	s_add_i32 s36, s34, 0x100
	s_mov_b32 m0, s12
	s_nop 0
	buffer_load_dwordx4 v131, s[64:67], s36 offen lds
	s_add_i32 s37, s34, 0x100100
	s_mov_b32 m0, s15
	s_nop 0
	buffer_load_dwordx4 v131, s[64:67], s37 offen lds
	s_waitcnt vmcnt(10)
	s_setprio 1
	s_barrier
	s_waitcnt lgkmcnt(6)
	v_mfma_f32_16x16x32_bf16 v[60:63], v[218:221], v[132:135], v[60:63]
	v_mfma_f32_16x16x32_bf16 v[56:59], v[218:221], v[160:163], v[56:59]
	v_mfma_f32_16x16x32_bf16 v[52:55], v[226:229], v[132:135], v[52:55]
	v_mfma_f32_16x16x32_bf16 v[48:51], v[226:229], v[160:163], v[48:51]
	v_mfma_f32_16x16x32_bf16 v[44:47], v[238:241], v[132:135], v[44:47]
	v_mfma_f32_16x16x32_bf16 v[40:43], v[238:241], v[160:163], v[40:43]
	v_mfma_f32_16x16x32_bf16 v[36:39], v[246:249], v[132:135], v[36:39]
	v_mfma_f32_16x16x32_bf16 v[32:35], v[246:249], v[160:163], v[32:35]
	v_mfma_f32_16x16x32_bf16 v[60:63], v[222:225], v[156:159], v[60:63]
	v_mfma_f32_16x16x32_bf16 v[56:59], v[222:225], v[164:167], v[56:59]
	v_mfma_f32_16x16x32_bf16 v[52:55], v[230:233], v[156:159], v[52:55]
	v_mfma_f32_16x16x32_bf16 v[48:51], v[230:233], v[164:167], v[48:51]
	v_mfma_f32_16x16x32_bf16 v[44:47], v[242:245], v[156:159], v[44:47]
	v_mfma_f32_16x16x32_bf16 v[40:43], v[242:245], v[164:167], v[40:43]
	v_mfma_f32_16x16x32_bf16 v[36:39], v[250:253], v[156:159], v[36:39]
	v_mfma_f32_16x16x32_bf16 v[32:35], v[250:253], v[164:167], v[32:35]
	s_barrier
	s_setprio 0
	ds_read_b128 v[132:135], v153
	ds_read_b128 v[156:159], v153 offset:1024
	ds_read_b128 v[160:163], v153 offset:2048
	ds_read_b128 v[164:167], v153 offset:3072
	ds_read_b128 v[192:195], v151 offset:32768
	ds_read_b128 v[196:199], v151 offset:33792
	s_add_i32 s37, s35, 0x8100
	s_mov_b32 m0, s16
	s_nop 0
	buffer_load_dwordx4 v144, s[80:83], s37 offen lds
	s_add_i32 s37, s35, 0x208100
	s_mov_b32 m0, s17
	s_nop 0
	buffer_load_dwordx4 v144, s[80:83], s37 offen lds
	s_waitcnt vmcnt(6)
	s_setprio 1
	s_barrier
; #define STAGE_A(POFF, h, kt) STAGE_AX(POFF, h, kt, brow)
; #define STAGE_B(POFF, h, kt) STAGE_BX(POFF, h, kt, bcol)
; #define LDA(dst, b, h) _Pragma("unroll") for (int m = 0; m < 4; ++m) _Pragma("unroll") for (int k = 0; k < 2; ++k) \
;     dst[m][k] = *reinterpret_cast<const bf16x8*>((char*)SA(b, h) + lds_byte(wr * 64 + m * 16 + fr, k * 32 + fq * 8))
; #define LDB(dst, b, h) _Pragma("unroll") for (int n = 0; n < 2; ++n) _Pragma("unroll") for (int k = 0; k < 2; ++k) \
;     dst[n][k] = *reinterpret_cast<const bf16x8*>((char*)SB(b, h) + lds_byte(wc * 32 + n * 16 + fr, k * 32 + fq * 8))
; #define MMA(ai, bj, At_, Bt_) do { __builtin_amdgcn_s_setprio(1); \
;     _Pragma("unroll") for (int k = 0; k < 2; ++k) _Pragma("unroll") for (int m = 0; m < 4; ++m) _Pragma("unroll") for (int n = 0; n < 2; ++n) \
;       acc[ai][bj][m][n] = __builtin_amdgcn_mfma_f32_16x16x32_bf16(At_[m][k], Bt_[n][k], acc[ai][bj][m][n], 0, 0, 0); \
;     __builtin_amdgcn_s_setprio(0); } while (0)
; #define WAIT_V(n) asm volatile("s_waitcnt vmcnt(" #n ")" ::: "memory")
; #define BAR __builtin_amdgcn_s_barrier()
; #define SCHED __builtin_amdgcn_sched_barrier(0)
; template <int EPI, int N, int K>
; __device__ __forceinline__ void gemm_phase(const bf16_t* __restrict__ A, const bf16_t* __restrict__ Bt, const EpiArgs ea) {
;     ...
;       WAIT_V(6); BAR; MMA(1, 1, At, B1); BAR;
;       LDB(B0, 1, 0); SCHED; LDA(At, 1, 0); STAGE_A(SA_OFF(0, 1), 1, t + 2);
;       WAIT_L(8); BAR; WAIT_L(0); MMA(0, 0, At, B0); BAR; SCHED;
;       LDB(B1, 1, 1); STAGE_B(SB_OFF(1, 0), 0, t + 3);
;       BAR; WAIT_L(0); MMA(0, 1, At, B1); BAR;
;       LDA(At, 1, 1); STAGE_A(SA_OFF(1, 0), 0, t + 3);
;       BAR; WAIT_L(0); MMA(1, 0, At, B0); BAR; SCHED;
;       STAGE_B(SB_OFF(1, 1), 1, t + 3);
;       WAIT_V(6); BAR; MMA(1, 1, At, B1); BAR;
	v_mfma_f32_16x16x32_bf16 v[28:31], v[218:221], v[200:203], v[28:31]
	v_mfma_f32_16x16x32_bf16 v[24:27], v[218:221], v[208:211], v[24:27]
	v_mfma_f32_16x16x32_bf16 v[20:23], v[226:229], v[200:203], v[20:23]
	v_mfma_f32_16x16x32_bf16 v[16:19], v[226:229], v[208:211], v[16:19]
	v_mfma_f32_16x16x32_bf16 v[12:15], v[238:241], v[200:203], v[12:15]
	v_mfma_f32_16x16x32_bf16 v[8:11], v[238:241], v[208:211], v[8:11]
	v_mfma_f32_16x16x32_bf16 v[4:7], v[246:249], v[200:203], v[4:7]
	v_mfma_f32_16x16x32_bf16 v[0:3], v[246:249], v[208:211], v[0:3]
	v_mfma_f32_16x16x32_bf16 v[28:31], v[222:225], v[204:207], v[28:31]
	v_mfma_f32_16x16x32_bf16 v[24:27], v[222:225], v[212:215], v[24:27]
	v_mfma_f32_16x16x32_bf16 v[20:23], v[230:233], v[204:207], v[20:23]
	v_mfma_f32_16x16x32_bf16 v[16:19], v[230:233], v[212:215], v[16:19]
	v_mfma_f32_16x16x32_bf16 v[12:15], v[242:245], v[204:207], v[12:15]
	v_mfma_f32_16x16x32_bf16 v[8:11], v[242:245], v[212:215], v[8:11]
	v_mfma_f32_16x16x32_bf16 v[4:7], v[250:253], v[204:207], v[4:7]
	v_mfma_f32_16x16x32_bf16 v[0:3], v[250:253], v[212:215], v[0:3]
	s_barrier
	s_setprio 0
	ds_read_b128 v[218:221], v148 offset:49152
	ds_read_b128 v[222:225], v148 offset:50176
	ds_read_b128 v[226:229], v149 offset:49152
	ds_read_b128 v[230:233], v149 offset:50176
	ds_read_b128 v[238:241], v150 offset:49152
	ds_read_b128 v[242:245], v150 offset:50176
	s_or_b32 s37, s36, 0x200000
	s_mov_b32 m0, s18
	s_nop 0
	buffer_load_dwordx4 v131, s[64:67], s37 offen lds
	s_or_b32 s36, s36, 0x300000
	s_mov_b32 m0, s19
	s_nop 0
	buffer_load_dwordx4 v131, s[64:67], s36 offen lds
	s_setprio 1
	s_barrier
	s_waitcnt lgkmcnt(6)
	v_mfma_f32_16x16x32_bf16 v[124:127], v[168:171], v[132:135], v[124:127]
	v_mfma_f32_16x16x32_bf16 v[120:123], v[168:171], v[160:163], v[120:123]
	v_mfma_f32_16x16x32_bf16 v[116:119], v[176:179], v[132:135], v[116:119]
	v_mfma_f32_16x16x32_bf16 v[112:115], v[176:179], v[160:163], v[112:115]
	v_mfma_f32_16x16x32_bf16 v[108:111], v[184:187], v[132:135], v[108:111]
	v_mfma_f32_16x16x32_bf16 v[104:107], v[184:187], v[160:163], v[104:107]
	v_mfma_f32_16x16x32_bf16 v[100:103], v[192:195], v[132:135], v[100:103]
	v_mfma_f32_16x16x32_bf16 v[96:99], v[192:195], v[160:163], v[96:99]
	v_mfma_f32_16x16x32_bf16 v[124:127], v[172:175], v[156:159], v[124:127]
	v_mfma_f32_16x16x32_bf16 v[120:123], v[172:175], v[164:167], v[120:123]
	v_mfma_f32_16x16x32_bf16 v[116:119], v[180:183], v[156:159], v[116:119]
	v_mfma_f32_16x16x32_bf16 v[112:115], v[180:183], v[164:167], v[112:115]
	v_mfma_f32_16x16x32_bf16 v[108:111], v[188:191], v[156:159], v[108:111]
	v_mfma_f32_16x16x32_bf16 v[104:107], v[188:191], v[164:167], v[104:107]
	v_mfma_f32_16x16x32_bf16 v[100:103], v[196:199], v[156:159], v[100:103]
	v_mfma_f32_16x16x32_bf16 v[96:99], v[196:199], v[164:167], v[96:99]
	s_barrier
	s_setprio 0
	ds_read_b128 v[200:203], v154
	ds_read_b128 v[204:207], v154 offset:1024
	ds_read_b128 v[208:211], v154 offset:2048
	ds_read_b128 v[212:215], v154 offset:3072
	ds_read_b128 v[246:249], v151 offset:49152
	ds_read_b128 v[250:253], v151 offset:50176
	s_add_i32 s36, s35, 0x180
	s_mov_b32 m0, s20
	s_nop 0
	buffer_load_dwordx4 v144, s[80:83], s36 offen lds
	s_add_i32 s36, s35, 0x200180
	s_mov_b32 m0, s21
	s_nop 0
	buffer_load_dwordx4 v144, s[80:83], s36 offen lds
	s_waitcnt vmcnt(6)
	s_setprio 1
	s_barrier
	s_waitcnt lgkmcnt(2)
	v_mfma_f32_16x16x32_bf16 v[92:95], v[168:171], v[200:203], v[92:95]
	v_mfma_f32_16x16x32_bf16 v[88:91], v[168:171], v[208:211], v[88:91]
	v_mfma_f32_16x16x32_bf16 v[84:87], v[176:179], v[200:203], v[84:87]
	v_mfma_f32_16x16x32_bf16 v[80:83], v[176:179], v[208:211], v[80:83]
	v_mfma_f32_16x16x32_bf16 v[76:79], v[184:187], v[200:203], v[76:79]
	v_mfma_f32_16x16x32_bf16 v[72:75], v[184:187], v[208:211], v[72:75]
	v_mfma_f32_16x16x32_bf16 v[68:71], v[192:195], v[200:203], v[68:71]
	v_mfma_f32_16x16x32_bf16 v[64:67], v[192:195], v[208:211], v[64:67]
	v_mfma_f32_16x16x32_bf16 v[92:95], v[172:175], v[204:207], v[92:95]
	v_mfma_f32_16x16x32_bf16 v[88:91], v[172:175], v[212:215], v[88:91]
	v_mfma_f32_16x16x32_bf16 v[84:87], v[180:183], v[204:207], v[84:87]
	v_mfma_f32_16x16x32_bf16 v[80:83], v[180:183], v[212:215], v[80:83]
	v_mfma_f32_16x16x32_bf16 v[76:79], v[188:191], v[204:207], v[76:79]
	v_mfma_f32_16x16x32_bf16 v[72:75], v[188:191], v[212:215], v[72:75]
	v_mfma_f32_16x16x32_bf16 v[68:71], v[196:199], v[204:207], v[68:71]
	v_mfma_f32_16x16x32_bf16 v[64:67], v[196:199], v[212:215], v[64:67]
	s_barrier
	s_setprio 0
	ds_read_b128 v[168:171], v148
	ds_read_b128 v[172:175], v148 offset:1024
	ds_read_b128 v[176:179], v149
	ds_read_b128 v[180:183], v149 offset:1024
	ds_read_b128 v[184:187], v150
	ds_read_b128 v[188:191], v150 offset:1024
	s_add_i32 s36, s34, 0x180
	s_mov_b32 m0, s22
	s_nop 0
	buffer_load_dwordx4 v131, s[64:67], s36 offen lds
	s_add_i32 s34, s34, 0x100180
	s_mov_b32 m0, s23
	s_nop 0
	buffer_load_dwordx4 v131, s[64:67], s34 offen lds
	s_waitcnt vmcnt(10)
	s_setprio 1
	s_barrier
	s_waitcnt lgkmcnt(6)
	v_mfma_f32_16x16x32_bf16 v[60:63], v[218:221], v[132:135], v[60:63]
	v_mfma_f32_16x16x32_bf16 v[56:59], v[218:221], v[160:163], v[56:59]
	v_mfma_f32_16x16x32_bf16 v[52:55], v[226:229], v[132:135], v[52:55]
	v_mfma_f32_16x16x32_bf16 v[48:51], v[226:229], v[160:163], v[48:51]
	v_mfma_f32_16x16x32_bf16 v[44:47], v[238:241], v[132:135], v[44:47]
	v_mfma_f32_16x16x32_bf16 v[40:43], v[238:241], v[160:163], v[40:43]
	v_mfma_f32_16x16x32_bf16 v[36:39], v[246:249], v[132:135], v[36:39]
	v_mfma_f32_16x16x32_bf16 v[32:35], v[246:249], v[160:163], v[32:35]
	v_mfma_f32_16x16x32_bf16 v[60:63], v[222:225], v[156:159], v[60:63]
	v_mfma_f32_16x16x32_bf16 v[56:59], v[222:225], v[164:167], v[56:59]
	v_mfma_f32_16x16x32_bf16 v[52:55], v[230:233], v[156:159], v[52:55]
	v_mfma_f32_16x16x32_bf16 v[48:51], v[230:233], v[164:167], v[48:51]
	v_mfma_f32_16x16x32_bf16 v[44:47], v[242:245], v[156:159], v[44:47]
	v_mfma_f32_16x16x32_bf16 v[40:43], v[242:245], v[164:167], v[40:43]
	v_mfma_f32_16x16x32_bf16 v[36:39], v[250:253], v[156:159], v[36:39]
	v_mfma_f32_16x16x32_bf16 v[32:35], v[250:253], v[164:167], v[32:35]
	s_barrier
; #define STAGE_A(POFF, h, kt) STAGE_AX(POFF, h, kt, brow)
; #define LDA(dst, b, h) _Pragma("unroll") for (int m = 0; m < 4; ++m) _Pragma("unroll") for (int k = 0; k < 2; ++k) \
;     dst[m][k] = *reinterpret_cast<const bf16x8*>((char*)SA(b, h) + lds_byte(wr * 64 + m * 16 + fr, k * 32 + fq * 8))
; #define LDB(dst, b, h) _Pragma("unroll") for (int n = 0; n < 2; ++n) _Pragma("unroll") for (int k = 0; k < 2; ++k) \
;     dst[n][k] = *reinterpret_cast<const bf16x8*>((char*)SB(b, h) + lds_byte(wc * 32 + n * 16 + fr, k * 32 + fq * 8))
; #define MMA(ai, bj, At_, Bt_) do { __builtin_amdgcn_s_setprio(1); \
;     _Pragma("unroll") for (int k = 0; k < 2; ++k) _Pragma("unroll") for (int m = 0; m < 4; ++m) _Pragma("unroll") for (int n = 0; n < 2; ++n) \
;       acc[ai][bj][m][n] = __builtin_amdgcn_mfma_f32_16x16x32_bf16(At_[m][k], Bt_[n][k], acc[ai][bj][m][n], 0, 0, 0); \
;     __builtin_amdgcn_s_setprio(0); } while (0)
; #define WAIT_V(n) asm volatile("s_waitcnt vmcnt(" #n ")" ::: "memory")
; #define BAR __builtin_amdgcn_s_barrier()
; template <int EPI, int N, int K>
; __device__ __forceinline__ void gemm_phase(const bf16_t* __restrict__ A, const bf16_t* __restrict__ Bt, const EpiArgs ea) {
;     ...
;       WAIT_V(6); BAR; MMA(1, 1, At, B1); BAR;
;     }
;     { LDB(B0, 0, 0); LDA(At, 0, 0); STAGE_A(SA_OFF(1, 1), 1, nt - 1);
;       BAR; WAIT_L(0); MMA(0, 0, At, B0); BAR;
;       LDB(B1, 0, 1); BAR; WAIT_L(0); MMA(0, 1, At, B1); BAR;
;       LDA(At, 0, 1); WAIT_V(4); BAR; WAIT_L(0); MMA(1, 0, At, B0); MMA(1, 1, At, B1); BAR; }
;     { LDB(B0, 1, 0); LDA(At, 1, 0); WAIT_V(2); BAR; WAIT_L(0); MMA(0, 0, At, B0); BAR;
	s_setprio 0
	ds_read_b128 v[132:135], v147
	ds_read_b128 v[156:159], v147 offset:1024
	ds_read_b128 v[160:163], v147 offset:2048
	ds_read_b128 v[164:167], v147 offset:3072
	ds_read_b128 v[192:195], v151
	ds_read_b128 v[196:199], v151 offset:1024
	s_add_i32 s34, s35, 0x8180
	s_mov_b32 m0, s24
	s_nop 0
	buffer_load_dwordx4 v144, s[80:83], s34 offen lds
	s_add_i32 s35, s35, 0x208180
	s_mov_b32 m0, s25
	s_nop 0
	buffer_load_dwordx4 v144, s[80:83], s35 offen lds
	s_waitcnt vmcnt(6)
	s_setprio 1
	s_barrier
	v_mfma_f32_16x16x32_bf16 v[28:31], v[218:221], v[200:203], v[28:31]
	v_mfma_f32_16x16x32_bf16 v[24:27], v[218:221], v[208:211], v[24:27]
	v_mfma_f32_16x16x32_bf16 v[20:23], v[226:229], v[200:203], v[20:23]
	v_mfma_f32_16x16x32_bf16 v[16:19], v[226:229], v[208:211], v[16:19]
	v_mfma_f32_16x16x32_bf16 v[12:15], v[238:241], v[200:203], v[12:15]
	v_mfma_f32_16x16x32_bf16 v[8:11], v[238:241], v[208:211], v[8:11]
	v_mfma_f32_16x16x32_bf16 v[4:7], v[246:249], v[200:203], v[4:7]
	v_mfma_f32_16x16x32_bf16 v[0:3], v[246:249], v[208:211], v[0:3]
	v_mfma_f32_16x16x32_bf16 v[28:31], v[222:225], v[204:207], v[28:31]
	v_mfma_f32_16x16x32_bf16 v[24:27], v[222:225], v[212:215], v[24:27]
	v_mfma_f32_16x16x32_bf16 v[20:23], v[230:233], v[204:207], v[20:23]
	v_mfma_f32_16x16x32_bf16 v[16:19], v[230:233], v[212:215], v[16:19]
	v_mfma_f32_16x16x32_bf16 v[12:15], v[242:245], v[204:207], v[12:15]
	v_mfma_f32_16x16x32_bf16 v[8:11], v[242:245], v[212:215], v[8:11]
	v_mfma_f32_16x16x32_bf16 v[4:7], v[250:253], v[204:207], v[4:7]
	v_mfma_f32_16x16x32_bf16 v[0:3], v[250:253], v[212:215], v[0:3]
	s_barrier
	s_setprio 0
	s_add_i32 s30, s30, 2
	s_addk_i32 s31, 0x100
	s_cmpk_lt_u32 s30, 0x7c
	s_cbranch_scc1 .LBB0_568
	s_and_b32 s3, s3, 0x700
	s_lshl_b32 s2, s2, 11
	s_or_b32 s29, s3, s2
	s_lshl_b32 s2, s29, 14
	s_or_b32 s3, s2, 0x203f80
	s_mov_b32 m0, s26
	s_nop 0
	buffer_load_dwordx4 v131, s[64:67], s3 offen lds
	s_or_b32 s2, s2, 0x303f80
	s_mov_b32 m0, s27
	s_nop 0
	buffer_load_dwordx4 v131, s[64:67], s2 offen lds
	s_barrier
	s_waitcnt lgkmcnt(0)
	s_setprio 1
	v_mfma_f32_16x16x32_bf16 v[124:127], v[168:171], v[132:135], v[124:127]
	v_mfma_f32_16x16x32_bf16 v[120:123], v[168:171], v[160:163], v[120:123]
	v_mfma_f32_16x16x32_bf16 v[116:119], v[176:179], v[132:135], v[116:119]
	v_mfma_f32_16x16x32_bf16 v[112:115], v[176:179], v[160:163], v[112:115]
	v_mfma_f32_16x16x32_bf16 v[108:111], v[184:187], v[132:135], v[108:111]
	v_mfma_f32_16x16x32_bf16 v[104:107], v[184:187], v[160:163], v[104:107]
	v_mfma_f32_16x16x32_bf16 v[100:103], v[192:195], v[132:135], v[100:103]
	v_mfma_f32_16x16x32_bf16 v[96:99], v[192:195], v[160:163], v[96:99]
	v_mfma_f32_16x16x32_bf16 v[124:127], v[172:175], v[156:159], v[124:127]
	v_mfma_f32_16x16x32_bf16 v[120:123], v[172:175], v[164:167], v[120:123]
	v_mfma_f32_16x16x32_bf16 v[116:119], v[180:183], v[156:159], v[116:119]
	v_mfma_f32_16x16x32_bf16 v[112:115], v[180:183], v[164:167], v[112:115]
	v_mfma_f32_16x16x32_bf16 v[108:111], v[188:191], v[156:159], v[108:111]
	v_mfma_f32_16x16x32_bf16 v[104:107], v[188:191], v[164:167], v[104:107]
	v_mfma_f32_16x16x32_bf16 v[100:103], v[196:199], v[156:159], v[100:103]
	v_mfma_f32_16x16x32_bf16 v[96:99], v[196:199], v[164:167], v[96:99]
	s_setprio 0
	s_barrier
	ds_read_b128 v[200:203], v152
	ds_read_b128 v[204:207], v152 offset:1024
	ds_read_b128 v[208:211], v152 offset:2048
	ds_read_b128 v[212:215], v152 offset:3072
	s_barrier
	s_waitcnt lgkmcnt(0)
	s_setprio 1
	v_mfma_f32_16x16x32_bf16 v[92:95], v[168:171], v[200:203], v[92:95]
	v_mfma_f32_16x16x32_bf16 v[88:91], v[168:171], v[208:211], v[88:91]
	v_mfma_f32_16x16x32_bf16 v[76:79], v[184:187], v[200:203], v[76:79]
	v_mfma_f32_16x16x32_bf16 v[72:75], v[184:187], v[208:211], v[72:75]
	v_mfma_f32_16x16x32_bf16 v[84:87], v[176:179], v[200:203], v[84:87]
	v_mfma_f32_16x16x32_bf16 v[80:83], v[176:179], v[208:211], v[80:83]
	v_mfma_f32_16x16x32_bf16 v[68:71], v[192:195], v[200:203], v[68:71]
	v_mfma_f32_16x16x32_bf16 v[64:67], v[192:195], v[208:211], v[64:67]
	v_mfma_f32_16x16x32_bf16 v[92:95], v[172:175], v[204:207], v[92:95]
	v_mfma_f32_16x16x32_bf16 v[88:91], v[172:175], v[212:215], v[88:91]
	v_mfma_f32_16x16x32_bf16 v[76:79], v[188:191], v[204:207], v[76:79]
	v_mfma_f32_16x16x32_bf16 v[72:75], v[188:191], v[212:215], v[72:75]
	v_mfma_f32_16x16x32_bf16 v[168:171], v[180:183], v[204:207], v[84:87]
	v_mfma_f32_16x16x32_bf16 v[172:175], v[180:183], v[212:215], v[80:83]
	v_mfma_f32_16x16x32_bf16 v[176:179], v[196:199], v[204:207], v[68:71]
	v_mfma_f32_16x16x32_bf16 v[180:183], v[196:199], v[212:215], v[64:67]
	s_setprio 0
	s_barrier
	s_nop 0
	ds_read_b128 v[64:67], v148 offset:16384
	ds_read_b128 v[68:71], v148 offset:17408
	ds_read_b128 v[80:83], v149 offset:16384
	ds_read_b128 v[84:87], v149 offset:17408
	ds_read_b128 v[184:187], v150 offset:16384
	ds_read_b128 v[188:191], v150 offset:17408
	ds_read_b128 v[192:195], v151 offset:16384
	ds_read_b128 v[196:199], v151 offset:17408
	s_waitcnt vmcnt(4)
	s_barrier
; #define LDA(dst, b, h) _Pragma("unroll") for (int m = 0; m < 4; ++m) _Pragma("unroll") for (int k = 0; k < 2; ++k) \
;     dst[m][k] = *reinterpret_cast<const bf16x8*>((char*)SA(b, h) + lds_byte(wr * 64 + m * 16 + fr, k * 32 + fq * 8))
; #define LDB(dst, b, h) _Pragma("unroll") for (int n = 0; n < 2; ++n) _Pragma("unroll") for (int k = 0; k < 2; ++k) \
;     dst[n][k] = *reinterpret_cast<const bf16x8*>((char*)SB(b, h) + lds_byte(wc * 32 + n * 16 + fr, k * 32 + fq * 8))
; #define MMA(ai, bj, At_, Bt_) do { __builtin_amdgcn_s_setprio(1); \
;     _Pragma("unroll") for (int k = 0; k < 2; ++k) _Pragma("unroll") for (int m = 0; m < 4; ++m) _Pragma("unroll") for (int n = 0; n < 2; ++n) \
;       acc[ai][bj][m][n] = __builtin_amdgcn_mfma_f32_16x16x32_bf16(At_[m][k], Bt_[n][k], acc[ai][bj][m][n], 0, 0, 0); \
;     __builtin_amdgcn_s_setprio(0); } while (0)
; #define WAIT_V(n) asm volatile("s_waitcnt vmcnt(" #n ")" ::: "memory")
; #define BAR __builtin_amdgcn_s_barrier()
; template <int EPI, int N, int K>
; __device__ __forceinline__ void gemm_phase(const bf16_t* __restrict__ A, const bf16_t* __restrict__ Bt, const EpiArgs ea) {
;     ...
;       LDA(At, 0, 1); WAIT_V(4); BAR; WAIT_L(0); MMA(1, 0, At, B0); MMA(1, 1, At, B1); BAR; }
;     { LDB(B0, 1, 0); LDA(At, 1, 0); WAIT_V(2); BAR; WAIT_L(0); MMA(0, 0, At, B0); BAR;
;       LDB(B1, 1, 1); WAIT_V(0); BAR; WAIT_L(0); MMA(0, 1, At, B1); BAR;
	s_waitcnt lgkmcnt(0)
	s_setprio 1
	v_mfma_f32_16x16x32_bf16 v[60:63], v[64:67], v[132:135], v[60:63]
	v_mfma_f32_16x16x32_bf16 v[56:59], v[64:67], v[160:163], v[56:59]
	v_mfma_f32_16x16x32_bf16 v[52:55], v[80:83], v[132:135], v[52:55]
	v_mfma_f32_16x16x32_bf16 v[48:51], v[80:83], v[160:163], v[48:51]
	v_mfma_f32_16x16x32_bf16 v[44:47], v[184:187], v[132:135], v[44:47]
	v_mfma_f32_16x16x32_bf16 v[40:43], v[184:187], v[160:163], v[40:43]
	v_mfma_f32_16x16x32_bf16 v[36:39], v[192:195], v[132:135], v[36:39]
	v_mfma_f32_16x16x32_bf16 v[32:35], v[192:195], v[160:163], v[32:35]
	v_mfma_f32_16x16x32_bf16 v[60:63], v[68:71], v[156:159], v[60:63]
	v_mfma_f32_16x16x32_bf16 v[56:59], v[68:71], v[164:167], v[56:59]
	v_mfma_f32_16x16x32_bf16 v[52:55], v[84:87], v[156:159], v[52:55]
	v_mfma_f32_16x16x32_bf16 v[48:51], v[84:87], v[164:167], v[48:51]
	v_mfma_f32_16x16x32_bf16 v[44:47], v[188:191], v[156:159], v[44:47]
	v_mfma_f32_16x16x32_bf16 v[40:43], v[188:191], v[164:167], v[40:43]
	v_mfma_f32_16x16x32_bf16 v[36:39], v[196:199], v[156:159], v[36:39]
	v_mfma_f32_16x16x32_bf16 v[32:35], v[196:199], v[164:167], v[32:35]
	s_setprio 0
	s_setprio 1
	v_mfma_f32_16x16x32_bf16 v[28:31], v[64:67], v[200:203], v[28:31]
	v_mfma_f32_16x16x32_bf16 v[24:27], v[64:67], v[208:211], v[24:27]
	v_mfma_f32_16x16x32_bf16 v[4:7], v[192:195], v[200:203], v[4:7]
	v_mfma_f32_16x16x32_bf16 v[0:3], v[192:195], v[208:211], v[0:3]
	v_mfma_f32_16x16x32_bf16 v[20:23], v[80:83], v[200:203], v[20:23]
	v_mfma_f32_16x16x32_bf16 v[16:19], v[80:83], v[208:211], v[16:19]
	v_mfma_f32_16x16x32_bf16 v[12:15], v[184:187], v[200:203], v[12:15]
	v_mfma_f32_16x16x32_bf16 v[8:11], v[184:187], v[208:211], v[8:11]
	v_mfma_f32_16x16x32_bf16 v[28:31], v[68:71], v[204:207], v[28:31]
	v_mfma_f32_16x16x32_bf16 v[24:27], v[68:71], v[212:215], v[24:27]
	v_mfma_f32_16x16x32_bf16 v[4:7], v[196:199], v[204:207], v[4:7]
	v_mfma_f32_16x16x32_bf16 v[0:3], v[196:199], v[212:215], v[0:3]
	v_mfma_f32_16x16x32_bf16 v[132:135], v[84:87], v[204:207], v[20:23]
	v_mfma_f32_16x16x32_bf16 v[156:159], v[84:87], v[212:215], v[16:19]
	v_mfma_f32_16x16x32_bf16 v[160:163], v[188:191], v[204:207], v[12:15]
	v_mfma_f32_16x16x32_bf16 v[164:167], v[188:191], v[212:215], v[8:11]
	s_setprio 0
	s_barrier
	s_nop 0
	ds_read_b128 v[8:11], v153
	ds_read_b128 v[12:15], v153 offset:1024
	ds_read_b128 v[16:19], v153 offset:2048
	ds_read_b128 v[184:187], v153 offset:3072
	ds_read_b128 v[20:23], v148 offset:32768
	ds_read_b128 v[188:191], v148 offset:33792
	ds_read_b128 v[192:195], v149 offset:32768
	ds_read_b128 v[196:199], v149 offset:33792
	ds_read_b128 v[200:203], v150 offset:32768
	ds_read_b128 v[204:207], v150 offset:33792
	ds_read_b128 v[208:211], v151 offset:32768
	ds_read_b128 v[212:215], v151 offset:33792
	s_waitcnt vmcnt(2)
	s_barrier
	s_waitcnt lgkmcnt(0)
	s_setprio 1
	v_mfma_f32_16x16x32_bf16 v[64:67], v[20:23], v[8:11], v[124:127]
	v_mfma_f32_16x16x32_bf16 v[68:71], v[20:23], v[16:19], v[120:123]
	v_mfma_f32_16x16x32_bf16 v[80:83], v[192:195], v[8:11], v[116:119]
	v_mfma_f32_16x16x32_bf16 v[84:87], v[192:195], v[16:19], v[112:115]
	v_mfma_f32_16x16x32_bf16 v[108:111], v[200:203], v[8:11], v[108:111]
	v_mfma_f32_16x16x32_bf16 v[104:107], v[200:203], v[16:19], v[104:107]
	v_mfma_f32_16x16x32_bf16 v[120:123], v[208:211], v[8:11], v[100:103]
	v_mfma_f32_16x16x32_bf16 v[124:127], v[208:211], v[16:19], v[96:99]
	v_mfma_f32_16x16x32_bf16 v[116:119], v[188:191], v[12:15], v[64:67]
	v_mfma_f32_16x16x32_bf16 v[112:115], v[188:191], v[184:187], v[68:71]
	v_mfma_f32_16x16x32_bf16 v[100:103], v[196:199], v[12:15], v[80:83]
	v_mfma_f32_16x16x32_bf16 v[96:99], v[196:199], v[184:187], v[84:87]
	v_mfma_f32_16x16x32_bf16 v[84:87], v[204:207], v[12:15], v[108:111]
	v_mfma_f32_16x16x32_bf16 v[80:83], v[204:207], v[184:187], v[104:107]
	v_mfma_f32_16x16x32_bf16 v[68:71], v[212:215], v[12:15], v[120:123]
	v_mfma_f32_16x16x32_bf16 v[64:67], v[212:215], v[184:187], v[124:127]
	s_setprio 0
	s_barrier
; #define LDA(dst, b, h) _Pragma("unroll") for (int m = 0; m < 4; ++m) _Pragma("unroll") for (int k = 0; k < 2; ++k) \
;     dst[m][k] = *reinterpret_cast<const bf16x8*>((char*)SA(b, h) + lds_byte(wr * 64 + m * 16 + fr, k * 32 + fq * 8))
; #define LDB(dst, b, h) _Pragma("unroll") for (int n = 0; n < 2; ++n) _Pragma("unroll") for (int k = 0; k < 2; ++k) \
;     dst[n][k] = *reinterpret_cast<const bf16x8*>((char*)SB(b, h) + lds_byte(wc * 32 + n * 16 + fr, k * 32 + fq * 8))
; #define MMA(ai, bj, At_, Bt_) do { __builtin_amdgcn_s_setprio(1); \
;     _Pragma("unroll") for (int k = 0; k < 2; ++k) _Pragma("unroll") for (int m = 0; m < 4; ++m) _Pragma("unroll") for (int n = 0; n < 2; ++n) \
;       acc[ai][bj][m][n] = __builtin_amdgcn_mfma_f32_16x16x32_bf16(At_[m][k], Bt_[n][k], acc[ai][bj][m][n], 0, 0, 0); \
;     __builtin_amdgcn_s_setprio(0); } while (0)
; #define WAIT_V(n) asm volatile("s_waitcnt vmcnt(" #n ")" ::: "memory")
; #define BAR __builtin_amdgcn_s_barrier()
; template <int EPI, int N, int K>
; __device__ __forceinline__ void gemm_phase(const bf16_t* __restrict__ A, const bf16_t* __restrict__ Bt, const EpiArgs ea) {
;     ...
;     { LDB(B0, 1, 0); LDA(At, 1, 0); WAIT_V(2); BAR; WAIT_L(0); MMA(0, 0, At, B0); BAR;
;       LDB(B1, 1, 1); WAIT_V(0); BAR; WAIT_L(0); MMA(0, 1, At, B1); BAR;
;       LDA(At, 1, 1); BAR; WAIT_L(0); MMA(1, 0, At, B0); MMA(1, 1, At, B1); BAR; }
;     if (wr == 0) BAR;
	ds_read_b128 v[216:219], v154
	ds_read_b128 v[220:223], v154 offset:1024
	ds_read_b128 v[224:227], v154 offset:2048
	ds_read_b128 v[228:231], v154 offset:3072
	s_waitcnt vmcnt(0)
	s_barrier
	s_waitcnt lgkmcnt(0)
	s_setprio 1
	v_mfma_f32_16x16x32_bf16 v[92:95], v[20:23], v[216:219], v[92:95]
	v_mfma_f32_16x16x32_bf16 v[20:23], v[20:23], v[224:227], v[88:91]
	v_mfma_f32_16x16x32_bf16 v[88:91], v[192:195], v[216:219], v[168:171]
	v_mfma_f32_16x16x32_bf16 v[104:107], v[192:195], v[224:227], v[172:175]
	v_mfma_f32_16x16x32_bf16 v[76:79], v[200:203], v[216:219], v[76:79]
	v_mfma_f32_16x16x32_bf16 v[72:75], v[200:203], v[224:227], v[72:75]
	v_mfma_f32_16x16x32_bf16 v[168:171], v[208:211], v[216:219], v[176:179]
	v_mfma_f32_16x16x32_bf16 v[172:175], v[208:211], v[224:227], v[180:183]
	v_mfma_f32_16x16x32_bf16 v[124:127], v[188:191], v[220:223], v[92:95]
	v_mfma_f32_16x16x32_bf16 v[120:123], v[188:191], v[228:231], v[20:23]
	v_mfma_f32_16x16x32_bf16 v[108:111], v[196:199], v[220:223], v[88:91]
	v_mfma_f32_16x16x32_bf16 v[104:107], v[196:199], v[228:231], v[104:107]
	v_mfma_f32_16x16x32_bf16 v[92:95], v[204:207], v[220:223], v[76:79]
	v_mfma_f32_16x16x32_bf16 v[88:91], v[204:207], v[228:231], v[72:75]
	v_mfma_f32_16x16x32_bf16 v[76:79], v[212:215], v[220:223], v[168:171]
	v_mfma_f32_16x16x32_bf16 v[72:75], v[212:215], v[228:231], v[172:175]
	s_setprio 0
	s_barrier
	ds_read_b128 v[168:171], v148 offset:49152
	ds_read_b128 v[172:175], v148 offset:50176
	ds_read_b128 v[176:179], v149 offset:49152
	ds_read_b128 v[180:183], v149 offset:50176
	ds_read_b128 v[188:191], v150 offset:49152
	ds_read_b128 v[192:195], v150 offset:50176
	ds_read_b128 v[196:199], v151 offset:49152
	ds_read_b128 v[200:203], v151 offset:50176
	s_barrier
	s_waitcnt lgkmcnt(0)
	s_setprio 1
	v_mfma_f32_16x16x32_bf16 v[20:23], v[168:171], v[8:11], v[60:63]
	v_mfma_f32_16x16x32_bf16 v[56:59], v[168:171], v[16:19], v[56:59]
	v_mfma_f32_16x16x32_bf16 v[60:63], v[176:179], v[8:11], v[52:55]
	v_mfma_f32_16x16x32_bf16 v[204:207], v[176:179], v[16:19], v[48:51]
	v_mfma_f32_16x16x32_bf16 v[44:47], v[188:191], v[8:11], v[44:47]
	v_mfma_f32_16x16x32_bf16 v[40:43], v[188:191], v[16:19], v[40:43]
	v_mfma_f32_16x16x32_bf16 v[8:11], v[196:199], v[8:11], v[36:39]
	v_mfma_f32_16x16x32_bf16 v[208:211], v[196:199], v[16:19], v[32:35]
	v_mfma_f32_16x16x32_bf16 v[52:55], v[172:175], v[12:15], v[20:23]
	v_mfma_f32_16x16x32_bf16 v[48:51], v[172:175], v[184:187], v[56:59]
	v_mfma_f32_16x16x32_bf16 v[36:39], v[180:183], v[12:15], v[60:63]
	v_mfma_f32_16x16x32_bf16 v[32:35], v[180:183], v[184:187], v[204:207]
	v_mfma_f32_16x16x32_bf16 v[20:23], v[192:195], v[12:15], v[44:47]
	v_mfma_f32_16x16x32_bf16 v[16:19], v[192:195], v[184:187], v[40:43]
	v_mfma_f32_16x16x32_bf16 v[8:11], v[200:203], v[12:15], v[8:11]
	v_mfma_f32_16x16x32_bf16 v[12:15], v[200:203], v[184:187], v[208:211]
	s_setprio 0
	s_setprio 1
	v_mfma_f32_16x16x32_bf16 v[28:31], v[168:171], v[216:219], v[28:31]
	v_mfma_f32_16x16x32_bf16 v[24:27], v[168:171], v[224:227], v[24:27]
	v_mfma_f32_16x16x32_bf16 v[40:43], v[176:179], v[216:219], v[132:135]
	v_mfma_f32_16x16x32_bf16 v[132:135], v[176:179], v[224:227], v[156:159]
	v_mfma_f32_16x16x32_bf16 v[156:159], v[188:191], v[216:219], v[160:163]
	v_mfma_f32_16x16x32_bf16 v[160:163], v[188:191], v[224:227], v[164:167]
	v_mfma_f32_16x16x32_bf16 v[4:7], v[196:199], v[216:219], v[4:7]
	v_mfma_f32_16x16x32_bf16 v[0:3], v[196:199], v[224:227], v[0:3]
	v_mfma_f32_16x16x32_bf16 v[60:63], v[172:175], v[220:223], v[28:31]
	v_mfma_f32_16x16x32_bf16 v[56:59], v[172:175], v[228:231], v[24:27]
	v_mfma_f32_16x16x32_bf16 v[44:47], v[180:183], v[220:223], v[40:43]
	v_mfma_f32_16x16x32_bf16 v[40:43], v[180:183], v[228:231], v[132:135]
	v_mfma_f32_16x16x32_bf16 v[28:31], v[192:195], v[220:223], v[156:159]
	v_mfma_f32_16x16x32_bf16 v[24:27], v[192:195], v[228:231], v[160:163]
	v_mfma_f32_16x16x32_bf16 v[4:7], v[200:203], v[220:223], v[4:7]
	v_mfma_f32_16x16x32_bf16 v[0:3], v[200:203], v[228:231], v[0:3]
	s_setprio 0
	s_barrier
	s_and_saveexec_b64 s[2:3], s[6:7]
	s_cbranch_execz .LBB0_571
	s_barrier
